# GEMM main loops: removed the no-op s_setprio 0 / s_setprio 1 pair between the two MFMA blocks of each phase (36 pairs)
# speedup vs baseline: 1.0054x; 1.0054x over previous
; #define PG8_STAGE(bufoff, gbase, voff) do { _Pragma("unroll") for (int _i = 0; _i < 2; ++_i) \
;         __builtin_amdgcn_global_load_lds((const unsigned*)((const char*)(gbase) + (voff)[_i]), (LAS unsigned*)(lds + (bufoff) + ldsw + _i * 8192), 16, 0, 0); } while (0)
; #define PG8_LDA(dst, b, h) do { _Pragma("unroll") for (int m = 0; m < 4; ++m) _Pragma("unroll") for (int k = 0; k < 2; ++k) dst[m][k] = *(const LAS bf16x8*)(lds + PG8_SA(b, h) + aoff + m * 2048 + k * 1024); } while (0)
; #define PG8_LDB(dst, b, h) do { _Pragma("unroll") for (int n = 0; n < 2; ++n) _Pragma("unroll") for (int k = 0; k < 2; ++k) dst[n][k] = *(const LAS bf16x8*)(lds + PG8_SB(b, h) + boff + n * 2048 + k * 1024); } while (0)
; #define PG8_MMA(ai, bj, At, Bt) do { __builtin_amdgcn_s_setprio(1); _Pragma("unroll") for (int m = 0; m < 4; ++m) _Pragma("unroll") for (int n = 0; n < 2; ++n) _Pragma("unroll") for (int k = 0; k < 2; ++k) \
;         acc[ai][bj][m][n] = __builtin_amdgcn_mfma_f32_16x16x32_bf16(Bt[n][k], At[m][k], acc[ai][bj][m][n], 0, 0, 0); __builtin_amdgcn_s_setprio(0); } while (0)
; #define PG8_WAIT_V(n) asm volatile("s_waitcnt vmcnt(" #n ")" ::: "memory")
; #define PG8_WAIT_L(n) asm volatile("s_waitcnt lgkmcnt(" #n ")" ::: "memory")
; template <class Epi>
; __device__ __forceinline__ void gemm_phase(LAS unsigned char* lds, const Gemm g, const StaticOrder& S, const Epi& E) {
;     ...
;         for (int t = 0; t < nt; t += 2) {
;             if constexpr (Epi::GATED) { if (t == 8 || t == 16) E.rescale(acc, cur, t == 8 ? 0 : 1, wr, wc, fr, fq); }
;             const bool last = (t == nt - 2);
;             const char* a1 = PG8_AP(cA, t + 1);
;             const char* a2 = last ? nA : PG8_AP(cA, t + 2); const char* b2 = last ? nB : cB + (size_t)(t + 2) * kstep;
;             const char* a3 = last ? nA + kstep : PG8_AP(cA, t + 3); const char* b3 = b2 + kstep;
;             PG8_LDB(B0, 0, 0); PG8_LDB(B1, 0, 1); PG8_SCHED; PG8_LDA(At, 0, 0); PG8_STAGE(PG8_SA(1, 1), a1 + hstepA, voffA);
;             PG8_WAIT_V(8); PG8_WAIT_L(0); PG8_BAR; PG8_MMA(0, 0, At, B0); PG8_MMA(0, 1, At, B1); PG8_BAR; PG8_SCHED;
;             PG8_LDA(At, 0, 1); PG8_STAGE(PG8_SB(0, 0), b2, voffB); PG8_STAGE(PG8_SB(0, 1), b2 + hstep, voffB); PG8_STAGE(PG8_SA(0, 0), a2, voffA);
;             PG8_WAIT_V(8); PG8_WAIT_L(0); PG8_BAR; PG8_MMA(1, 0, At, B0); PG8_MMA(1, 1, At, B1); PG8_BAR; PG8_SCHED;
.LBB0_233:
	s_add_u32 s50, s46, s48
	s_addc_u32 s51, s47, s49
	s_add_u32 s56, s50, 0x100
	s_addc_u32 s57, s51, 0
	s_add_u32 s54, s93, s48
	s_addc_u32 s55, s94, s49
	s_add_u32 s50, s50, 0x180
	s_addc_u32 s51, s51, 0
	s_add_i32 s90, 0, 0x10000
	s_add_i32 s91, 0, 0x14000
	v_add_u32_e32 v147, s90, v1
	ds_read_b128 v[148:151], v147
	ds_read_b128 v[152:155], v147 offset:1024
	ds_read_b128 v[156:159], v147 offset:2048
	ds_read_b128 v[160:163], v147 offset:3072
	v_add_u32_e32 v147, s91, v1
	ds_read_b128 v[186:189], v147
	ds_read_b128 v[190:193], v147 offset:1024
	ds_read_b128 v[194:197], v147 offset:2048
	ds_read_b128 v[198:201], v147 offset:3072
	s_cmpk_eq_i32 s48, 0xf00
	s_cselect_b32 s51, s92, s51
	s_cselect_b32 s50, s87, s50
	s_cselect_b32 s55, s37, s55
	s_cselect_b32 s54, s86, s54
	s_cselect_b32 s57, s41, s57
	s_cselect_b32 s56, s85, s56
	v_lshl_add_u64 v[222:223], v[142:143], 0, s[48:49]
	s_add_i32 m0, s25, 0xc000
	ds_read_b128 v[202:205], v146
	ds_read_b128 v[206:209], v146 offset:1024
	ds_read_b128 v[226:229], v146 offset:2048
	ds_read_b128 v[230:233], v146 offset:3072
	ds_read_b128 v[234:237], v146 offset:4096
	ds_read_b128 v[238:241], v146 offset:5120
	ds_read_b128 v[242:245], v146 offset:6144
	ds_read_b128 v[246:249], v146 offset:7168
	global_load_lds_dwordx4 v[222:223], off
	v_lshl_add_u64 v[222:223], v[144:145], 0, s[48:49]
	s_add_i32 m0, s25, 0xe000
	s_nop 0
	global_load_lds_dwordx4 v[222:223], off
	s_waitcnt vmcnt(8)
	s_waitcnt lgkmcnt(0)
	s_barrier
	s_setprio 1
	s_waitcnt lgkmcnt(0)
	v_mfma_f32_16x16x32_bf16 v[126:129], v[148:151], v[202:205], v[126:129]
	v_mfma_f32_16x16x32_bf16 v[122:125], v[156:159], v[202:205], v[122:125]
	v_mfma_f32_16x16x32_bf16 v[118:121], v[148:151], v[226:229], v[118:121]
	v_mfma_f32_16x16x32_bf16 v[110:113], v[156:159], v[226:229], v[110:113]
	v_mfma_f32_16x16x32_bf16 v[102:105], v[148:151], v[234:237], v[102:105]
	v_mfma_f32_16x16x32_bf16 v[94:97], v[156:159], v[234:237], v[94:97]
	v_mfma_f32_16x16x32_bf16 v[86:89], v[148:151], v[242:245], v[86:89]
	v_mfma_f32_16x16x32_bf16 v[78:81], v[156:159], v[242:245], v[78:81]
	v_mfma_f32_16x16x32_bf16 v[126:129], v[152:155], v[206:209], v[126:129]
	v_mfma_f32_16x16x32_bf16 v[122:125], v[160:163], v[206:209], v[122:125]
	v_mfma_f32_16x16x32_bf16 v[118:121], v[152:155], v[230:233], v[118:121]
	v_mfma_f32_16x16x32_bf16 v[110:113], v[160:163], v[230:233], v[110:113]
	v_mfma_f32_16x16x32_bf16 v[102:105], v[152:155], v[238:241], v[102:105]
	v_mfma_f32_16x16x32_bf16 v[94:97], v[160:163], v[238:241], v[94:97]
	v_mfma_f32_16x16x32_bf16 v[86:89], v[152:155], v[246:249], v[86:89]
	v_mfma_f32_16x16x32_bf16 v[78:81], v[160:163], v[246:249], v[78:81]
	v_mfma_f32_16x16x32_bf16 v[114:117], v[186:189], v[202:205], v[114:117]
	v_mfma_f32_16x16x32_bf16 v[106:109], v[194:197], v[202:205], v[106:109]
	v_mfma_f32_16x16x32_bf16 v[98:101], v[186:189], v[226:229], v[98:101]
	v_mfma_f32_16x16x32_bf16 v[90:93], v[194:197], v[226:229], v[90:93]
	v_mfma_f32_16x16x32_bf16 v[82:85], v[186:189], v[234:237], v[82:85]
	v_mfma_f32_16x16x32_bf16 v[74:77], v[194:197], v[234:237], v[74:77]
	v_mfma_f32_16x16x32_bf16 v[70:73], v[186:189], v[242:245], v[70:73]
	v_mfma_f32_16x16x32_bf16 v[66:69], v[194:197], v[242:245], v[66:69]
	v_mfma_f32_16x16x32_bf16 v[114:117], v[190:193], v[206:209], v[114:117]
	v_mfma_f32_16x16x32_bf16 v[106:109], v[198:201], v[206:209], v[106:109]
	v_mfma_f32_16x16x32_bf16 v[98:101], v[190:193], v[230:233], v[98:101]
	v_mfma_f32_16x16x32_bf16 v[90:93], v[198:201], v[230:233], v[90:93]
	v_mfma_f32_16x16x32_bf16 v[82:85], v[190:193], v[238:241], v[82:85]
	v_mfma_f32_16x16x32_bf16 v[74:77], v[198:201], v[238:241], v[74:77]
	v_mfma_f32_16x16x32_bf16 v[70:73], v[190:193], v[246:249], v[70:73]
	v_mfma_f32_16x16x32_bf16 v[66:69], v[198:201], v[246:249], v[66:69]
	s_setprio 0
	s_barrier
	s_add_i32 s90, s90, s24
	v_lshl_add_u64 v[222:223], s[54:55], 0, v[134:135]
	s_mov_b32 m0, s90
	ds_read_b128 v[202:205], v146 offset:16384
	ds_read_b128 v[206:209], v146 offset:17408
	ds_read_b128 v[226:229], v146 offset:18432
	ds_read_b128 v[230:233], v146 offset:19456
	ds_read_b128 v[234:237], v146 offset:20480
	ds_read_b128 v[238:241], v146 offset:21504
	ds_read_b128 v[242:245], v146 offset:22528
	ds_read_b128 v[246:249], v146 offset:23552
	global_load_lds_dwordx4 v[222:223], off
	s_add_i32 m0, s90, 0x2000
	s_add_u32 vcc_lo, s54, 0x80000
	v_lshl_add_u64 v[224:225], s[54:55], 0, v[130:131]
	s_addc_u32 vcc_hi, s55, 0
	s_add_i32 s90, s91, s24
	global_load_lds_dwordx4 v[224:225], off
	v_lshl_add_u64 v[212:213], vcc, 0, v[134:135]
	s_mov_b32 m0, s90
	s_nop 0
	global_load_lds_dwordx4 v[212:213], off
	v_lshl_add_u64 v[212:213], vcc, 0, v[130:131]
	s_add_i32 m0, s90, 0x2000
	s_nop 0
	global_load_lds_dwordx4 v[212:213], off
	v_lshl_add_u64 v[212:213], s[56:57], 0, v[136:137]
	s_mov_b32 m0, s25
	s_nop 0
	global_load_lds_dwordx4 v[212:213], off
	v_lshl_add_u64 v[212:213], s[56:57], 0, v[132:133]
	s_mov_b32 m0, s26
	s_nop 0
	global_load_lds_dwordx4 v[212:213], off
	s_waitcnt vmcnt(8)
	s_waitcnt lgkmcnt(0)
	s_barrier
; #define PG8_STAGE(bufoff, gbase, voff) do { _Pragma("unroll") for (int _i = 0; _i < 2; ++_i) \
;         __builtin_amdgcn_global_load_lds((const unsigned*)((const char*)(gbase) + (voff)[_i]), (LAS unsigned*)(lds + (bufoff) + ldsw + _i * 8192), 16, 0, 0); } while (0)
; #define PG8_LDA(dst, b, h) do { _Pragma("unroll") for (int m = 0; m < 4; ++m) _Pragma("unroll") for (int k = 0; k < 2; ++k) dst[m][k] = *(const LAS bf16x8*)(lds + PG8_SA(b, h) + aoff + m * 2048 + k * 1024); } while (0)
; #define PG8_LDB(dst, b, h) do { _Pragma("unroll") for (int n = 0; n < 2; ++n) _Pragma("unroll") for (int k = 0; k < 2; ++k) dst[n][k] = *(const LAS bf16x8*)(lds + PG8_SB(b, h) + boff + n * 2048 + k * 1024); } while (0)
; #define PG8_MMA(ai, bj, At, Bt) do { __builtin_amdgcn_s_setprio(1); _Pragma("unroll") for (int m = 0; m < 4; ++m) _Pragma("unroll") for (int n = 0; n < 2; ++n) _Pragma("unroll") for (int k = 0; k < 2; ++k) \
;         acc[ai][bj][m][n] = __builtin_amdgcn_mfma_f32_16x16x32_bf16(Bt[n][k], At[m][k], acc[ai][bj][m][n], 0, 0, 0); __builtin_amdgcn_s_setprio(0); } while (0)
; #define PG8_WAIT_V(n) asm volatile("s_waitcnt vmcnt(" #n ")" ::: "memory")
; #define PG8_WAIT_L(n) asm volatile("s_waitcnt lgkmcnt(" #n ")" ::: "memory")
; #define PG8_BAR __builtin_amdgcn_s_barrier()
; #define PG8_SCHED __builtin_amdgcn_sched_barrier(0)
; template <class Epi>
; __device__ __forceinline__ void gemm_phase(LAS unsigned char* lds, const Gemm g, const StaticOrder& S, const Epi& E) {
;     ...
;             PG8_WAIT_V(8); PG8_WAIT_L(0); PG8_BAR; PG8_MMA(0, 0, At, B0); PG8_MMA(0, 1, At, B1); PG8_BAR; PG8_SCHED;
;             PG8_LDA(At, 0, 1); PG8_STAGE(PG8_SB(0, 0), b2, voffB); PG8_STAGE(PG8_SB(0, 1), b2 + hstep, voffB); PG8_STAGE(PG8_SA(0, 0), a2, voffA);
;             PG8_WAIT_V(8); PG8_WAIT_L(0); PG8_BAR; PG8_MMA(1, 0, At, B0); PG8_MMA(1, 1, At, B1); PG8_BAR; PG8_SCHED;
;             PG8_LDB(B0, 1, 0); PG8_LDB(B1, 1, 1); PG8_SCHED; PG8_LDA(At, 1, 0); PG8_STAGE(PG8_SA(0, 1), a2 + hstepA, voffA);
;             PG8_WAIT_V(8); PG8_WAIT_L(0); PG8_BAR; PG8_MMA(0, 0, At, B0); PG8_MMA(0, 1, At, B1); PG8_BAR; PG8_SCHED;
	s_setprio 1
	s_waitcnt lgkmcnt(0)
	v_mfma_f32_16x16x32_bf16 v[62:65], v[148:151], v[202:205], v[62:65]
	v_mfma_f32_16x16x32_bf16 v[58:61], v[156:159], v[202:205], v[58:61]
	v_mfma_f32_16x16x32_bf16 v[54:57], v[148:151], v[226:229], v[54:57]
	v_mfma_f32_16x16x32_bf16 v[46:49], v[156:159], v[226:229], v[46:49]
	v_mfma_f32_16x16x32_bf16 v[38:41], v[148:151], v[234:237], v[38:41]
	v_mfma_f32_16x16x32_bf16 v[30:33], v[156:159], v[234:237], v[30:33]
	v_mfma_f32_16x16x32_bf16 v[22:25], v[148:151], v[242:245], v[22:25]
	v_mfma_f32_16x16x32_bf16 v[14:17], v[156:159], v[242:245], v[14:17]
	v_mfma_f32_16x16x32_bf16 v[62:65], v[152:155], v[206:209], v[62:65]
	v_mfma_f32_16x16x32_bf16 v[58:61], v[160:163], v[206:209], v[58:61]
	v_mfma_f32_16x16x32_bf16 v[54:57], v[152:155], v[230:233], v[54:57]
	v_mfma_f32_16x16x32_bf16 v[46:49], v[160:163], v[230:233], v[46:49]
	v_mfma_f32_16x16x32_bf16 v[38:41], v[152:155], v[238:241], v[38:41]
	v_mfma_f32_16x16x32_bf16 v[30:33], v[160:163], v[238:241], v[30:33]
	v_mfma_f32_16x16x32_bf16 v[22:25], v[152:155], v[246:249], v[22:25]
	v_mfma_f32_16x16x32_bf16 v[14:17], v[160:163], v[246:249], v[14:17]
	v_mfma_f32_16x16x32_bf16 v[50:53], v[186:189], v[202:205], v[50:53]
	v_mfma_f32_16x16x32_bf16 v[42:45], v[194:197], v[202:205], v[42:45]
	v_mfma_f32_16x16x32_bf16 v[34:37], v[186:189], v[226:229], v[34:37]
	v_mfma_f32_16x16x32_bf16 v[26:29], v[194:197], v[226:229], v[26:29]
	v_mfma_f32_16x16x32_bf16 v[18:21], v[186:189], v[234:237], v[18:21]
	v_mfma_f32_16x16x32_bf16 v[10:13], v[194:197], v[234:237], v[10:13]
	v_mfma_f32_16x16x32_bf16 v[6:9], v[186:189], v[242:245], v[6:9]
	v_mfma_f32_16x16x32_bf16 v[2:5], v[194:197], v[242:245], v[2:5]
	v_mfma_f32_16x16x32_bf16 v[50:53], v[190:193], v[206:209], v[50:53]
	v_mfma_f32_16x16x32_bf16 v[42:45], v[198:201], v[206:209], v[42:45]
	v_mfma_f32_16x16x32_bf16 v[34:37], v[190:193], v[230:233], v[34:37]
	v_mfma_f32_16x16x32_bf16 v[26:29], v[198:201], v[230:233], v[26:29]
	v_mfma_f32_16x16x32_bf16 v[18:21], v[190:193], v[238:241], v[18:21]
	v_mfma_f32_16x16x32_bf16 v[10:13], v[198:201], v[238:241], v[10:13]
	v_mfma_f32_16x16x32_bf16 v[6:9], v[190:193], v[246:249], v[6:9]
	v_mfma_f32_16x16x32_bf16 v[2:5], v[198:201], v[246:249], v[2:5]
	s_setprio 0
	s_barrier
	s_add_i32 s90, 0, 0x18000
	v_add_u32_e32 v147, s90, v1
	s_add_i32 s91, 0, 0x1c000
	ds_read_b128 v[148:151], v147
	ds_read_b128 v[152:155], v147 offset:1024
	ds_read_b128 v[156:159], v147 offset:2048
	ds_read_b128 v[160:163], v147 offset:3072
	v_add_u32_e32 v147, s91, v1
	ds_read_b128 v[186:189], v147
	ds_read_b128 v[190:193], v147 offset:1024
	ds_read_b128 v[194:197], v147 offset:2048
	ds_read_b128 v[198:201], v147 offset:3072
	s_add_u32 s56, s56, 0x80000
	s_addc_u32 s57, s57, 0
	s_mov_b32 m0, s27
	v_lshl_add_u64 v[212:213], s[56:57], 0, v[136:137]
	ds_read_b128 v[202:205], v146 offset:32768
	ds_read_b128 v[206:209], v146 offset:33792
	ds_read_b128 v[226:229], v146 offset:34816
	ds_read_b128 v[230:233], v146 offset:35840
	ds_read_b128 v[234:237], v146 offset:36864
	ds_read_b128 v[238:241], v146 offset:37888
	ds_read_b128 v[242:245], v146 offset:38912
	ds_read_b128 v[246:249], v146 offset:39936
	global_load_lds_dwordx4 v[212:213], off
	v_lshl_add_u64 v[212:213], s[56:57], 0, v[132:133]
	s_mov_b32 m0, s33
	s_nop 0
	global_load_lds_dwordx4 v[212:213], off
	s_waitcnt vmcnt(8)
	s_waitcnt lgkmcnt(0)
	s_barrier
	s_setprio 1
	s_waitcnt lgkmcnt(0)
	v_mfma_f32_16x16x32_bf16 v[126:129], v[148:151], v[202:205], v[126:129]
	v_mfma_f32_16x16x32_bf16 v[122:125], v[156:159], v[202:205], v[122:125]
	v_mfma_f32_16x16x32_bf16 v[118:121], v[148:151], v[226:229], v[118:121]
	v_mfma_f32_16x16x32_bf16 v[110:113], v[156:159], v[226:229], v[110:113]
	v_mfma_f32_16x16x32_bf16 v[102:105], v[148:151], v[234:237], v[102:105]
	v_mfma_f32_16x16x32_bf16 v[94:97], v[156:159], v[234:237], v[94:97]
	v_mfma_f32_16x16x32_bf16 v[86:89], v[148:151], v[242:245], v[86:89]
	v_mfma_f32_16x16x32_bf16 v[78:81], v[156:159], v[242:245], v[78:81]
	v_mfma_f32_16x16x32_bf16 v[126:129], v[152:155], v[206:209], v[126:129]
	v_mfma_f32_16x16x32_bf16 v[122:125], v[160:163], v[206:209], v[122:125]
	v_mfma_f32_16x16x32_bf16 v[118:121], v[152:155], v[230:233], v[118:121]
	v_mfma_f32_16x16x32_bf16 v[110:113], v[160:163], v[230:233], v[110:113]
	v_mfma_f32_16x16x32_bf16 v[102:105], v[152:155], v[238:241], v[102:105]
	v_mfma_f32_16x16x32_bf16 v[94:97], v[160:163], v[238:241], v[94:97]
	v_mfma_f32_16x16x32_bf16 v[86:89], v[152:155], v[246:249], v[86:89]
	v_mfma_f32_16x16x32_bf16 v[78:81], v[160:163], v[246:249], v[78:81]
	v_mfma_f32_16x16x32_bf16 v[114:117], v[186:189], v[202:205], v[114:117]
	v_mfma_f32_16x16x32_bf16 v[106:109], v[194:197], v[202:205], v[106:109]
	v_mfma_f32_16x16x32_bf16 v[98:101], v[186:189], v[226:229], v[98:101]
	v_mfma_f32_16x16x32_bf16 v[90:93], v[194:197], v[226:229], v[90:93]
	v_mfma_f32_16x16x32_bf16 v[82:85], v[186:189], v[234:237], v[82:85]
	v_mfma_f32_16x16x32_bf16 v[74:77], v[194:197], v[234:237], v[74:77]
	v_mfma_f32_16x16x32_bf16 v[70:73], v[186:189], v[242:245], v[70:73]
	v_mfma_f32_16x16x32_bf16 v[66:69], v[194:197], v[242:245], v[66:69]
	v_mfma_f32_16x16x32_bf16 v[114:117], v[190:193], v[206:209], v[114:117]
	v_mfma_f32_16x16x32_bf16 v[106:109], v[198:201], v[206:209], v[106:109]
	v_mfma_f32_16x16x32_bf16 v[98:101], v[190:193], v[230:233], v[98:101]
	v_mfma_f32_16x16x32_bf16 v[90:93], v[198:201], v[230:233], v[90:93]
	v_mfma_f32_16x16x32_bf16 v[82:85], v[190:193], v[238:241], v[82:85]
	v_mfma_f32_16x16x32_bf16 v[74:77], v[198:201], v[238:241], v[74:77]
	v_mfma_f32_16x16x32_bf16 v[70:73], v[190:193], v[246:249], v[70:73]
	v_mfma_f32_16x16x32_bf16 v[66:69], v[198:201], v[246:249], v[66:69]
	s_setprio 0
	s_barrier
; #define PG8_STAGE(bufoff, gbase, voff) do { _Pragma("unroll") for (int _i = 0; _i < 2; ++_i) \
;         __builtin_amdgcn_global_load_lds((const unsigned*)((const char*)(gbase) + (voff)[_i]), (LAS unsigned*)(lds + (bufoff) + ldsw + _i * 8192), 16, 0, 0); } while (0)
; #define PG8_LDA(dst, b, h) do { _Pragma("unroll") for (int m = 0; m < 4; ++m) _Pragma("unroll") for (int k = 0; k < 2; ++k) dst[m][k] = *(const LAS bf16x8*)(lds + PG8_SA(b, h) + aoff + m * 2048 + k * 1024); } while (0)
; #define PG8_MMA(ai, bj, At, Bt) do { __builtin_amdgcn_s_setprio(1); _Pragma("unroll") for (int m = 0; m < 4; ++m) _Pragma("unroll") for (int n = 0; n < 2; ++n) _Pragma("unroll") for (int k = 0; k < 2; ++k) \
;         acc[ai][bj][m][n] = __builtin_amdgcn_mfma_f32_16x16x32_bf16(Bt[n][k], At[m][k], acc[ai][bj][m][n], 0, 0, 0); __builtin_amdgcn_s_setprio(0); } while (0)
; #define PG8_WAIT_V(n) asm volatile("s_waitcnt vmcnt(" #n ")" ::: "memory")
; #define PG8_WAIT_L(n) asm volatile("s_waitcnt lgkmcnt(" #n ")" ::: "memory")
; #define PG8_BAR __builtin_amdgcn_s_barrier()
; #define PG8_SCHED __builtin_amdgcn_sched_barrier(0)
; template <class Epi>
; __device__ __forceinline__ void gemm_phase(LAS unsigned char* lds, const Gemm g, const StaticOrder& S, const Epi& E) {
;     ...
;             PG8_WAIT_V(8); PG8_WAIT_L(0); PG8_BAR; PG8_MMA(0, 0, At, B0); PG8_MMA(0, 1, At, B1); PG8_BAR; PG8_SCHED;
;             PG8_LDA(At, 1, 1); PG8_STAGE(PG8_SB(1, 0), b3, voffB); PG8_STAGE(PG8_SB(1, 1), b3 + hstep, voffB); PG8_STAGE(PG8_SA(1, 0), a3, voffA);
;             PG8_WAIT_V(8); PG8_WAIT_L(0); PG8_BAR; PG8_MMA(1, 0, At, B0); PG8_MMA(1, 1, At, B1); PG8_BAR; PG8_SCHED;
;         }
;         if (wr == 0) PG8_BAR;
	s_add_i32 s56, s90, s24
	v_lshl_add_u64 v[212:213], v[222:223], 0, s[6:7]
	s_mov_b32 m0, s56
	ds_read_b128 v[202:205], v146 offset:49152
	ds_read_b128 v[206:209], v146 offset:50176
	ds_read_b128 v[226:229], v146 offset:51200
	ds_read_b128 v[230:233], v146 offset:52224
	ds_read_b128 v[234:237], v146 offset:53248
	ds_read_b128 v[238:241], v146 offset:54272
	ds_read_b128 v[242:245], v146 offset:55296
	ds_read_b128 v[246:249], v146 offset:56320
	global_load_lds_dwordx4 v[212:213], off
	s_add_i32 m0, s56, 0x2000
	s_add_u32 s54, s54, 0x80080
	v_lshl_add_u64 v[212:213], v[224:225], 0, s[6:7]
	s_addc_u32 s55, s55, 0
	s_add_i32 s56, s91, s24
	global_load_lds_dwordx4 v[212:213], off
	v_lshl_add_u64 v[212:213], s[54:55], 0, v[134:135]
	s_mov_b32 m0, s56
	s_nop 0
	global_load_lds_dwordx4 v[212:213], off
	v_lshl_add_u64 v[212:213], s[54:55], 0, v[130:131]
	s_add_i32 m0, s56, 0x2000
	s_nop 0
	global_load_lds_dwordx4 v[212:213], off
	v_lshl_add_u64 v[212:213], s[50:51], 0, v[136:137]
	s_mov_b32 m0, s52
	s_nop 0
	global_load_lds_dwordx4 v[212:213], off
	v_lshl_add_u64 v[212:213], s[50:51], 0, v[132:133]
	s_mov_b32 m0, s63
	s_nop 0
	global_load_lds_dwordx4 v[212:213], off
	s_waitcnt vmcnt(8)
	s_waitcnt lgkmcnt(0)
	s_barrier
	s_setprio 1
	s_waitcnt lgkmcnt(0)
	v_mfma_f32_16x16x32_bf16 v[62:65], v[148:151], v[202:205], v[62:65]
	v_mfma_f32_16x16x32_bf16 v[58:61], v[156:159], v[202:205], v[58:61]
	v_mfma_f32_16x16x32_bf16 v[54:57], v[148:151], v[226:229], v[54:57]
	v_mfma_f32_16x16x32_bf16 v[46:49], v[156:159], v[226:229], v[46:49]
	v_mfma_f32_16x16x32_bf16 v[38:41], v[148:151], v[234:237], v[38:41]
	v_mfma_f32_16x16x32_bf16 v[30:33], v[156:159], v[234:237], v[30:33]
	v_mfma_f32_16x16x32_bf16 v[22:25], v[148:151], v[242:245], v[22:25]
	v_mfma_f32_16x16x32_bf16 v[14:17], v[156:159], v[242:245], v[14:17]
	v_mfma_f32_16x16x32_bf16 v[62:65], v[152:155], v[206:209], v[62:65]
	v_mfma_f32_16x16x32_bf16 v[58:61], v[160:163], v[206:209], v[58:61]
	v_mfma_f32_16x16x32_bf16 v[54:57], v[152:155], v[230:233], v[54:57]
	v_mfma_f32_16x16x32_bf16 v[46:49], v[160:163], v[230:233], v[46:49]
	v_mfma_f32_16x16x32_bf16 v[38:41], v[152:155], v[238:241], v[38:41]
	v_mfma_f32_16x16x32_bf16 v[30:33], v[160:163], v[238:241], v[30:33]
	v_mfma_f32_16x16x32_bf16 v[22:25], v[152:155], v[246:249], v[22:25]
	v_mfma_f32_16x16x32_bf16 v[14:17], v[160:163], v[246:249], v[14:17]
	v_mfma_f32_16x16x32_bf16 v[50:53], v[186:189], v[202:205], v[50:53]
	v_mfma_f32_16x16x32_bf16 v[42:45], v[194:197], v[202:205], v[42:45]
	v_mfma_f32_16x16x32_bf16 v[34:37], v[186:189], v[226:229], v[34:37]
	v_mfma_f32_16x16x32_bf16 v[26:29], v[194:197], v[226:229], v[26:29]
	v_mfma_f32_16x16x32_bf16 v[18:21], v[186:189], v[234:237], v[18:21]
	v_mfma_f32_16x16x32_bf16 v[10:13], v[194:197], v[234:237], v[10:13]
	v_mfma_f32_16x16x32_bf16 v[6:9], v[186:189], v[242:245], v[6:9]
	v_mfma_f32_16x16x32_bf16 v[2:5], v[194:197], v[242:245], v[2:5]
	v_mfma_f32_16x16x32_bf16 v[50:53], v[190:193], v[206:209], v[50:53]
	v_mfma_f32_16x16x32_bf16 v[42:45], v[198:201], v[206:209], v[42:45]
	v_mfma_f32_16x16x32_bf16 v[34:37], v[190:193], v[230:233], v[34:37]
	v_mfma_f32_16x16x32_bf16 v[26:29], v[198:201], v[230:233], v[26:29]
	v_mfma_f32_16x16x32_bf16 v[18:21], v[190:193], v[238:241], v[18:21]
	v_mfma_f32_16x16x32_bf16 v[10:13], v[198:201], v[238:241], v[10:13]
	v_mfma_f32_16x16x32_bf16 v[6:9], v[190:193], v[246:249], v[6:9]
	v_mfma_f32_16x16x32_bf16 v[2:5], v[198:201], v[246:249], v[2:5]
	s_setprio 0
	s_barrier
	s_add_i32 s96, s96, 2
	s_add_u32 s48, s48, 0x100
	s_addc_u32 s49, s49, 0
	s_cmp_gt_u32 s96, 29
	s_cbranch_scc0 .LBB0_233
	s_and_b64 vcc, exec, s[34:35]
	s_cbranch_vccz .LBB0_236
	s_barrier

; #define PG8_STAGE(bufoff, gbase, voff) do { _Pragma("unroll") for (int _i = 0; _i < 2; ++_i) \
;         __builtin_amdgcn_global_load_lds((const unsigned*)((const char*)(gbase) + (voff)[_i]), (LAS unsigned*)(lds + (bufoff) + ldsw + _i * 8192), 16, 0, 0); } while (0)
; #define PG8_LDA(dst, b, h) do { _Pragma("unroll") for (int m = 0; m < 4; ++m) _Pragma("unroll") for (int k = 0; k < 2; ++k) dst[m][k] = *(const LAS bf16x8*)(lds + PG8_SA(b, h) + aoff + m * 2048 + k * 1024); } while (0)
; #define PG8_LDB(dst, b, h) do { _Pragma("unroll") for (int n = 0; n < 2; ++n) _Pragma("unroll") for (int k = 0; k < 2; ++k) dst[n][k] = *(const LAS bf16x8*)(lds + PG8_SB(b, h) + boff + n * 2048 + k * 1024); } while (0)
; #define PG8_MMA(ai, bj, At, Bt) do { __builtin_amdgcn_s_setprio(1); _Pragma("unroll") for (int m = 0; m < 4; ++m) _Pragma("unroll") for (int n = 0; n < 2; ++n) _Pragma("unroll") for (int k = 0; k < 2; ++k) \
;         acc[ai][bj][m][n] = __builtin_amdgcn_mfma_f32_16x16x32_bf16(Bt[n][k], At[m][k], acc[ai][bj][m][n], 0, 0, 0); __builtin_amdgcn_s_setprio(0); } while (0)
; #define PG8_WAIT_V(n) asm volatile("s_waitcnt vmcnt(" #n ")" ::: "memory")
; #define PG8_WAIT_L(n) asm volatile("s_waitcnt lgkmcnt(" #n ")" ::: "memory")
; template <class Epi>
; __device__ __forceinline__ void gemm_phase(LAS unsigned char* lds, const Gemm g, const StaticOrder& S, const Epi& E) {
;     ...
;         for (int t = 0; t < nt; t += 2) {
;             if constexpr (Epi::GATED) { if (t == 8 || t == 16) E.rescale(acc, cur, t == 8 ? 0 : 1, wr, wc, fr, fq); }
;             const bool last = (t == nt - 2);
;             const char* a1 = PG8_AP(cA, t + 1);
;             const char* a2 = last ? nA : PG8_AP(cA, t + 2); const char* b2 = last ? nB : cB + (size_t)(t + 2) * kstep;
;             const char* a3 = last ? nA + kstep : PG8_AP(cA, t + 3); const char* b3 = b2 + kstep;
;             PG8_LDB(B0, 0, 0); PG8_LDB(B1, 0, 1); PG8_SCHED; PG8_LDA(At, 0, 0); PG8_STAGE(PG8_SA(1, 1), a1 + hstepA, voffA);
;             PG8_WAIT_V(8); PG8_WAIT_L(0); PG8_BAR; PG8_MMA(0, 0, At, B0); PG8_MMA(0, 1, At, B1); PG8_BAR; PG8_SCHED;
;             PG8_LDA(At, 0, 1); PG8_STAGE(PG8_SB(0, 0), b2, voffB); PG8_STAGE(PG8_SB(0, 1), b2 + hstep, voffB); PG8_STAGE(PG8_SA(0, 0), a2, voffA);
;             PG8_WAIT_V(8); PG8_WAIT_L(0); PG8_BAR; PG8_MMA(1, 0, At, B0); PG8_MMA(1, 1, At, B1); PG8_BAR; PG8_SCHED;
.LBB0_253:
	s_add_u32 s50, s46, s48
	s_addc_u32 s51, s47, s49
	s_add_u32 s56, s50, 0x100
	s_addc_u32 s57, s51, 0
	s_add_u32 s54, s93, s48
	s_addc_u32 s55, s94, s49
	s_add_u32 s50, s50, 0x180
	s_addc_u32 s51, s51, 0
	s_add_i32 s90, 0, 0x10000
	s_add_i32 s91, 0, 0x14000
	v_add_u32_e32 v147, s90, v1
	ds_read_b128 v[148:151], v147
	ds_read_b128 v[152:155], v147 offset:1024
	ds_read_b128 v[156:159], v147 offset:2048
	ds_read_b128 v[160:163], v147 offset:3072
	v_add_u32_e32 v147, s91, v1
	ds_read_b128 v[186:189], v147
	ds_read_b128 v[190:193], v147 offset:1024
	ds_read_b128 v[194:197], v147 offset:2048
	ds_read_b128 v[198:201], v147 offset:3072
	s_cmpk_eq_i32 s48, 0xf00
	s_cselect_b32 s51, s92, s51
	s_cselect_b32 s50, s87, s50
	s_cselect_b32 s55, s37, s55
	s_cselect_b32 s54, s86, s54
	s_cselect_b32 s57, s41, s57
	s_cselect_b32 s56, s85, s56
	v_lshl_add_u64 v[212:213], v[142:143], 0, s[48:49]
	s_add_i32 m0, s25, 0xc000
	ds_read_b128 v[202:205], v146
	ds_read_b128 v[206:209], v146 offset:1024
	ds_read_b128 v[226:229], v146 offset:2048
	ds_read_b128 v[230:233], v146 offset:3072
	ds_read_b128 v[234:237], v146 offset:4096
	ds_read_b128 v[238:241], v146 offset:5120
	ds_read_b128 v[242:245], v146 offset:6144
	ds_read_b128 v[246:249], v146 offset:7168
	global_load_lds_dwordx4 v[212:213], off
	v_lshl_add_u64 v[212:213], v[144:145], 0, s[48:49]
	s_add_i32 m0, s25, 0xe000
	s_nop 0
	global_load_lds_dwordx4 v[212:213], off
	s_waitcnt vmcnt(8)
	s_waitcnt lgkmcnt(0)
	s_barrier
	s_setprio 1
	s_waitcnt lgkmcnt(0)
	v_mfma_f32_16x16x32_bf16 v[126:129], v[148:151], v[202:205], v[126:129]
	v_mfma_f32_16x16x32_bf16 v[122:125], v[156:159], v[202:205], v[122:125]
	v_mfma_f32_16x16x32_bf16 v[118:121], v[148:151], v[226:229], v[118:121]
	v_mfma_f32_16x16x32_bf16 v[110:113], v[156:159], v[226:229], v[110:113]
	v_mfma_f32_16x16x32_bf16 v[102:105], v[148:151], v[234:237], v[102:105]
	v_mfma_f32_16x16x32_bf16 v[94:97], v[156:159], v[234:237], v[94:97]
	v_mfma_f32_16x16x32_bf16 v[86:89], v[148:151], v[242:245], v[86:89]
	v_mfma_f32_16x16x32_bf16 v[78:81], v[156:159], v[242:245], v[78:81]
	v_mfma_f32_16x16x32_bf16 v[126:129], v[152:155], v[206:209], v[126:129]
	v_mfma_f32_16x16x32_bf16 v[122:125], v[160:163], v[206:209], v[122:125]
	v_mfma_f32_16x16x32_bf16 v[118:121], v[152:155], v[230:233], v[118:121]
	v_mfma_f32_16x16x32_bf16 v[110:113], v[160:163], v[230:233], v[110:113]
	v_mfma_f32_16x16x32_bf16 v[102:105], v[152:155], v[238:241], v[102:105]
	v_mfma_f32_16x16x32_bf16 v[94:97], v[160:163], v[238:241], v[94:97]
	v_mfma_f32_16x16x32_bf16 v[86:89], v[152:155], v[246:249], v[86:89]
	v_mfma_f32_16x16x32_bf16 v[78:81], v[160:163], v[246:249], v[78:81]
	v_mfma_f32_16x16x32_bf16 v[114:117], v[186:189], v[202:205], v[114:117]
	v_mfma_f32_16x16x32_bf16 v[106:109], v[194:197], v[202:205], v[106:109]
	v_mfma_f32_16x16x32_bf16 v[98:101], v[186:189], v[226:229], v[98:101]
	v_mfma_f32_16x16x32_bf16 v[90:93], v[194:197], v[226:229], v[90:93]
	v_mfma_f32_16x16x32_bf16 v[82:85], v[186:189], v[234:237], v[82:85]
	v_mfma_f32_16x16x32_bf16 v[74:77], v[194:197], v[234:237], v[74:77]
	v_mfma_f32_16x16x32_bf16 v[70:73], v[186:189], v[242:245], v[70:73]
	v_mfma_f32_16x16x32_bf16 v[66:69], v[194:197], v[242:245], v[66:69]
	v_mfma_f32_16x16x32_bf16 v[114:117], v[190:193], v[206:209], v[114:117]
	v_mfma_f32_16x16x32_bf16 v[106:109], v[198:201], v[206:209], v[106:109]
	v_mfma_f32_16x16x32_bf16 v[98:101], v[190:193], v[230:233], v[98:101]
	v_mfma_f32_16x16x32_bf16 v[90:93], v[198:201], v[230:233], v[90:93]
	v_mfma_f32_16x16x32_bf16 v[82:85], v[190:193], v[238:241], v[82:85]
	v_mfma_f32_16x16x32_bf16 v[74:77], v[198:201], v[238:241], v[74:77]
	v_mfma_f32_16x16x32_bf16 v[70:73], v[190:193], v[246:249], v[70:73]
	v_mfma_f32_16x16x32_bf16 v[66:69], v[198:201], v[246:249], v[66:69]
	s_setprio 0
	s_barrier
	s_add_i32 s90, s90, s24
	v_lshl_add_u64 v[212:213], s[54:55], 0, v[134:135]
	s_mov_b32 m0, s90
	ds_read_b128 v[202:205], v146 offset:16384
	ds_read_b128 v[206:209], v146 offset:17408
	ds_read_b128 v[226:229], v146 offset:18432
	ds_read_b128 v[230:233], v146 offset:19456
	ds_read_b128 v[234:237], v146 offset:20480
	ds_read_b128 v[238:241], v146 offset:21504
	ds_read_b128 v[242:245], v146 offset:22528
	ds_read_b128 v[246:249], v146 offset:23552
	global_load_lds_dwordx4 v[212:213], off
	s_add_i32 m0, s90, 0x2000
	s_add_u32 vcc_lo, s54, 0x80000
	v_lshl_add_u64 v[222:223], s[54:55], 0, v[130:131]
	s_addc_u32 vcc_hi, s55, 0
	s_add_i32 s90, s91, s24
	global_load_lds_dwordx4 v[222:223], off
	v_lshl_add_u64 v[224:225], vcc, 0, v[134:135]
	s_mov_b32 m0, s90
	s_nop 0
	global_load_lds_dwordx4 v[224:225], off
	v_lshl_add_u64 v[224:225], vcc, 0, v[130:131]
	s_add_i32 m0, s90, 0x2000
	s_nop 0
	global_load_lds_dwordx4 v[224:225], off
	v_lshl_add_u64 v[224:225], s[56:57], 0, v[136:137]
	s_mov_b32 m0, s25
	s_nop 0
	global_load_lds_dwordx4 v[224:225], off
	v_lshl_add_u64 v[224:225], s[56:57], 0, v[132:133]
	s_mov_b32 m0, s26
	s_nop 0
	global_load_lds_dwordx4 v[224:225], off
	s_waitcnt vmcnt(8)
	s_waitcnt lgkmcnt(0)
	s_barrier
; #define PG8_STAGE(bufoff, gbase, voff) do { _Pragma("unroll") for (int _i = 0; _i < 2; ++_i) \
;         __builtin_amdgcn_global_load_lds((const unsigned*)((const char*)(gbase) + (voff)[_i]), (LAS unsigned*)(lds + (bufoff) + ldsw + _i * 8192), 16, 0, 0); } while (0)
; #define PG8_LDA(dst, b, h) do { _Pragma("unroll") for (int m = 0; m < 4; ++m) _Pragma("unroll") for (int k = 0; k < 2; ++k) dst[m][k] = *(const LAS bf16x8*)(lds + PG8_SA(b, h) + aoff + m * 2048 + k * 1024); } while (0)
; #define PG8_LDB(dst, b, h) do { _Pragma("unroll") for (int n = 0; n < 2; ++n) _Pragma("unroll") for (int k = 0; k < 2; ++k) dst[n][k] = *(const LAS bf16x8*)(lds + PG8_SB(b, h) + boff + n * 2048 + k * 1024); } while (0)
; #define PG8_MMA(ai, bj, At, Bt) do { __builtin_amdgcn_s_setprio(1); _Pragma("unroll") for (int m = 0; m < 4; ++m) _Pragma("unroll") for (int n = 0; n < 2; ++n) _Pragma("unroll") for (int k = 0; k < 2; ++k) \
;         acc[ai][bj][m][n] = __builtin_amdgcn_mfma_f32_16x16x32_bf16(Bt[n][k], At[m][k], acc[ai][bj][m][n], 0, 0, 0); __builtin_amdgcn_s_setprio(0); } while (0)
; #define PG8_WAIT_V(n) asm volatile("s_waitcnt vmcnt(" #n ")" ::: "memory")
; #define PG8_WAIT_L(n) asm volatile("s_waitcnt lgkmcnt(" #n ")" ::: "memory")
; #define PG8_BAR __builtin_amdgcn_s_barrier()
; #define PG8_SCHED __builtin_amdgcn_sched_barrier(0)
; template <class Epi>
; __device__ __forceinline__ void gemm_phase(LAS unsigned char* lds, const Gemm g, const StaticOrder& S, const Epi& E) {
;     ...
;             PG8_WAIT_V(8); PG8_WAIT_L(0); PG8_BAR; PG8_MMA(0, 0, At, B0); PG8_MMA(0, 1, At, B1); PG8_BAR; PG8_SCHED;
;             PG8_LDA(At, 0, 1); PG8_STAGE(PG8_SB(0, 0), b2, voffB); PG8_STAGE(PG8_SB(0, 1), b2 + hstep, voffB); PG8_STAGE(PG8_SA(0, 0), a2, voffA);
;             PG8_WAIT_V(8); PG8_WAIT_L(0); PG8_BAR; PG8_MMA(1, 0, At, B0); PG8_MMA(1, 1, At, B1); PG8_BAR; PG8_SCHED;
;             PG8_LDB(B0, 1, 0); PG8_LDB(B1, 1, 1); PG8_SCHED; PG8_LDA(At, 1, 0); PG8_STAGE(PG8_SA(0, 1), a2 + hstepA, voffA);
;             PG8_WAIT_V(8); PG8_WAIT_L(0); PG8_BAR; PG8_MMA(0, 0, At, B0); PG8_MMA(0, 1, At, B1); PG8_BAR; PG8_SCHED;
	s_setprio 1
	s_waitcnt lgkmcnt(0)
	v_mfma_f32_16x16x32_bf16 v[62:65], v[148:151], v[202:205], v[62:65]
	v_mfma_f32_16x16x32_bf16 v[58:61], v[156:159], v[202:205], v[58:61]
	v_mfma_f32_16x16x32_bf16 v[54:57], v[148:151], v[226:229], v[54:57]
	v_mfma_f32_16x16x32_bf16 v[46:49], v[156:159], v[226:229], v[46:49]
	v_mfma_f32_16x16x32_bf16 v[38:41], v[148:151], v[234:237], v[38:41]
	v_mfma_f32_16x16x32_bf16 v[30:33], v[156:159], v[234:237], v[30:33]
	v_mfma_f32_16x16x32_bf16 v[22:25], v[148:151], v[242:245], v[22:25]
	v_mfma_f32_16x16x32_bf16 v[14:17], v[156:159], v[242:245], v[14:17]
	v_mfma_f32_16x16x32_bf16 v[62:65], v[152:155], v[206:209], v[62:65]
	v_mfma_f32_16x16x32_bf16 v[58:61], v[160:163], v[206:209], v[58:61]
	v_mfma_f32_16x16x32_bf16 v[54:57], v[152:155], v[230:233], v[54:57]
	v_mfma_f32_16x16x32_bf16 v[46:49], v[160:163], v[230:233], v[46:49]
	v_mfma_f32_16x16x32_bf16 v[38:41], v[152:155], v[238:241], v[38:41]
	v_mfma_f32_16x16x32_bf16 v[30:33], v[160:163], v[238:241], v[30:33]
	v_mfma_f32_16x16x32_bf16 v[22:25], v[152:155], v[246:249], v[22:25]
	v_mfma_f32_16x16x32_bf16 v[14:17], v[160:163], v[246:249], v[14:17]
	v_mfma_f32_16x16x32_bf16 v[50:53], v[186:189], v[202:205], v[50:53]
	v_mfma_f32_16x16x32_bf16 v[42:45], v[194:197], v[202:205], v[42:45]
	v_mfma_f32_16x16x32_bf16 v[34:37], v[186:189], v[226:229], v[34:37]
	v_mfma_f32_16x16x32_bf16 v[26:29], v[194:197], v[226:229], v[26:29]
	v_mfma_f32_16x16x32_bf16 v[18:21], v[186:189], v[234:237], v[18:21]
	v_mfma_f32_16x16x32_bf16 v[10:13], v[194:197], v[234:237], v[10:13]
	v_mfma_f32_16x16x32_bf16 v[6:9], v[186:189], v[242:245], v[6:9]
	v_mfma_f32_16x16x32_bf16 v[2:5], v[194:197], v[242:245], v[2:5]
	v_mfma_f32_16x16x32_bf16 v[50:53], v[190:193], v[206:209], v[50:53]
	v_mfma_f32_16x16x32_bf16 v[42:45], v[198:201], v[206:209], v[42:45]
	v_mfma_f32_16x16x32_bf16 v[34:37], v[190:193], v[230:233], v[34:37]
	v_mfma_f32_16x16x32_bf16 v[26:29], v[198:201], v[230:233], v[26:29]
	v_mfma_f32_16x16x32_bf16 v[18:21], v[190:193], v[238:241], v[18:21]
	v_mfma_f32_16x16x32_bf16 v[10:13], v[198:201], v[238:241], v[10:13]
	v_mfma_f32_16x16x32_bf16 v[6:9], v[190:193], v[246:249], v[6:9]
	v_mfma_f32_16x16x32_bf16 v[2:5], v[198:201], v[246:249], v[2:5]
	s_setprio 0
	s_barrier
	s_add_i32 s90, 0, 0x18000
	v_add_u32_e32 v147, s90, v1
	s_add_i32 s91, 0, 0x1c000
	ds_read_b128 v[148:151], v147
	ds_read_b128 v[152:155], v147 offset:1024
	ds_read_b128 v[156:159], v147 offset:2048
	ds_read_b128 v[160:163], v147 offset:3072
	v_add_u32_e32 v147, s91, v1
	ds_read_b128 v[186:189], v147
	ds_read_b128 v[190:193], v147 offset:1024
	ds_read_b128 v[194:197], v147 offset:2048
	ds_read_b128 v[198:201], v147 offset:3072
	s_add_u32 s56, s56, 0x80000
	s_addc_u32 s57, s57, 0
	s_mov_b32 m0, s27
	v_lshl_add_u64 v[224:225], s[56:57], 0, v[136:137]
	ds_read_b128 v[202:205], v146 offset:32768
	ds_read_b128 v[206:209], v146 offset:33792
	ds_read_b128 v[226:229], v146 offset:34816
	ds_read_b128 v[230:233], v146 offset:35840
	ds_read_b128 v[234:237], v146 offset:36864
	ds_read_b128 v[238:241], v146 offset:37888
	ds_read_b128 v[242:245], v146 offset:38912
	ds_read_b128 v[246:249], v146 offset:39936
	global_load_lds_dwordx4 v[224:225], off
	v_lshl_add_u64 v[224:225], s[56:57], 0, v[132:133]
	s_mov_b32 m0, s33
	s_nop 0
	global_load_lds_dwordx4 v[224:225], off
	s_waitcnt vmcnt(8)
	s_waitcnt lgkmcnt(0)
	s_barrier
	s_setprio 1
	s_waitcnt lgkmcnt(0)
	v_mfma_f32_16x16x32_bf16 v[126:129], v[148:151], v[202:205], v[126:129]
	v_mfma_f32_16x16x32_bf16 v[122:125], v[156:159], v[202:205], v[122:125]
	v_mfma_f32_16x16x32_bf16 v[118:121], v[148:151], v[226:229], v[118:121]
	v_mfma_f32_16x16x32_bf16 v[110:113], v[156:159], v[226:229], v[110:113]
	v_mfma_f32_16x16x32_bf16 v[102:105], v[148:151], v[234:237], v[102:105]
	v_mfma_f32_16x16x32_bf16 v[94:97], v[156:159], v[234:237], v[94:97]
	v_mfma_f32_16x16x32_bf16 v[86:89], v[148:151], v[242:245], v[86:89]
	v_mfma_f32_16x16x32_bf16 v[78:81], v[156:159], v[242:245], v[78:81]
	v_mfma_f32_16x16x32_bf16 v[126:129], v[152:155], v[206:209], v[126:129]
	v_mfma_f32_16x16x32_bf16 v[122:125], v[160:163], v[206:209], v[122:125]
	v_mfma_f32_16x16x32_bf16 v[118:121], v[152:155], v[230:233], v[118:121]
	v_mfma_f32_16x16x32_bf16 v[110:113], v[160:163], v[230:233], v[110:113]
	v_mfma_f32_16x16x32_bf16 v[102:105], v[152:155], v[238:241], v[102:105]
	v_mfma_f32_16x16x32_bf16 v[94:97], v[160:163], v[238:241], v[94:97]
	v_mfma_f32_16x16x32_bf16 v[86:89], v[152:155], v[246:249], v[86:89]
	v_mfma_f32_16x16x32_bf16 v[78:81], v[160:163], v[246:249], v[78:81]
	v_mfma_f32_16x16x32_bf16 v[114:117], v[186:189], v[202:205], v[114:117]
	v_mfma_f32_16x16x32_bf16 v[106:109], v[194:197], v[202:205], v[106:109]
	v_mfma_f32_16x16x32_bf16 v[98:101], v[186:189], v[226:229], v[98:101]
	v_mfma_f32_16x16x32_bf16 v[90:93], v[194:197], v[226:229], v[90:93]
	v_mfma_f32_16x16x32_bf16 v[82:85], v[186:189], v[234:237], v[82:85]
	v_mfma_f32_16x16x32_bf16 v[74:77], v[194:197], v[234:237], v[74:77]
	v_mfma_f32_16x16x32_bf16 v[70:73], v[186:189], v[242:245], v[70:73]
	v_mfma_f32_16x16x32_bf16 v[66:69], v[194:197], v[242:245], v[66:69]
	v_mfma_f32_16x16x32_bf16 v[114:117], v[190:193], v[206:209], v[114:117]
	v_mfma_f32_16x16x32_bf16 v[106:109], v[198:201], v[206:209], v[106:109]
	v_mfma_f32_16x16x32_bf16 v[98:101], v[190:193], v[230:233], v[98:101]
	v_mfma_f32_16x16x32_bf16 v[90:93], v[198:201], v[230:233], v[90:93]
	v_mfma_f32_16x16x32_bf16 v[82:85], v[190:193], v[238:241], v[82:85]
	v_mfma_f32_16x16x32_bf16 v[74:77], v[198:201], v[238:241], v[74:77]
	v_mfma_f32_16x16x32_bf16 v[70:73], v[190:193], v[246:249], v[70:73]
	v_mfma_f32_16x16x32_bf16 v[66:69], v[198:201], v[246:249], v[66:69]
	s_setprio 0
	s_barrier
; #define PG8_STAGE(bufoff, gbase, voff) do { _Pragma("unroll") for (int _i = 0; _i < 2; ++_i) \
;         __builtin_amdgcn_global_load_lds((const unsigned*)((const char*)(gbase) + (voff)[_i]), (LAS unsigned*)(lds + (bufoff) + ldsw + _i * 8192), 16, 0, 0); } while (0)
; #define PG8_LDA(dst, b, h) do { _Pragma("unroll") for (int m = 0; m < 4; ++m) _Pragma("unroll") for (int k = 0; k < 2; ++k) dst[m][k] = *(const LAS bf16x8*)(lds + PG8_SA(b, h) + aoff + m * 2048 + k * 1024); } while (0)
; #define PG8_MMA(ai, bj, At, Bt) do { __builtin_amdgcn_s_setprio(1); _Pragma("unroll") for (int m = 0; m < 4; ++m) _Pragma("unroll") for (int n = 0; n < 2; ++n) _Pragma("unroll") for (int k = 0; k < 2; ++k) \
;         acc[ai][bj][m][n] = __builtin_amdgcn_mfma_f32_16x16x32_bf16(Bt[n][k], At[m][k], acc[ai][bj][m][n], 0, 0, 0); __builtin_amdgcn_s_setprio(0); } while (0)
; #define PG8_WAIT_V(n) asm volatile("s_waitcnt vmcnt(" #n ")" ::: "memory")
; #define PG8_WAIT_L(n) asm volatile("s_waitcnt lgkmcnt(" #n ")" ::: "memory")
; #define PG8_BAR __builtin_amdgcn_s_barrier()
; #define PG8_SCHED __builtin_amdgcn_sched_barrier(0)
; template <class Epi>
; __device__ __forceinline__ void gemm_phase(LAS unsigned char* lds, const Gemm g, const StaticOrder& S, const Epi& E) {
;     ...
;             PG8_WAIT_V(8); PG8_WAIT_L(0); PG8_BAR; PG8_MMA(0, 0, At, B0); PG8_MMA(0, 1, At, B1); PG8_BAR; PG8_SCHED;
;             PG8_LDA(At, 1, 1); PG8_STAGE(PG8_SB(1, 0), b3, voffB); PG8_STAGE(PG8_SB(1, 1), b3 + hstep, voffB); PG8_STAGE(PG8_SA(1, 0), a3, voffA);
;             PG8_WAIT_V(8); PG8_WAIT_L(0); PG8_BAR; PG8_MMA(1, 0, At, B0); PG8_MMA(1, 1, At, B1); PG8_BAR; PG8_SCHED;
;         }
;         if (wr == 0) PG8_BAR;
	s_add_i32 s56, s90, s24
	v_lshl_add_u64 v[212:213], v[212:213], 0, s[6:7]
	s_mov_b32 m0, s56
	ds_read_b128 v[202:205], v146 offset:49152
	ds_read_b128 v[206:209], v146 offset:50176
	ds_read_b128 v[226:229], v146 offset:51200
	ds_read_b128 v[230:233], v146 offset:52224
	ds_read_b128 v[234:237], v146 offset:53248
	ds_read_b128 v[238:241], v146 offset:54272
	ds_read_b128 v[242:245], v146 offset:55296
	ds_read_b128 v[246:249], v146 offset:56320
	global_load_lds_dwordx4 v[212:213], off
	s_add_i32 m0, s56, 0x2000
	s_add_u32 s54, s54, 0x80080
	v_lshl_add_u64 v[212:213], v[222:223], 0, s[6:7]
	s_addc_u32 s55, s55, 0
	s_add_i32 s56, s91, s24
	global_load_lds_dwordx4 v[212:213], off
	v_lshl_add_u64 v[212:213], s[54:55], 0, v[134:135]
	s_mov_b32 m0, s56
	s_nop 0
	global_load_lds_dwordx4 v[212:213], off
	v_lshl_add_u64 v[212:213], s[54:55], 0, v[130:131]
	s_add_i32 m0, s56, 0x2000
	s_nop 0
	global_load_lds_dwordx4 v[212:213], off
	v_lshl_add_u64 v[212:213], s[50:51], 0, v[136:137]
	s_mov_b32 m0, s52
	s_nop 0
	global_load_lds_dwordx4 v[212:213], off
	v_lshl_add_u64 v[212:213], s[50:51], 0, v[132:133]
	s_mov_b32 m0, s63
	s_nop 0
	global_load_lds_dwordx4 v[212:213], off
	s_waitcnt vmcnt(8)
	s_waitcnt lgkmcnt(0)
	s_barrier
	s_setprio 1
	s_waitcnt lgkmcnt(0)
	v_mfma_f32_16x16x32_bf16 v[62:65], v[148:151], v[202:205], v[62:65]
	v_mfma_f32_16x16x32_bf16 v[58:61], v[156:159], v[202:205], v[58:61]
	v_mfma_f32_16x16x32_bf16 v[54:57], v[148:151], v[226:229], v[54:57]
	v_mfma_f32_16x16x32_bf16 v[46:49], v[156:159], v[226:229], v[46:49]
	v_mfma_f32_16x16x32_bf16 v[38:41], v[148:151], v[234:237], v[38:41]
	v_mfma_f32_16x16x32_bf16 v[30:33], v[156:159], v[234:237], v[30:33]
	v_mfma_f32_16x16x32_bf16 v[22:25], v[148:151], v[242:245], v[22:25]
	v_mfma_f32_16x16x32_bf16 v[14:17], v[156:159], v[242:245], v[14:17]
	v_mfma_f32_16x16x32_bf16 v[62:65], v[152:155], v[206:209], v[62:65]
	v_mfma_f32_16x16x32_bf16 v[58:61], v[160:163], v[206:209], v[58:61]
	v_mfma_f32_16x16x32_bf16 v[54:57], v[152:155], v[230:233], v[54:57]
	v_mfma_f32_16x16x32_bf16 v[46:49], v[160:163], v[230:233], v[46:49]
	v_mfma_f32_16x16x32_bf16 v[38:41], v[152:155], v[238:241], v[38:41]
	v_mfma_f32_16x16x32_bf16 v[30:33], v[160:163], v[238:241], v[30:33]
	v_mfma_f32_16x16x32_bf16 v[22:25], v[152:155], v[246:249], v[22:25]
	v_mfma_f32_16x16x32_bf16 v[14:17], v[160:163], v[246:249], v[14:17]
	v_mfma_f32_16x16x32_bf16 v[50:53], v[186:189], v[202:205], v[50:53]
	v_mfma_f32_16x16x32_bf16 v[42:45], v[194:197], v[202:205], v[42:45]
	v_mfma_f32_16x16x32_bf16 v[34:37], v[186:189], v[226:229], v[34:37]
	v_mfma_f32_16x16x32_bf16 v[26:29], v[194:197], v[226:229], v[26:29]
	v_mfma_f32_16x16x32_bf16 v[18:21], v[186:189], v[234:237], v[18:21]
	v_mfma_f32_16x16x32_bf16 v[10:13], v[194:197], v[234:237], v[10:13]
	v_mfma_f32_16x16x32_bf16 v[6:9], v[186:189], v[242:245], v[6:9]
	v_mfma_f32_16x16x32_bf16 v[2:5], v[194:197], v[242:245], v[2:5]
	v_mfma_f32_16x16x32_bf16 v[50:53], v[190:193], v[206:209], v[50:53]
	v_mfma_f32_16x16x32_bf16 v[42:45], v[198:201], v[206:209], v[42:45]
	v_mfma_f32_16x16x32_bf16 v[34:37], v[190:193], v[230:233], v[34:37]
	v_mfma_f32_16x16x32_bf16 v[26:29], v[198:201], v[230:233], v[26:29]
	v_mfma_f32_16x16x32_bf16 v[18:21], v[190:193], v[238:241], v[18:21]
	v_mfma_f32_16x16x32_bf16 v[10:13], v[198:201], v[238:241], v[10:13]
	v_mfma_f32_16x16x32_bf16 v[6:9], v[190:193], v[246:249], v[6:9]
	v_mfma_f32_16x16x32_bf16 v[2:5], v[198:201], v[246:249], v[2:5]
	s_setprio 0
	s_barrier
	s_add_i32 s96, s96, 2
	s_add_u32 s48, s48, 0x100
	s_addc_u32 s49, s49, 0
	s_cmp_gt_u32 s96, 29
	s_cbranch_scc0 .LBB0_253
	s_and_b64 vcc, exec, s[34:35]
	s_cbranch_vccz .LBB0_256
	s_barrier

; #define PG8_STAGE(bufoff, gbase, voff) do { _Pragma("unroll") for (int _i = 0; _i < 2; ++_i) \
;         __builtin_amdgcn_global_load_lds((const unsigned*)((const char*)(gbase) + (voff)[_i]), (LAS unsigned*)(lds + (bufoff) + ldsw + _i * 8192), 16, 0, 0); } while (0)
; #define PG8_LDA(dst, b, h) do { _Pragma("unroll") for (int m = 0; m < 4; ++m) _Pragma("unroll") for (int k = 0; k < 2; ++k) dst[m][k] = *(const LAS bf16x8*)(lds + PG8_SA(b, h) + aoff + m * 2048 + k * 1024); } while (0)
; #define PG8_LDB(dst, b, h) do { _Pragma("unroll") for (int n = 0; n < 2; ++n) _Pragma("unroll") for (int k = 0; k < 2; ++k) dst[n][k] = *(const LAS bf16x8*)(lds + PG8_SB(b, h) + boff + n * 2048 + k * 1024); } while (0)
; #define PG8_MMA(ai, bj, At, Bt) do { __builtin_amdgcn_s_setprio(1); _Pragma("unroll") for (int m = 0; m < 4; ++m) _Pragma("unroll") for (int n = 0; n < 2; ++n) _Pragma("unroll") for (int k = 0; k < 2; ++k) \
;         acc[ai][bj][m][n] = __builtin_amdgcn_mfma_f32_16x16x32_bf16(Bt[n][k], At[m][k], acc[ai][bj][m][n], 0, 0, 0); __builtin_amdgcn_s_setprio(0); } while (0)
; #define PG8_WAIT_V(n) asm volatile("s_waitcnt vmcnt(" #n ")" ::: "memory")
; #define PG8_WAIT_L(n) asm volatile("s_waitcnt lgkmcnt(" #n ")" ::: "memory")
; template <class Epi>
; __device__ __forceinline__ void gemm_phase(LAS unsigned char* lds, const Gemm g, const StaticOrder& S, const Epi& E) {
;     ...
;         for (int t = 0; t < nt; t += 2) {
;             if constexpr (Epi::GATED) { if (t == 8 || t == 16) E.rescale(acc, cur, t == 8 ? 0 : 1, wr, wc, fr, fq); }
;             const bool last = (t == nt - 2);
;             const char* a1 = PG8_AP(cA, t + 1);
;             const char* a2 = last ? nA : PG8_AP(cA, t + 2); const char* b2 = last ? nB : cB + (size_t)(t + 2) * kstep;
;             const char* a3 = last ? nA + kstep : PG8_AP(cA, t + 3); const char* b3 = b2 + kstep;
;             PG8_LDB(B0, 0, 0); PG8_LDB(B1, 0, 1); PG8_SCHED; PG8_LDA(At, 0, 0); PG8_STAGE(PG8_SA(1, 1), a1 + hstepA, voffA);
;             PG8_WAIT_V(8); PG8_WAIT_L(0); PG8_BAR; PG8_MMA(0, 0, At, B0); PG8_MMA(0, 1, At, B1); PG8_BAR; PG8_SCHED;
;             PG8_LDA(At, 0, 1); PG8_STAGE(PG8_SB(0, 0), b2, voffB); PG8_STAGE(PG8_SB(0, 1), b2 + hstep, voffB); PG8_STAGE(PG8_SA(0, 0), a2, voffA);
;             PG8_WAIT_V(8); PG8_WAIT_L(0); PG8_BAR; PG8_MMA(1, 0, At, B0); PG8_MMA(1, 1, At, B1); PG8_BAR; PG8_SCHED;
.LBB0_277:
	s_add_u32 s86, s54, s56
	s_addc_u32 s87, s55, s57
	s_add_u32 s90, s86, 0x100
	s_addc_u32 s91, s87, 0
	s_add_u32 s92, s80, s56
	s_addc_u32 s93, s81, s57
	s_add_u32 s86, s86, 0x180
	s_addc_u32 s87, s87, 0
	s_add_i32 s94, 0, 0x10000
	s_add_i32 s12, 0, 0x14000
	v_add_u32_e32 v147, s94, v1
	ds_read_b128 v[148:151], v147
	ds_read_b128 v[152:155], v147 offset:1024
	ds_read_b128 v[156:159], v147 offset:2048
	ds_read_b128 v[160:163], v147 offset:3072
	v_add_u32_e32 v147, s12, v1
	ds_read_b128 v[186:189], v147
	ds_read_b128 v[190:193], v147 offset:1024
	ds_read_b128 v[194:197], v147 offset:2048
	ds_read_b128 v[198:201], v147 offset:3072
	s_cmpk_eq_i32 s56, 0xf00
	s_cselect_b32 s97, s67, s87
	s_cselect_b32 s96, s63, s86
	s_cselect_b32 vcc_hi, s43, s93
	s_cselect_b32 vcc_lo, s52, s92
	s_cselect_b32 s87, s41, s91
	s_cselect_b32 s86, s45, s90
	v_lshl_add_u64 v[212:213], v[142:143], 0, s[56:57]
	s_add_i32 m0, s25, 0xc000
	ds_read_b128 v[202:205], v146
	ds_read_b128 v[206:209], v146 offset:1024
	ds_read_b128 v[226:229], v146 offset:2048
	ds_read_b128 v[230:233], v146 offset:3072
	ds_read_b128 v[234:237], v146 offset:4096
	ds_read_b128 v[238:241], v146 offset:5120
	ds_read_b128 v[242:245], v146 offset:6144
	ds_read_b128 v[246:249], v146 offset:7168
	global_load_lds_dwordx4 v[212:213], off
	v_lshl_add_u64 v[212:213], v[144:145], 0, s[56:57]
	s_add_i32 m0, s25, 0xe000
	s_nop 0
	global_load_lds_dwordx4 v[212:213], off
	s_waitcnt vmcnt(8)
	s_waitcnt lgkmcnt(0)
	s_barrier
	s_setprio 1
	s_waitcnt lgkmcnt(0)
	v_mfma_f32_16x16x32_bf16 v[126:129], v[148:151], v[202:205], v[126:129]
	v_mfma_f32_16x16x32_bf16 v[122:125], v[156:159], v[202:205], v[122:125]
	v_mfma_f32_16x16x32_bf16 v[110:113], v[148:151], v[226:229], v[110:113]
	v_mfma_f32_16x16x32_bf16 v[106:109], v[156:159], v[226:229], v[106:109]
	v_mfma_f32_16x16x32_bf16 v[94:97], v[148:151], v[234:237], v[94:97]
	v_mfma_f32_16x16x32_bf16 v[90:93], v[156:159], v[234:237], v[90:93]
	v_mfma_f32_16x16x32_bf16 v[78:81], v[148:151], v[242:245], v[78:81]
	v_mfma_f32_16x16x32_bf16 v[74:77], v[156:159], v[242:245], v[74:77]
	v_mfma_f32_16x16x32_bf16 v[126:129], v[152:155], v[206:209], v[126:129]
	v_mfma_f32_16x16x32_bf16 v[122:125], v[160:163], v[206:209], v[122:125]
	v_mfma_f32_16x16x32_bf16 v[110:113], v[152:155], v[230:233], v[110:113]
	v_mfma_f32_16x16x32_bf16 v[106:109], v[160:163], v[230:233], v[106:109]
	v_mfma_f32_16x16x32_bf16 v[94:97], v[152:155], v[238:241], v[94:97]
	v_mfma_f32_16x16x32_bf16 v[90:93], v[160:163], v[238:241], v[90:93]
	v_mfma_f32_16x16x32_bf16 v[78:81], v[152:155], v[246:249], v[78:81]
	v_mfma_f32_16x16x32_bf16 v[74:77], v[160:163], v[246:249], v[74:77]
	v_mfma_f32_16x16x32_bf16 v[118:121], v[186:189], v[202:205], v[118:121]
	v_mfma_f32_16x16x32_bf16 v[114:117], v[194:197], v[202:205], v[114:117]
	v_mfma_f32_16x16x32_bf16 v[102:105], v[186:189], v[226:229], v[102:105]
	v_mfma_f32_16x16x32_bf16 v[98:101], v[194:197], v[226:229], v[98:101]
	v_mfma_f32_16x16x32_bf16 v[86:89], v[186:189], v[234:237], v[86:89]
	v_mfma_f32_16x16x32_bf16 v[82:85], v[194:197], v[234:237], v[82:85]
	v_mfma_f32_16x16x32_bf16 v[70:73], v[186:189], v[242:245], v[70:73]
	v_mfma_f32_16x16x32_bf16 v[66:69], v[194:197], v[242:245], v[66:69]
	v_mfma_f32_16x16x32_bf16 v[118:121], v[190:193], v[206:209], v[118:121]
	v_mfma_f32_16x16x32_bf16 v[114:117], v[198:201], v[206:209], v[114:117]
	v_mfma_f32_16x16x32_bf16 v[102:105], v[190:193], v[230:233], v[102:105]
	v_mfma_f32_16x16x32_bf16 v[98:101], v[198:201], v[230:233], v[98:101]
	v_mfma_f32_16x16x32_bf16 v[86:89], v[190:193], v[238:241], v[86:89]
	v_mfma_f32_16x16x32_bf16 v[82:85], v[198:201], v[238:241], v[82:85]
	v_mfma_f32_16x16x32_bf16 v[70:73], v[190:193], v[246:249], v[70:73]
	v_mfma_f32_16x16x32_bf16 v[66:69], v[198:201], v[246:249], v[66:69]
	s_setprio 0
	s_barrier
	s_add_i32 s13, s94, s24
	v_lshl_add_u64 v[212:213], vcc, 0, v[132:133]
	s_mov_b32 m0, s13
	ds_read_b128 v[202:205], v146 offset:16384
	ds_read_b128 v[206:209], v146 offset:17408
	ds_read_b128 v[226:229], v146 offset:18432
	ds_read_b128 v[230:233], v146 offset:19456
	ds_read_b128 v[234:237], v146 offset:20480
	ds_read_b128 v[238:241], v146 offset:21504
	ds_read_b128 v[242:245], v146 offset:22528
	ds_read_b128 v[246:249], v146 offset:23552
	global_load_lds_dwordx4 v[212:213], off
	s_add_i32 m0, s13, 0x2000
	s_add_u32 s92, vcc_lo, 0x80000
	v_lshl_add_u64 v[222:223], vcc, 0, v[136:137]
	s_addc_u32 s93, vcc_hi, 0
	s_add_i32 s12, s12, s24
	global_load_lds_dwordx4 v[222:223], off
	v_lshl_add_u64 v[224:225], s[92:93], 0, v[132:133]
	s_mov_b32 m0, s12
	s_nop 0
	global_load_lds_dwordx4 v[224:225], off
	v_lshl_add_u64 v[224:225], s[92:93], 0, v[136:137]
	s_add_i32 m0, s12, 0x2000
	s_nop 0
	global_load_lds_dwordx4 v[224:225], off
	v_lshl_add_u64 v[224:225], s[86:87], 0, v[130:131]
	s_mov_b32 m0, s25
	s_nop 0
	global_load_lds_dwordx4 v[224:225], off
	v_lshl_add_u64 v[224:225], s[86:87], 0, v[134:135]
	s_mov_b32 m0, s26
	s_nop 0
	global_load_lds_dwordx4 v[224:225], off
	s_waitcnt vmcnt(8)
	s_waitcnt lgkmcnt(0)
	s_barrier
; #define PG8_STAGE(bufoff, gbase, voff) do { _Pragma("unroll") for (int _i = 0; _i < 2; ++_i) \
;         __builtin_amdgcn_global_load_lds((const unsigned*)((const char*)(gbase) + (voff)[_i]), (LAS unsigned*)(lds + (bufoff) + ldsw + _i * 8192), 16, 0, 0); } while (0)
; #define PG8_LDA(dst, b, h) do { _Pragma("unroll") for (int m = 0; m < 4; ++m) _Pragma("unroll") for (int k = 0; k < 2; ++k) dst[m][k] = *(const LAS bf16x8*)(lds + PG8_SA(b, h) + aoff + m * 2048 + k * 1024); } while (0)
; #define PG8_LDB(dst, b, h) do { _Pragma("unroll") for (int n = 0; n < 2; ++n) _Pragma("unroll") for (int k = 0; k < 2; ++k) dst[n][k] = *(const LAS bf16x8*)(lds + PG8_SB(b, h) + boff + n * 2048 + k * 1024); } while (0)
; #define PG8_MMA(ai, bj, At, Bt) do { __builtin_amdgcn_s_setprio(1); _Pragma("unroll") for (int m = 0; m < 4; ++m) _Pragma("unroll") for (int n = 0; n < 2; ++n) _Pragma("unroll") for (int k = 0; k < 2; ++k) \
;         acc[ai][bj][m][n] = __builtin_amdgcn_mfma_f32_16x16x32_bf16(Bt[n][k], At[m][k], acc[ai][bj][m][n], 0, 0, 0); __builtin_amdgcn_s_setprio(0); } while (0)
; #define PG8_WAIT_V(n) asm volatile("s_waitcnt vmcnt(" #n ")" ::: "memory")
; #define PG8_WAIT_L(n) asm volatile("s_waitcnt lgkmcnt(" #n ")" ::: "memory")
; #define PG8_BAR __builtin_amdgcn_s_barrier()
; #define PG8_SCHED __builtin_amdgcn_sched_barrier(0)
; template <class Epi>
; __device__ __forceinline__ void gemm_phase(LAS unsigned char* lds, const Gemm g, const StaticOrder& S, const Epi& E) {
;     ...
;             PG8_WAIT_V(8); PG8_WAIT_L(0); PG8_BAR; PG8_MMA(0, 0, At, B0); PG8_MMA(0, 1, At, B1); PG8_BAR; PG8_SCHED;
;             PG8_LDA(At, 0, 1); PG8_STAGE(PG8_SB(0, 0), b2, voffB); PG8_STAGE(PG8_SB(0, 1), b2 + hstep, voffB); PG8_STAGE(PG8_SA(0, 0), a2, voffA);
;             PG8_WAIT_V(8); PG8_WAIT_L(0); PG8_BAR; PG8_MMA(1, 0, At, B0); PG8_MMA(1, 1, At, B1); PG8_BAR; PG8_SCHED;
;             PG8_LDB(B0, 1, 0); PG8_LDB(B1, 1, 1); PG8_SCHED; PG8_LDA(At, 1, 0); PG8_STAGE(PG8_SA(0, 1), a2 + hstepA, voffA);
;             PG8_WAIT_V(8); PG8_WAIT_L(0); PG8_BAR; PG8_MMA(0, 0, At, B0); PG8_MMA(0, 1, At, B1); PG8_BAR; PG8_SCHED;
	s_setprio 1
	s_waitcnt lgkmcnt(0)
	v_mfma_f32_16x16x32_bf16 v[62:65], v[148:151], v[202:205], v[62:65]
	v_mfma_f32_16x16x32_bf16 v[58:61], v[156:159], v[202:205], v[58:61]
	v_mfma_f32_16x16x32_bf16 v[46:49], v[148:151], v[226:229], v[46:49]
	v_mfma_f32_16x16x32_bf16 v[42:45], v[156:159], v[226:229], v[42:45]
	v_mfma_f32_16x16x32_bf16 v[30:33], v[148:151], v[234:237], v[30:33]
	v_mfma_f32_16x16x32_bf16 v[26:29], v[156:159], v[234:237], v[26:29]
	v_mfma_f32_16x16x32_bf16 v[14:17], v[148:151], v[242:245], v[14:17]
	v_mfma_f32_16x16x32_bf16 v[10:13], v[156:159], v[242:245], v[10:13]
	v_mfma_f32_16x16x32_bf16 v[62:65], v[152:155], v[206:209], v[62:65]
	v_mfma_f32_16x16x32_bf16 v[58:61], v[160:163], v[206:209], v[58:61]
	v_mfma_f32_16x16x32_bf16 v[46:49], v[152:155], v[230:233], v[46:49]
	v_mfma_f32_16x16x32_bf16 v[42:45], v[160:163], v[230:233], v[42:45]
	v_mfma_f32_16x16x32_bf16 v[30:33], v[152:155], v[238:241], v[30:33]
	v_mfma_f32_16x16x32_bf16 v[26:29], v[160:163], v[238:241], v[26:29]
	v_mfma_f32_16x16x32_bf16 v[14:17], v[152:155], v[246:249], v[14:17]
	v_mfma_f32_16x16x32_bf16 v[10:13], v[160:163], v[246:249], v[10:13]
	v_mfma_f32_16x16x32_bf16 v[54:57], v[186:189], v[202:205], v[54:57]
	v_mfma_f32_16x16x32_bf16 v[50:53], v[194:197], v[202:205], v[50:53]
	v_mfma_f32_16x16x32_bf16 v[38:41], v[186:189], v[226:229], v[38:41]
	v_mfma_f32_16x16x32_bf16 v[34:37], v[194:197], v[226:229], v[34:37]
	v_mfma_f32_16x16x32_bf16 v[22:25], v[186:189], v[234:237], v[22:25]
	v_mfma_f32_16x16x32_bf16 v[18:21], v[194:197], v[234:237], v[18:21]
	v_mfma_f32_16x16x32_bf16 v[6:9], v[186:189], v[242:245], v[6:9]
	v_mfma_f32_16x16x32_bf16 v[2:5], v[194:197], v[242:245], v[2:5]
	v_mfma_f32_16x16x32_bf16 v[54:57], v[190:193], v[206:209], v[54:57]
	v_mfma_f32_16x16x32_bf16 v[50:53], v[198:201], v[206:209], v[50:53]
	v_mfma_f32_16x16x32_bf16 v[38:41], v[190:193], v[230:233], v[38:41]
	v_mfma_f32_16x16x32_bf16 v[34:37], v[198:201], v[230:233], v[34:37]
	v_mfma_f32_16x16x32_bf16 v[22:25], v[190:193], v[238:241], v[22:25]
	v_mfma_f32_16x16x32_bf16 v[18:21], v[198:201], v[238:241], v[18:21]
	v_mfma_f32_16x16x32_bf16 v[6:9], v[190:193], v[246:249], v[6:9]
	v_mfma_f32_16x16x32_bf16 v[2:5], v[198:201], v[246:249], v[2:5]
	s_setprio 0
	s_barrier
	s_add_i32 s12, 0, 0x18000
	v_add_u32_e32 v147, s12, v1
	s_add_i32 s13, 0, 0x1c000
	ds_read_b128 v[148:151], v147
	ds_read_b128 v[152:155], v147 offset:1024
	ds_read_b128 v[156:159], v147 offset:2048
	ds_read_b128 v[160:163], v147 offset:3072
	v_add_u32_e32 v147, s13, v1
	ds_read_b128 v[186:189], v147
	ds_read_b128 v[190:193], v147 offset:1024
	ds_read_b128 v[194:197], v147 offset:2048
	ds_read_b128 v[198:201], v147 offset:3072
	s_add_u32 s86, s86, 0x80000
	s_addc_u32 s87, s87, 0
	s_mov_b32 m0, s27
	v_lshl_add_u64 v[224:225], s[86:87], 0, v[130:131]
	ds_read_b128 v[202:205], v146 offset:32768
	ds_read_b128 v[206:209], v146 offset:33792
	ds_read_b128 v[226:229], v146 offset:34816
	ds_read_b128 v[230:233], v146 offset:35840
	ds_read_b128 v[234:237], v146 offset:36864
	ds_read_b128 v[238:241], v146 offset:37888
	ds_read_b128 v[242:245], v146 offset:38912
	ds_read_b128 v[246:249], v146 offset:39936
	global_load_lds_dwordx4 v[224:225], off
	v_lshl_add_u64 v[224:225], s[86:87], 0, v[134:135]
	s_mov_b32 m0, s28
	s_nop 0
	global_load_lds_dwordx4 v[224:225], off
	s_waitcnt vmcnt(8)
	s_waitcnt lgkmcnt(0)
	s_barrier
	s_setprio 1
	s_waitcnt lgkmcnt(0)
	v_mfma_f32_16x16x32_bf16 v[126:129], v[148:151], v[202:205], v[126:129]
	v_mfma_f32_16x16x32_bf16 v[122:125], v[156:159], v[202:205], v[122:125]
	v_mfma_f32_16x16x32_bf16 v[110:113], v[148:151], v[226:229], v[110:113]
	v_mfma_f32_16x16x32_bf16 v[106:109], v[156:159], v[226:229], v[106:109]
	v_mfma_f32_16x16x32_bf16 v[94:97], v[148:151], v[234:237], v[94:97]
	v_mfma_f32_16x16x32_bf16 v[90:93], v[156:159], v[234:237], v[90:93]
	v_mfma_f32_16x16x32_bf16 v[78:81], v[148:151], v[242:245], v[78:81]
	v_mfma_f32_16x16x32_bf16 v[74:77], v[156:159], v[242:245], v[74:77]
	v_mfma_f32_16x16x32_bf16 v[126:129], v[152:155], v[206:209], v[126:129]
	v_mfma_f32_16x16x32_bf16 v[122:125], v[160:163], v[206:209], v[122:125]
	v_mfma_f32_16x16x32_bf16 v[110:113], v[152:155], v[230:233], v[110:113]
	v_mfma_f32_16x16x32_bf16 v[106:109], v[160:163], v[230:233], v[106:109]
	v_mfma_f32_16x16x32_bf16 v[94:97], v[152:155], v[238:241], v[94:97]
	v_mfma_f32_16x16x32_bf16 v[90:93], v[160:163], v[238:241], v[90:93]
	v_mfma_f32_16x16x32_bf16 v[78:81], v[152:155], v[246:249], v[78:81]
	v_mfma_f32_16x16x32_bf16 v[74:77], v[160:163], v[246:249], v[74:77]
	v_mfma_f32_16x16x32_bf16 v[118:121], v[186:189], v[202:205], v[118:121]
	v_mfma_f32_16x16x32_bf16 v[114:117], v[194:197], v[202:205], v[114:117]
	v_mfma_f32_16x16x32_bf16 v[102:105], v[186:189], v[226:229], v[102:105]
	v_mfma_f32_16x16x32_bf16 v[98:101], v[194:197], v[226:229], v[98:101]
	v_mfma_f32_16x16x32_bf16 v[86:89], v[186:189], v[234:237], v[86:89]
	v_mfma_f32_16x16x32_bf16 v[82:85], v[194:197], v[234:237], v[82:85]
	v_mfma_f32_16x16x32_bf16 v[70:73], v[186:189], v[242:245], v[70:73]
	v_mfma_f32_16x16x32_bf16 v[66:69], v[194:197], v[242:245], v[66:69]
	v_mfma_f32_16x16x32_bf16 v[118:121], v[190:193], v[206:209], v[118:121]
	v_mfma_f32_16x16x32_bf16 v[114:117], v[198:201], v[206:209], v[114:117]
	v_mfma_f32_16x16x32_bf16 v[102:105], v[190:193], v[230:233], v[102:105]
	v_mfma_f32_16x16x32_bf16 v[98:101], v[198:201], v[230:233], v[98:101]
	v_mfma_f32_16x16x32_bf16 v[86:89], v[190:193], v[238:241], v[86:89]
	v_mfma_f32_16x16x32_bf16 v[82:85], v[198:201], v[238:241], v[82:85]
	v_mfma_f32_16x16x32_bf16 v[70:73], v[190:193], v[246:249], v[70:73]
	v_mfma_f32_16x16x32_bf16 v[66:69], v[198:201], v[246:249], v[66:69]
	s_setprio 0
	s_barrier
; #define PG8_STAGE(bufoff, gbase, voff) do { _Pragma("unroll") for (int _i = 0; _i < 2; ++_i) \
;         __builtin_amdgcn_global_load_lds((const unsigned*)((const char*)(gbase) + (voff)[_i]), (LAS unsigned*)(lds + (bufoff) + ldsw + _i * 8192), 16, 0, 0); } while (0)
; #define PG8_LDA(dst, b, h) do { _Pragma("unroll") for (int m = 0; m < 4; ++m) _Pragma("unroll") for (int k = 0; k < 2; ++k) dst[m][k] = *(const LAS bf16x8*)(lds + PG8_SA(b, h) + aoff + m * 2048 + k * 1024); } while (0)
; #define PG8_MMA(ai, bj, At, Bt) do { __builtin_amdgcn_s_setprio(1); _Pragma("unroll") for (int m = 0; m < 4; ++m) _Pragma("unroll") for (int n = 0; n < 2; ++n) _Pragma("unroll") for (int k = 0; k < 2; ++k) \
;         acc[ai][bj][m][n] = __builtin_amdgcn_mfma_f32_16x16x32_bf16(Bt[n][k], At[m][k], acc[ai][bj][m][n], 0, 0, 0); __builtin_amdgcn_s_setprio(0); } while (0)
; #define PG8_WAIT_V(n) asm volatile("s_waitcnt vmcnt(" #n ")" ::: "memory")
; #define PG8_WAIT_L(n) asm volatile("s_waitcnt lgkmcnt(" #n ")" ::: "memory")
; #define PG8_BAR __builtin_amdgcn_s_barrier()
; #define PG8_SCHED __builtin_amdgcn_sched_barrier(0)
; template <class Epi>
; __device__ __forceinline__ void gemm_phase(LAS unsigned char* lds, const Gemm g, const StaticOrder& S, const Epi& E) {
;     ...
;             PG8_WAIT_V(8); PG8_WAIT_L(0); PG8_BAR; PG8_MMA(0, 0, At, B0); PG8_MMA(0, 1, At, B1); PG8_BAR; PG8_SCHED;
;             PG8_LDA(At, 1, 1); PG8_STAGE(PG8_SB(1, 0), b3, voffB); PG8_STAGE(PG8_SB(1, 1), b3 + hstep, voffB); PG8_STAGE(PG8_SA(1, 0), a3, voffA);
;             PG8_WAIT_V(8); PG8_WAIT_L(0); PG8_BAR; PG8_MMA(1, 0, At, B0); PG8_MMA(1, 1, At, B1); PG8_BAR; PG8_SCHED;
;         }
;         if (wr == 0) PG8_BAR;
	s_add_i32 s12, s12, s24
	v_lshl_add_u64 v[212:213], v[212:213], 0, s[6:7]
	s_mov_b32 m0, s12
	ds_read_b128 v[202:205], v146 offset:49152
	ds_read_b128 v[206:209], v146 offset:50176
	ds_read_b128 v[226:229], v146 offset:51200
	ds_read_b128 v[230:233], v146 offset:52224
	ds_read_b128 v[234:237], v146 offset:53248
	ds_read_b128 v[238:241], v146 offset:54272
	ds_read_b128 v[242:245], v146 offset:55296
	ds_read_b128 v[246:249], v146 offset:56320
	global_load_lds_dwordx4 v[212:213], off
	s_add_i32 m0, s12, 0x2000
	s_add_u32 s86, vcc_lo, 0x80080
	v_lshl_add_u64 v[212:213], v[222:223], 0, s[6:7]
	s_addc_u32 s87, vcc_hi, 0
	s_add_i32 s12, s13, s24
	global_load_lds_dwordx4 v[212:213], off
	v_lshl_add_u64 v[212:213], s[86:87], 0, v[132:133]
	s_mov_b32 m0, s12
	s_nop 0
	global_load_lds_dwordx4 v[212:213], off
	v_lshl_add_u64 v[212:213], s[86:87], 0, v[136:137]
	s_add_i32 m0, s12, 0x2000
	s_nop 0
	global_load_lds_dwordx4 v[212:213], off
	v_lshl_add_u64 v[212:213], s[96:97], 0, v[130:131]
	s_mov_b32 m0, s29
	s_nop 0
	global_load_lds_dwordx4 v[212:213], off
	v_lshl_add_u64 v[212:213], s[96:97], 0, v[134:135]
	s_mov_b32 m0, s33
	s_nop 0
	global_load_lds_dwordx4 v[212:213], off
	s_waitcnt vmcnt(8)
	s_waitcnt lgkmcnt(0)
	s_barrier
	s_setprio 1
	s_waitcnt lgkmcnt(0)
	v_mfma_f32_16x16x32_bf16 v[62:65], v[148:151], v[202:205], v[62:65]
	v_mfma_f32_16x16x32_bf16 v[58:61], v[156:159], v[202:205], v[58:61]
	v_mfma_f32_16x16x32_bf16 v[46:49], v[148:151], v[226:229], v[46:49]
	v_mfma_f32_16x16x32_bf16 v[42:45], v[156:159], v[226:229], v[42:45]
	v_mfma_f32_16x16x32_bf16 v[30:33], v[148:151], v[234:237], v[30:33]
	v_mfma_f32_16x16x32_bf16 v[26:29], v[156:159], v[234:237], v[26:29]
	v_mfma_f32_16x16x32_bf16 v[14:17], v[148:151], v[242:245], v[14:17]
	v_mfma_f32_16x16x32_bf16 v[10:13], v[156:159], v[242:245], v[10:13]
	v_mfma_f32_16x16x32_bf16 v[62:65], v[152:155], v[206:209], v[62:65]
	v_mfma_f32_16x16x32_bf16 v[58:61], v[160:163], v[206:209], v[58:61]
	v_mfma_f32_16x16x32_bf16 v[46:49], v[152:155], v[230:233], v[46:49]
	v_mfma_f32_16x16x32_bf16 v[42:45], v[160:163], v[230:233], v[42:45]
	v_mfma_f32_16x16x32_bf16 v[30:33], v[152:155], v[238:241], v[30:33]
	v_mfma_f32_16x16x32_bf16 v[26:29], v[160:163], v[238:241], v[26:29]
	v_mfma_f32_16x16x32_bf16 v[14:17], v[152:155], v[246:249], v[14:17]
	v_mfma_f32_16x16x32_bf16 v[10:13], v[160:163], v[246:249], v[10:13]
	v_mfma_f32_16x16x32_bf16 v[54:57], v[186:189], v[202:205], v[54:57]
	v_mfma_f32_16x16x32_bf16 v[50:53], v[194:197], v[202:205], v[50:53]
	v_mfma_f32_16x16x32_bf16 v[38:41], v[186:189], v[226:229], v[38:41]
	v_mfma_f32_16x16x32_bf16 v[34:37], v[194:197], v[226:229], v[34:37]
	v_mfma_f32_16x16x32_bf16 v[22:25], v[186:189], v[234:237], v[22:25]
	v_mfma_f32_16x16x32_bf16 v[18:21], v[194:197], v[234:237], v[18:21]
	v_mfma_f32_16x16x32_bf16 v[6:9], v[186:189], v[242:245], v[6:9]
	v_mfma_f32_16x16x32_bf16 v[2:5], v[194:197], v[242:245], v[2:5]
	v_mfma_f32_16x16x32_bf16 v[54:57], v[190:193], v[206:209], v[54:57]
	v_mfma_f32_16x16x32_bf16 v[50:53], v[198:201], v[206:209], v[50:53]
	v_mfma_f32_16x16x32_bf16 v[38:41], v[190:193], v[230:233], v[38:41]
	v_mfma_f32_16x16x32_bf16 v[34:37], v[198:201], v[230:233], v[34:37]
	v_mfma_f32_16x16x32_bf16 v[22:25], v[190:193], v[238:241], v[22:25]
	v_mfma_f32_16x16x32_bf16 v[18:21], v[198:201], v[238:241], v[18:21]
	v_mfma_f32_16x16x32_bf16 v[6:9], v[190:193], v[246:249], v[6:9]
	v_mfma_f32_16x16x32_bf16 v[2:5], v[198:201], v[246:249], v[2:5]
	s_setprio 0
	s_barrier
	s_add_i32 s85, s85, 2
	s_add_u32 s56, s56, 0x100
	s_addc_u32 s57, s57, 0
	s_cmp_gt_u32 s85, 29
	s_cbranch_scc0 .LBB0_277
	s_and_b64 vcc, exec, s[36:37]
	s_cbranch_vccz .LBB0_280
	s_barrier

; #define PG8_STAGE(bufoff, gbase, voff) do { _Pragma("unroll") for (int _i = 0; _i < 2; ++_i) \
;         __builtin_amdgcn_global_load_lds((const unsigned*)((const char*)(gbase) + (voff)[_i]), (LAS unsigned*)(lds + (bufoff) + ldsw + _i * 8192), 16, 0, 0); } while (0)
; #define PG8_LDA(dst, b, h) do { _Pragma("unroll") for (int m = 0; m < 4; ++m) _Pragma("unroll") for (int k = 0; k < 2; ++k) dst[m][k] = *(const LAS bf16x8*)(lds + PG8_SA(b, h) + aoff + m * 2048 + k * 1024); } while (0)
; #define PG8_LDB(dst, b, h) do { _Pragma("unroll") for (int n = 0; n < 2; ++n) _Pragma("unroll") for (int k = 0; k < 2; ++k) dst[n][k] = *(const LAS bf16x8*)(lds + PG8_SB(b, h) + boff + n * 2048 + k * 1024); } while (0)
; #define PG8_MMA(ai, bj, At, Bt) do { __builtin_amdgcn_s_setprio(1); _Pragma("unroll") for (int m = 0; m < 4; ++m) _Pragma("unroll") for (int n = 0; n < 2; ++n) _Pragma("unroll") for (int k = 0; k < 2; ++k) \
;         acc[ai][bj][m][n] = __builtin_amdgcn_mfma_f32_16x16x32_bf16(Bt[n][k], At[m][k], acc[ai][bj][m][n], 0, 0, 0); __builtin_amdgcn_s_setprio(0); } while (0)
; #define PG8_WAIT_V(n) asm volatile("s_waitcnt vmcnt(" #n ")" ::: "memory")
; #define PG8_WAIT_L(n) asm volatile("s_waitcnt lgkmcnt(" #n ")" ::: "memory")
; template <class Epi>
; __device__ __forceinline__ void gemm_phase(LAS unsigned char* lds, const Gemm g, const StaticOrder& S, const Epi& E) {
;     ...
;         for (int t = 0; t < nt; t += 2) {
;             if constexpr (Epi::GATED) { if (t == 8 || t == 16) E.rescale(acc, cur, t == 8 ? 0 : 1, wr, wc, fr, fq); }
;             const bool last = (t == nt - 2);
;             const char* a1 = PG8_AP(cA, t + 1);
;             const char* a2 = last ? nA : PG8_AP(cA, t + 2); const char* b2 = last ? nB : cB + (size_t)(t + 2) * kstep;
;             const char* a3 = last ? nA + kstep : PG8_AP(cA, t + 3); const char* b3 = b2 + kstep;
;             PG8_LDB(B0, 0, 0); PG8_LDB(B1, 0, 1); PG8_SCHED; PG8_LDA(At, 0, 0); PG8_STAGE(PG8_SA(1, 1), a1 + hstepA, voffA);
;             PG8_WAIT_V(8); PG8_WAIT_L(0); PG8_BAR; PG8_MMA(0, 0, At, B0); PG8_MMA(0, 1, At, B1); PG8_BAR; PG8_SCHED;
;             PG8_LDA(At, 0, 1); PG8_STAGE(PG8_SB(0, 0), b2, voffB); PG8_STAGE(PG8_SB(0, 1), b2 + hstep, voffB); PG8_STAGE(PG8_SA(0, 0), a2, voffA);
;             PG8_WAIT_V(8); PG8_WAIT_L(0); PG8_BAR; PG8_MMA(1, 0, At, B0); PG8_MMA(1, 1, At, B1); PG8_BAR; PG8_SCHED;
.LBB0_494:
	s_add_u32 s12, s42, s40
	s_addc_u32 s13, s43, s41
	s_add_u32 s44, s12, 0x100
	s_addc_u32 s45, s13, 0
	s_add_u32 s86, s92, s40
	s_addc_u32 s87, s93, s41
	s_add_u32 s12, s12, 0x180
	s_addc_u32 s13, s13, 0
	s_add_i32 s90, 0, 0x10000
	s_add_i32 s91, 0, 0x14000
	v_add_u32_e32 v150, s90, v1
	ds_read_b128 v[146:149], v150
	ds_read_b128 v[154:157], v150 offset:1024
	ds_read_b128 v[158:161], v150 offset:2048
	ds_read_b128 v[186:189], v150 offset:3072
	v_add_u32_e32 v150, s91, v1
	ds_read_b128 v[190:193], v150
	ds_read_b128 v[194:197], v150 offset:1024
	ds_read_b128 v[198:201], v150 offset:2048
	ds_read_b128 v[202:205], v150 offset:3072
	s_cmpk_eq_i32 s40, 0x200
	s_cselect_b32 s97, s85, s13
	s_cselect_b32 s96, s81, s12
	s_cselect_b32 vcc_hi, s57, s87
	s_cselect_b32 vcc_lo, s56, s86
	s_cselect_b32 s87, s55, s45
	s_cselect_b32 s86, s54, s44
	v_lshl_add_u64 v[150:151], v[142:143], 0, s[40:41]
	s_add_i32 m0, s25, 0xc000
	ds_read_b128 v[206:209], v152
	ds_read_b128 v[226:229], v152 offset:1024
	ds_read_b128 v[230:233], v152 offset:2048
	ds_read_b128 v[234:237], v152 offset:3072
	ds_read_b128 v[238:241], v152 offset:4096
	ds_read_b128 v[242:245], v152 offset:5120
	ds_read_b128 v[246:249], v152 offset:6144
	ds_read_b128 v[222:225], v152 offset:7168
	global_load_lds_dwordx4 v[150:151], off
	v_lshl_add_u64 v[150:151], v[144:145], 0, s[40:41]
	s_add_i32 m0, s25, 0xe000
	s_nop 0
	global_load_lds_dwordx4 v[150:151], off
	s_waitcnt vmcnt(8)
	s_waitcnt lgkmcnt(0)
	s_barrier
	s_setprio 1
	s_waitcnt lgkmcnt(0)
	v_mfma_f32_16x16x32_bf16 v[126:129], v[146:149], v[206:209], v[126:129]
	v_mfma_f32_16x16x32_bf16 v[122:125], v[158:161], v[206:209], v[122:125]
	v_mfma_f32_16x16x32_bf16 v[110:113], v[146:149], v[230:233], v[110:113]
	v_mfma_f32_16x16x32_bf16 v[106:109], v[158:161], v[230:233], v[106:109]
	v_mfma_f32_16x16x32_bf16 v[94:97], v[146:149], v[238:241], v[94:97]
	v_mfma_f32_16x16x32_bf16 v[90:93], v[158:161], v[238:241], v[90:93]
	v_mfma_f32_16x16x32_bf16 v[78:81], v[146:149], v[246:249], v[78:81]
	v_mfma_f32_16x16x32_bf16 v[74:77], v[158:161], v[246:249], v[74:77]
	v_mfma_f32_16x16x32_bf16 v[126:129], v[154:157], v[226:229], v[126:129]
	v_mfma_f32_16x16x32_bf16 v[122:125], v[186:189], v[226:229], v[122:125]
	v_mfma_f32_16x16x32_bf16 v[110:113], v[154:157], v[234:237], v[110:113]
	v_mfma_f32_16x16x32_bf16 v[106:109], v[186:189], v[234:237], v[106:109]
	v_mfma_f32_16x16x32_bf16 v[94:97], v[154:157], v[242:245], v[94:97]
	v_mfma_f32_16x16x32_bf16 v[90:93], v[186:189], v[242:245], v[90:93]
	v_mfma_f32_16x16x32_bf16 v[78:81], v[154:157], v[222:225], v[78:81]
	v_mfma_f32_16x16x32_bf16 v[74:77], v[186:189], v[222:225], v[74:77]
	v_mfma_f32_16x16x32_bf16 v[118:121], v[190:193], v[206:209], v[118:121]
	v_mfma_f32_16x16x32_bf16 v[114:117], v[198:201], v[206:209], v[114:117]
	v_mfma_f32_16x16x32_bf16 v[102:105], v[190:193], v[230:233], v[102:105]
	v_mfma_f32_16x16x32_bf16 v[98:101], v[198:201], v[230:233], v[98:101]
	v_mfma_f32_16x16x32_bf16 v[86:89], v[190:193], v[238:241], v[86:89]
	v_mfma_f32_16x16x32_bf16 v[82:85], v[198:201], v[238:241], v[82:85]
	v_mfma_f32_16x16x32_bf16 v[70:73], v[190:193], v[246:249], v[70:73]
	v_mfma_f32_16x16x32_bf16 v[66:69], v[198:201], v[246:249], v[66:69]
	v_mfma_f32_16x16x32_bf16 v[118:121], v[194:197], v[226:229], v[118:121]
	v_mfma_f32_16x16x32_bf16 v[114:117], v[202:205], v[226:229], v[114:117]
	v_mfma_f32_16x16x32_bf16 v[102:105], v[194:197], v[234:237], v[102:105]
	v_mfma_f32_16x16x32_bf16 v[98:101], v[202:205], v[234:237], v[98:101]
	v_mfma_f32_16x16x32_bf16 v[86:89], v[194:197], v[242:245], v[86:89]
	v_mfma_f32_16x16x32_bf16 v[82:85], v[202:205], v[242:245], v[82:85]
	v_mfma_f32_16x16x32_bf16 v[70:73], v[194:197], v[222:225], v[70:73]
	v_mfma_f32_16x16x32_bf16 v[66:69], v[202:205], v[222:225], v[66:69]
	s_setprio 0
	s_barrier
	s_add_i32 s12, s90, s24
	v_lshl_add_u64 v[150:151], vcc, 0, v[134:135]
	s_mov_b32 m0, s12
	ds_read_b128 v[206:209], v152 offset:16384
	ds_read_b128 v[222:225], v152 offset:17408
	ds_read_b128 v[226:229], v152 offset:18432
	ds_read_b128 v[230:233], v152 offset:19456
	ds_read_b128 v[234:237], v152 offset:20480
	ds_read_b128 v[238:241], v152 offset:21504
	ds_read_b128 v[242:245], v152 offset:22528
	ds_read_b128 v[246:249], v152 offset:23552
	global_load_lds_dwordx4 v[150:151], off
	s_add_i32 m0, s12, 0x2000
	s_add_u32 s44, vcc_lo, 0x18000
	v_lshl_add_u64 v[162:163], vcc, 0, v[130:131]
	s_addc_u32 s45, vcc_hi, 0
	s_add_i32 s12, s91, s24
	global_load_lds_dwordx4 v[162:163], off
	v_lshl_add_u64 v[212:213], s[44:45], 0, v[134:135]
	s_mov_b32 m0, s12
	s_nop 0
	global_load_lds_dwordx4 v[212:213], off
	v_lshl_add_u64 v[212:213], s[44:45], 0, v[130:131]
	s_add_i32 m0, s12, 0x2000
	s_nop 0
	global_load_lds_dwordx4 v[212:213], off
	v_lshl_add_u64 v[212:213], s[86:87], 0, v[136:137]
	s_mov_b32 m0, s25
	s_nop 0
	global_load_lds_dwordx4 v[212:213], off
	v_lshl_add_u64 v[212:213], s[86:87], 0, v[132:133]
	s_mov_b32 m0, s26
	s_nop 0
	global_load_lds_dwordx4 v[212:213], off
	s_waitcnt vmcnt(8)
	s_waitcnt lgkmcnt(0)
	s_barrier
; #define PG8_STAGE(bufoff, gbase, voff) do { _Pragma("unroll") for (int _i = 0; _i < 2; ++_i) \
;         __builtin_amdgcn_global_load_lds((const unsigned*)((const char*)(gbase) + (voff)[_i]), (LAS unsigned*)(lds + (bufoff) + ldsw + _i * 8192), 16, 0, 0); } while (0)
; #define PG8_LDA(dst, b, h) do { _Pragma("unroll") for (int m = 0; m < 4; ++m) _Pragma("unroll") for (int k = 0; k < 2; ++k) dst[m][k] = *(const LAS bf16x8*)(lds + PG8_SA(b, h) + aoff + m * 2048 + k * 1024); } while (0)
; #define PG8_LDB(dst, b, h) do { _Pragma("unroll") for (int n = 0; n < 2; ++n) _Pragma("unroll") for (int k = 0; k < 2; ++k) dst[n][k] = *(const LAS bf16x8*)(lds + PG8_SB(b, h) + boff + n * 2048 + k * 1024); } while (0)
; #define PG8_MMA(ai, bj, At, Bt) do { __builtin_amdgcn_s_setprio(1); _Pragma("unroll") for (int m = 0; m < 4; ++m) _Pragma("unroll") for (int n = 0; n < 2; ++n) _Pragma("unroll") for (int k = 0; k < 2; ++k) \
;         acc[ai][bj][m][n] = __builtin_amdgcn_mfma_f32_16x16x32_bf16(Bt[n][k], At[m][k], acc[ai][bj][m][n], 0, 0, 0); __builtin_amdgcn_s_setprio(0); } while (0)
; #define PG8_WAIT_V(n) asm volatile("s_waitcnt vmcnt(" #n ")" ::: "memory")
; #define PG8_WAIT_L(n) asm volatile("s_waitcnt lgkmcnt(" #n ")" ::: "memory")
; #define PG8_BAR __builtin_amdgcn_s_barrier()
; #define PG8_SCHED __builtin_amdgcn_sched_barrier(0)
; template <class Epi>
; __device__ __forceinline__ void gemm_phase(LAS unsigned char* lds, const Gemm g, const StaticOrder& S, const Epi& E) {
;     ...
;             PG8_WAIT_V(8); PG8_WAIT_L(0); PG8_BAR; PG8_MMA(0, 0, At, B0); PG8_MMA(0, 1, At, B1); PG8_BAR; PG8_SCHED;
;             PG8_LDA(At, 0, 1); PG8_STAGE(PG8_SB(0, 0), b2, voffB); PG8_STAGE(PG8_SB(0, 1), b2 + hstep, voffB); PG8_STAGE(PG8_SA(0, 0), a2, voffA);
;             PG8_WAIT_V(8); PG8_WAIT_L(0); PG8_BAR; PG8_MMA(1, 0, At, B0); PG8_MMA(1, 1, At, B1); PG8_BAR; PG8_SCHED;
;             PG8_LDB(B0, 1, 0); PG8_LDB(B1, 1, 1); PG8_SCHED; PG8_LDA(At, 1, 0); PG8_STAGE(PG8_SA(0, 1), a2 + hstepA, voffA);
;             PG8_WAIT_V(8); PG8_WAIT_L(0); PG8_BAR; PG8_MMA(0, 0, At, B0); PG8_MMA(0, 1, At, B1); PG8_BAR; PG8_SCHED;
	s_setprio 1
	s_waitcnt lgkmcnt(0)
	v_mfma_f32_16x16x32_bf16 v[62:65], v[146:149], v[206:209], v[62:65]
	v_mfma_f32_16x16x32_bf16 v[58:61], v[158:161], v[206:209], v[58:61]
	v_mfma_f32_16x16x32_bf16 v[46:49], v[146:149], v[226:229], v[46:49]
	v_mfma_f32_16x16x32_bf16 v[42:45], v[158:161], v[226:229], v[42:45]
	v_mfma_f32_16x16x32_bf16 v[30:33], v[146:149], v[234:237], v[30:33]
	v_mfma_f32_16x16x32_bf16 v[26:29], v[158:161], v[234:237], v[26:29]
	v_mfma_f32_16x16x32_bf16 v[14:17], v[146:149], v[242:245], v[14:17]
	v_mfma_f32_16x16x32_bf16 v[10:13], v[158:161], v[242:245], v[10:13]
	v_mfma_f32_16x16x32_bf16 v[62:65], v[154:157], v[222:225], v[62:65]
	v_mfma_f32_16x16x32_bf16 v[58:61], v[186:189], v[222:225], v[58:61]
	v_mfma_f32_16x16x32_bf16 v[46:49], v[154:157], v[230:233], v[46:49]
	v_mfma_f32_16x16x32_bf16 v[42:45], v[186:189], v[230:233], v[42:45]
	v_mfma_f32_16x16x32_bf16 v[30:33], v[154:157], v[238:241], v[30:33]
	v_mfma_f32_16x16x32_bf16 v[26:29], v[186:189], v[238:241], v[26:29]
	v_mfma_f32_16x16x32_bf16 v[14:17], v[154:157], v[246:249], v[14:17]
	v_mfma_f32_16x16x32_bf16 v[10:13], v[186:189], v[246:249], v[10:13]
	v_mfma_f32_16x16x32_bf16 v[54:57], v[190:193], v[206:209], v[54:57]
	v_mfma_f32_16x16x32_bf16 v[50:53], v[198:201], v[206:209], v[50:53]
	v_mfma_f32_16x16x32_bf16 v[38:41], v[190:193], v[226:229], v[38:41]
	v_mfma_f32_16x16x32_bf16 v[34:37], v[198:201], v[226:229], v[34:37]
	v_mfma_f32_16x16x32_bf16 v[22:25], v[190:193], v[234:237], v[22:25]
	v_mfma_f32_16x16x32_bf16 v[18:21], v[198:201], v[234:237], v[18:21]
	v_mfma_f32_16x16x32_bf16 v[6:9], v[190:193], v[242:245], v[6:9]
	v_mfma_f32_16x16x32_bf16 v[2:5], v[198:201], v[242:245], v[2:5]
	v_mfma_f32_16x16x32_bf16 v[54:57], v[194:197], v[222:225], v[54:57]
	v_mfma_f32_16x16x32_bf16 v[50:53], v[202:205], v[222:225], v[50:53]
	v_mfma_f32_16x16x32_bf16 v[38:41], v[194:197], v[230:233], v[38:41]
	v_mfma_f32_16x16x32_bf16 v[34:37], v[202:205], v[230:233], v[34:37]
	v_mfma_f32_16x16x32_bf16 v[22:25], v[194:197], v[238:241], v[22:25]
	v_mfma_f32_16x16x32_bf16 v[18:21], v[202:205], v[238:241], v[18:21]
	v_mfma_f32_16x16x32_bf16 v[6:9], v[194:197], v[246:249], v[6:9]
	v_mfma_f32_16x16x32_bf16 v[2:5], v[202:205], v[246:249], v[2:5]
	s_setprio 0
	s_barrier
	s_add_i32 s12, 0, 0x18000
	v_add_u32_e32 v153, s12, v1
	s_add_i32 s13, 0, 0x1c000
	ds_read_b128 v[146:149], v153
	ds_read_b128 v[154:157], v153 offset:1024
	ds_read_b128 v[158:161], v153 offset:2048
	ds_read_b128 v[186:189], v153 offset:3072
	v_add_u32_e32 v153, s13, v1
	ds_read_b128 v[190:193], v153
	ds_read_b128 v[194:197], v153 offset:1024
	ds_read_b128 v[198:201], v153 offset:2048
	ds_read_b128 v[202:205], v153 offset:3072
	s_add_u32 s44, s86, 0x18000
	s_addc_u32 s45, s87, 0
	s_mov_b32 m0, s27
	v_lshl_add_u64 v[212:213], s[44:45], 0, v[136:137]
	ds_read_b128 v[206:209], v152 offset:32768
	ds_read_b128 v[222:225], v152 offset:33792
	ds_read_b128 v[226:229], v152 offset:34816
	ds_read_b128 v[230:233], v152 offset:35840
	ds_read_b128 v[234:237], v152 offset:36864
	ds_read_b128 v[238:241], v152 offset:37888
	ds_read_b128 v[242:245], v152 offset:38912
	ds_read_b128 v[246:249], v152 offset:39936
	global_load_lds_dwordx4 v[212:213], off
	v_lshl_add_u64 v[212:213], s[44:45], 0, v[132:133]
	s_mov_b32 m0, s28
	s_nop 0
	global_load_lds_dwordx4 v[212:213], off
	s_waitcnt vmcnt(8)
	s_waitcnt lgkmcnt(0)
	s_barrier
	s_setprio 1
	s_waitcnt lgkmcnt(0)
	v_mfma_f32_16x16x32_bf16 v[126:129], v[146:149], v[206:209], v[126:129]
	v_mfma_f32_16x16x32_bf16 v[122:125], v[158:161], v[206:209], v[122:125]
	v_mfma_f32_16x16x32_bf16 v[110:113], v[146:149], v[226:229], v[110:113]
	v_mfma_f32_16x16x32_bf16 v[106:109], v[158:161], v[226:229], v[106:109]
	v_mfma_f32_16x16x32_bf16 v[94:97], v[146:149], v[234:237], v[94:97]
	v_mfma_f32_16x16x32_bf16 v[90:93], v[158:161], v[234:237], v[90:93]
	v_mfma_f32_16x16x32_bf16 v[78:81], v[146:149], v[242:245], v[78:81]
	v_mfma_f32_16x16x32_bf16 v[74:77], v[158:161], v[242:245], v[74:77]
	v_mfma_f32_16x16x32_bf16 v[126:129], v[154:157], v[222:225], v[126:129]
	v_mfma_f32_16x16x32_bf16 v[122:125], v[186:189], v[222:225], v[122:125]
	v_mfma_f32_16x16x32_bf16 v[110:113], v[154:157], v[230:233], v[110:113]
	v_mfma_f32_16x16x32_bf16 v[106:109], v[186:189], v[230:233], v[106:109]
	v_mfma_f32_16x16x32_bf16 v[94:97], v[154:157], v[238:241], v[94:97]
	v_mfma_f32_16x16x32_bf16 v[90:93], v[186:189], v[238:241], v[90:93]
	v_mfma_f32_16x16x32_bf16 v[78:81], v[154:157], v[246:249], v[78:81]
	v_mfma_f32_16x16x32_bf16 v[74:77], v[186:189], v[246:249], v[74:77]
	v_mfma_f32_16x16x32_bf16 v[118:121], v[190:193], v[206:209], v[118:121]
	v_mfma_f32_16x16x32_bf16 v[114:117], v[198:201], v[206:209], v[114:117]
	v_mfma_f32_16x16x32_bf16 v[102:105], v[190:193], v[226:229], v[102:105]
	v_mfma_f32_16x16x32_bf16 v[98:101], v[198:201], v[226:229], v[98:101]
	v_mfma_f32_16x16x32_bf16 v[86:89], v[190:193], v[234:237], v[86:89]
	v_mfma_f32_16x16x32_bf16 v[82:85], v[198:201], v[234:237], v[82:85]
	v_mfma_f32_16x16x32_bf16 v[70:73], v[190:193], v[242:245], v[70:73]
	v_mfma_f32_16x16x32_bf16 v[66:69], v[198:201], v[242:245], v[66:69]
	v_mfma_f32_16x16x32_bf16 v[118:121], v[194:197], v[222:225], v[118:121]
	v_mfma_f32_16x16x32_bf16 v[114:117], v[202:205], v[222:225], v[114:117]
	v_mfma_f32_16x16x32_bf16 v[102:105], v[194:197], v[230:233], v[102:105]
	v_mfma_f32_16x16x32_bf16 v[98:101], v[202:205], v[230:233], v[98:101]
	v_mfma_f32_16x16x32_bf16 v[86:89], v[194:197], v[238:241], v[86:89]
	v_mfma_f32_16x16x32_bf16 v[82:85], v[202:205], v[238:241], v[82:85]
	v_mfma_f32_16x16x32_bf16 v[70:73], v[194:197], v[246:249], v[70:73]
	v_mfma_f32_16x16x32_bf16 v[66:69], v[202:205], v[246:249], v[66:69]
	s_setprio 0
	s_barrier
; #define PG8_STAGE(bufoff, gbase, voff) do { _Pragma("unroll") for (int _i = 0; _i < 2; ++_i) \
;         __builtin_amdgcn_global_load_lds((const unsigned*)((const char*)(gbase) + (voff)[_i]), (LAS unsigned*)(lds + (bufoff) + ldsw + _i * 8192), 16, 0, 0); } while (0)
; #define PG8_LDA(dst, b, h) do { _Pragma("unroll") for (int m = 0; m < 4; ++m) _Pragma("unroll") for (int k = 0; k < 2; ++k) dst[m][k] = *(const LAS bf16x8*)(lds + PG8_SA(b, h) + aoff + m * 2048 + k * 1024); } while (0)
; #define PG8_MMA(ai, bj, At, Bt) do { __builtin_amdgcn_s_setprio(1); _Pragma("unroll") for (int m = 0; m < 4; ++m) _Pragma("unroll") for (int n = 0; n < 2; ++n) _Pragma("unroll") for (int k = 0; k < 2; ++k) \
;         acc[ai][bj][m][n] = __builtin_amdgcn_mfma_f32_16x16x32_bf16(Bt[n][k], At[m][k], acc[ai][bj][m][n], 0, 0, 0); __builtin_amdgcn_s_setprio(0); } while (0)
; #define PG8_WAIT_V(n) asm volatile("s_waitcnt vmcnt(" #n ")" ::: "memory")
; #define PG8_WAIT_L(n) asm volatile("s_waitcnt lgkmcnt(" #n ")" ::: "memory")
; #define PG8_BAR __builtin_amdgcn_s_barrier()
; #define PG8_SCHED __builtin_amdgcn_sched_barrier(0)
; template <class Epi>
; __device__ __forceinline__ void gemm_phase(LAS unsigned char* lds, const Gemm g, const StaticOrder& S, const Epi& E) {
;     ...
;             PG8_WAIT_V(8); PG8_WAIT_L(0); PG8_BAR; PG8_MMA(0, 0, At, B0); PG8_MMA(0, 1, At, B1); PG8_BAR; PG8_SCHED;
;             PG8_LDA(At, 1, 1); PG8_STAGE(PG8_SB(1, 0), b3, voffB); PG8_STAGE(PG8_SB(1, 1), b3 + hstep, voffB); PG8_STAGE(PG8_SA(1, 0), a3, voffA);
;             PG8_WAIT_V(8); PG8_WAIT_L(0); PG8_BAR; PG8_MMA(1, 0, At, B0); PG8_MMA(1, 1, At, B1); PG8_BAR; PG8_SCHED;
;         }
;         if (wr == 0) PG8_BAR;
	s_add_i32 s12, s12, s24
	v_lshl_add_u64 v[150:151], v[150:151], 0, s[6:7]
	s_mov_b32 m0, s12
	ds_read_b128 v[206:209], v152 offset:49152
	ds_read_b128 v[222:225], v152 offset:50176
	ds_read_b128 v[226:229], v152 offset:51200
	ds_read_b128 v[230:233], v152 offset:52224
	ds_read_b128 v[234:237], v152 offset:53248
	ds_read_b128 v[238:241], v152 offset:54272
	ds_read_b128 v[242:245], v152 offset:55296
	ds_read_b128 v[246:249], v152 offset:56320
	global_load_lds_dwordx4 v[150:151], off
	s_add_i32 m0, s12, 0x2000
	s_add_u32 s44, vcc_lo, 0x18080
	v_lshl_add_u64 v[150:151], v[162:163], 0, s[6:7]
	s_addc_u32 s45, vcc_hi, 0
	s_add_i32 s12, s13, s24
	global_load_lds_dwordx4 v[150:151], off
	v_lshl_add_u64 v[150:151], s[44:45], 0, v[134:135]
	s_mov_b32 m0, s12
	s_nop 0
	global_load_lds_dwordx4 v[150:151], off
	v_lshl_add_u64 v[150:151], s[44:45], 0, v[130:131]
	s_add_i32 m0, s12, 0x2000
	s_nop 0
	global_load_lds_dwordx4 v[150:151], off
	v_lshl_add_u64 v[150:151], s[96:97], 0, v[136:137]
	s_mov_b32 m0, s29
	s_nop 0
	global_load_lds_dwordx4 v[150:151], off
	v_lshl_add_u64 v[150:151], s[96:97], 0, v[132:133]
	s_mov_b32 m0, s33
	s_nop 0
	global_load_lds_dwordx4 v[150:151], off
	s_waitcnt vmcnt(8)
	s_waitcnt lgkmcnt(0)
	s_barrier
	s_setprio 1
	s_waitcnt lgkmcnt(0)
	v_mfma_f32_16x16x32_bf16 v[62:65], v[146:149], v[206:209], v[62:65]
	v_mfma_f32_16x16x32_bf16 v[58:61], v[158:161], v[206:209], v[58:61]
	v_mfma_f32_16x16x32_bf16 v[46:49], v[146:149], v[226:229], v[46:49]
	v_mfma_f32_16x16x32_bf16 v[42:45], v[158:161], v[226:229], v[42:45]
	v_mfma_f32_16x16x32_bf16 v[30:33], v[146:149], v[234:237], v[30:33]
	v_mfma_f32_16x16x32_bf16 v[26:29], v[158:161], v[234:237], v[26:29]
	v_mfma_f32_16x16x32_bf16 v[14:17], v[146:149], v[242:245], v[14:17]
	v_mfma_f32_16x16x32_bf16 v[10:13], v[158:161], v[242:245], v[10:13]
	v_mfma_f32_16x16x32_bf16 v[62:65], v[154:157], v[222:225], v[62:65]
	v_mfma_f32_16x16x32_bf16 v[58:61], v[186:189], v[222:225], v[58:61]
	v_mfma_f32_16x16x32_bf16 v[46:49], v[154:157], v[230:233], v[46:49]
	v_mfma_f32_16x16x32_bf16 v[42:45], v[186:189], v[230:233], v[42:45]
	v_mfma_f32_16x16x32_bf16 v[30:33], v[154:157], v[238:241], v[30:33]
	v_mfma_f32_16x16x32_bf16 v[26:29], v[186:189], v[238:241], v[26:29]
	v_mfma_f32_16x16x32_bf16 v[14:17], v[154:157], v[246:249], v[14:17]
	v_mfma_f32_16x16x32_bf16 v[10:13], v[186:189], v[246:249], v[10:13]
	v_mfma_f32_16x16x32_bf16 v[54:57], v[190:193], v[206:209], v[54:57]
	v_mfma_f32_16x16x32_bf16 v[50:53], v[198:201], v[206:209], v[50:53]
	v_mfma_f32_16x16x32_bf16 v[38:41], v[190:193], v[226:229], v[38:41]
	v_mfma_f32_16x16x32_bf16 v[34:37], v[198:201], v[226:229], v[34:37]
	v_mfma_f32_16x16x32_bf16 v[22:25], v[190:193], v[234:237], v[22:25]
	v_mfma_f32_16x16x32_bf16 v[18:21], v[198:201], v[234:237], v[18:21]
	v_mfma_f32_16x16x32_bf16 v[6:9], v[190:193], v[242:245], v[6:9]
	v_mfma_f32_16x16x32_bf16 v[2:5], v[198:201], v[242:245], v[2:5]
	v_mfma_f32_16x16x32_bf16 v[54:57], v[194:197], v[222:225], v[54:57]
	v_mfma_f32_16x16x32_bf16 v[50:53], v[202:205], v[222:225], v[50:53]
	v_mfma_f32_16x16x32_bf16 v[38:41], v[194:197], v[230:233], v[38:41]
	v_mfma_f32_16x16x32_bf16 v[34:37], v[202:205], v[230:233], v[34:37]
	v_mfma_f32_16x16x32_bf16 v[22:25], v[194:197], v[238:241], v[22:25]
	v_mfma_f32_16x16x32_bf16 v[18:21], v[202:205], v[238:241], v[18:21]
	v_mfma_f32_16x16x32_bf16 v[6:9], v[194:197], v[246:249], v[6:9]
	v_mfma_f32_16x16x32_bf16 v[2:5], v[202:205], v[246:249], v[2:5]
	s_setprio 0
	s_barrier
	s_add_i32 s94, s94, 2
	s_add_u32 s40, s40, 0x100
	s_addc_u32 s41, s41, 0
	s_cmp_gt_u32 s94, 3
	s_cbranch_scc0 .LBB0_494
	s_and_b64 vcc, exec, s[50:51]
	s_cbranch_vccz .LBB0_497
	s_barrier

; #define PG8_STAGE(bufoff, gbase, voff) do { _Pragma("unroll") for (int _i = 0; _i < 2; ++_i) \
;         __builtin_amdgcn_global_load_lds((const unsigned*)((const char*)(gbase) + (voff)[_i]), (LAS unsigned*)(lds + (bufoff) + ldsw + _i * 8192), 16, 0, 0); } while (0)
; #define PG8_LDA(dst, b, h) do { _Pragma("unroll") for (int m = 0; m < 4; ++m) _Pragma("unroll") for (int k = 0; k < 2; ++k) dst[m][k] = *(const LAS bf16x8*)(lds + PG8_SA(b, h) + aoff + m * 2048 + k * 1024); } while (0)
; #define PG8_LDB(dst, b, h) do { _Pragma("unroll") for (int n = 0; n < 2; ++n) _Pragma("unroll") for (int k = 0; k < 2; ++k) dst[n][k] = *(const LAS bf16x8*)(lds + PG8_SB(b, h) + boff + n * 2048 + k * 1024); } while (0)
; #define PG8_MMA(ai, bj, At, Bt) do { __builtin_amdgcn_s_setprio(1); _Pragma("unroll") for (int m = 0; m < 4; ++m) _Pragma("unroll") for (int n = 0; n < 2; ++n) _Pragma("unroll") for (int k = 0; k < 2; ++k) \
;         acc[ai][bj][m][n] = __builtin_amdgcn_mfma_f32_16x16x32_bf16(Bt[n][k], At[m][k], acc[ai][bj][m][n], 0, 0, 0); __builtin_amdgcn_s_setprio(0); } while (0)
; #define PG8_WAIT_V(n) asm volatile("s_waitcnt vmcnt(" #n ")" ::: "memory")
; #define PG8_WAIT_L(n) asm volatile("s_waitcnt lgkmcnt(" #n ")" ::: "memory")
; template <class Epi>
; __device__ __forceinline__ void gemm_phase(LAS unsigned char* lds, const Gemm g, const StaticOrder& S, const Epi& E) {
;     ...
;         for (int t = 0; t < nt; t += 2) {
;             if constexpr (Epi::GATED) { if (t == 8 || t == 16) E.rescale(acc, cur, t == 8 ? 0 : 1, wr, wc, fr, fq); }
;             const bool last = (t == nt - 2);
;             const char* a1 = PG8_AP(cA, t + 1);
;             const char* a2 = last ? nA : PG8_AP(cA, t + 2); const char* b2 = last ? nB : cB + (size_t)(t + 2) * kstep;
;             const char* a3 = last ? nA + kstep : PG8_AP(cA, t + 3); const char* b3 = b2 + kstep;
;             PG8_LDB(B0, 0, 0); PG8_LDB(B1, 0, 1); PG8_SCHED; PG8_LDA(At, 0, 0); PG8_STAGE(PG8_SA(1, 1), a1 + hstepA, voffA);
;             PG8_WAIT_V(8); PG8_WAIT_L(0); PG8_BAR; PG8_MMA(0, 0, At, B0); PG8_MMA(0, 1, At, B1); PG8_BAR; PG8_SCHED;
;             PG8_LDA(At, 0, 1); PG8_STAGE(PG8_SB(0, 0), b2, voffB); PG8_STAGE(PG8_SB(0, 1), b2 + hstep, voffB); PG8_STAGE(PG8_SA(0, 0), a2, voffA);
;             PG8_WAIT_V(8); PG8_WAIT_L(0); PG8_BAR; PG8_MMA(1, 0, At, B0); PG8_MMA(1, 1, At, B1); PG8_BAR; PG8_SCHED;
.LBB0_644:
	s_add_u32 s12, s40, s54
	s_addc_u32 s13, s41, s55
	s_add_u32 s44, s12, 0x100
	s_addc_u32 s45, s13, 0
	s_add_u32 s86, s93, s54
	s_addc_u32 s87, s94, s55
	s_add_u32 s12, s12, 0x180
	s_addc_u32 s13, s13, 0
	s_add_i32 s90, 0, 0x10000
	s_add_i32 s91, 0, 0x14000
	v_add_u32_e32 v147, s90, v1
	ds_read_b128 v[148:151], v147
	ds_read_b128 v[152:155], v147 offset:1024
	ds_read_b128 v[156:159], v147 offset:2048
	ds_read_b128 v[160:163], v147 offset:3072
	v_add_u32_e32 v147, s91, v1
	ds_read_b128 v[186:189], v147
	ds_read_b128 v[190:193], v147 offset:1024
	ds_read_b128 v[194:197], v147 offset:2048
	ds_read_b128 v[198:201], v147 offset:3072
	s_cmpk_eq_i32 s54, 0xf00
	s_cselect_b32 s57, s92, s13
	s_cselect_b32 s56, s85, s12
	s_cselect_b32 s97, s43, s87
	s_cselect_b32 s96, s81, s86
	s_cselect_b32 s87, s47, s45
	s_cselect_b32 s86, s80, s44
	v_lshl_add_u64 v[212:213], v[142:143], 0, s[54:55]
	s_add_i32 m0, s25, 0xc000
	ds_read_b128 v[202:205], v146
	ds_read_b128 v[206:209], v146 offset:1024
	ds_read_b128 v[222:225], v146 offset:2048
	ds_read_b128 v[226:229], v146 offset:3072
	ds_read_b128 v[230:233], v146 offset:4096
	ds_read_b128 v[234:237], v146 offset:5120
	ds_read_b128 v[238:241], v146 offset:6144
	ds_read_b128 v[242:245], v146 offset:7168
	global_load_lds_dwordx4 v[212:213], off
	v_lshl_add_u64 v[212:213], v[144:145], 0, s[54:55]
	s_add_i32 m0, s25, 0xe000
	s_nop 0
	global_load_lds_dwordx4 v[212:213], off
	s_waitcnt vmcnt(8)
	s_waitcnt lgkmcnt(0)
	s_barrier
	s_setprio 1
	s_waitcnt lgkmcnt(0)
	v_mfma_f32_16x16x32_bf16 v[126:129], v[148:151], v[202:205], v[126:129]
	v_mfma_f32_16x16x32_bf16 v[122:125], v[156:159], v[202:205], v[122:125]
	v_mfma_f32_16x16x32_bf16 v[110:113], v[148:151], v[222:225], v[110:113]
	v_mfma_f32_16x16x32_bf16 v[106:109], v[156:159], v[222:225], v[106:109]
	v_mfma_f32_16x16x32_bf16 v[94:97], v[148:151], v[230:233], v[94:97]
	v_mfma_f32_16x16x32_bf16 v[90:93], v[156:159], v[230:233], v[90:93]
	v_mfma_f32_16x16x32_bf16 v[78:81], v[148:151], v[238:241], v[78:81]
	v_mfma_f32_16x16x32_bf16 v[74:77], v[156:159], v[238:241], v[74:77]
	v_mfma_f32_16x16x32_bf16 v[126:129], v[152:155], v[206:209], v[126:129]
	v_mfma_f32_16x16x32_bf16 v[122:125], v[160:163], v[206:209], v[122:125]
	v_mfma_f32_16x16x32_bf16 v[110:113], v[152:155], v[226:229], v[110:113]
	v_mfma_f32_16x16x32_bf16 v[106:109], v[160:163], v[226:229], v[106:109]
	v_mfma_f32_16x16x32_bf16 v[94:97], v[152:155], v[234:237], v[94:97]
	v_mfma_f32_16x16x32_bf16 v[90:93], v[160:163], v[234:237], v[90:93]
	v_mfma_f32_16x16x32_bf16 v[78:81], v[152:155], v[242:245], v[78:81]
	v_mfma_f32_16x16x32_bf16 v[74:77], v[160:163], v[242:245], v[74:77]
	v_mfma_f32_16x16x32_bf16 v[118:121], v[186:189], v[202:205], v[118:121]
	v_mfma_f32_16x16x32_bf16 v[114:117], v[194:197], v[202:205], v[114:117]
	v_mfma_f32_16x16x32_bf16 v[102:105], v[186:189], v[222:225], v[102:105]
	v_mfma_f32_16x16x32_bf16 v[98:101], v[194:197], v[222:225], v[98:101]
	v_mfma_f32_16x16x32_bf16 v[86:89], v[186:189], v[230:233], v[86:89]
	v_mfma_f32_16x16x32_bf16 v[82:85], v[194:197], v[230:233], v[82:85]
	v_mfma_f32_16x16x32_bf16 v[70:73], v[186:189], v[238:241], v[70:73]
	v_mfma_f32_16x16x32_bf16 v[66:69], v[194:197], v[238:241], v[66:69]
	v_mfma_f32_16x16x32_bf16 v[118:121], v[190:193], v[206:209], v[118:121]
	v_mfma_f32_16x16x32_bf16 v[114:117], v[198:201], v[206:209], v[114:117]
	v_mfma_f32_16x16x32_bf16 v[102:105], v[190:193], v[226:229], v[102:105]
	v_mfma_f32_16x16x32_bf16 v[98:101], v[198:201], v[226:229], v[98:101]
	v_mfma_f32_16x16x32_bf16 v[86:89], v[190:193], v[234:237], v[86:89]
	v_mfma_f32_16x16x32_bf16 v[82:85], v[198:201], v[234:237], v[82:85]
	v_mfma_f32_16x16x32_bf16 v[70:73], v[190:193], v[242:245], v[70:73]
	v_mfma_f32_16x16x32_bf16 v[66:69], v[198:201], v[242:245], v[66:69]
	s_setprio 0
	s_barrier
	s_add_i32 s12, s90, s24
	v_lshl_add_u64 v[212:213], s[96:97], 0, v[134:135]
	s_mov_b32 m0, s12
	ds_read_b128 v[202:205], v146 offset:16384
	ds_read_b128 v[206:209], v146 offset:17408
	ds_read_b128 v[222:225], v146 offset:18432
	ds_read_b128 v[226:229], v146 offset:19456
	ds_read_b128 v[230:233], v146 offset:20480
	ds_read_b128 v[234:237], v146 offset:21504
	ds_read_b128 v[238:241], v146 offset:22528
	ds_read_b128 v[242:245], v146 offset:23552
	global_load_lds_dwordx4 v[212:213], off
	s_add_i32 m0, s12, 0x2000
	s_add_u32 s44, s96, 0x80000
	v_lshl_add_u64 v[246:247], s[96:97], 0, v[130:131]
	s_addc_u32 s45, s97, 0
	s_add_i32 s12, s91, s24
	global_load_lds_dwordx4 v[246:247], off
	v_lshl_add_u64 v[248:249], s[44:45], 0, v[134:135]
	s_mov_b32 m0, s12
	s_nop 0
	global_load_lds_dwordx4 v[248:249], off
	v_lshl_add_u64 v[248:249], s[44:45], 0, v[130:131]
	s_add_i32 m0, s12, 0x2000
	s_nop 0
	global_load_lds_dwordx4 v[248:249], off
	v_lshl_add_u64 v[248:249], s[86:87], 0, v[136:137]
	s_mov_b32 m0, s25
	s_nop 0
	global_load_lds_dwordx4 v[248:249], off
	v_lshl_add_u64 v[248:249], s[86:87], 0, v[132:133]
	s_mov_b32 m0, s26
	s_nop 0
	global_load_lds_dwordx4 v[248:249], off
	s_waitcnt vmcnt(8)
	s_waitcnt lgkmcnt(0)
	s_barrier
; #define PG8_STAGE(bufoff, gbase, voff) do { _Pragma("unroll") for (int _i = 0; _i < 2; ++_i) \
;         __builtin_amdgcn_global_load_lds((const unsigned*)((const char*)(gbase) + (voff)[_i]), (LAS unsigned*)(lds + (bufoff) + ldsw + _i * 8192), 16, 0, 0); } while (0)
; #define PG8_LDA(dst, b, h) do { _Pragma("unroll") for (int m = 0; m < 4; ++m) _Pragma("unroll") for (int k = 0; k < 2; ++k) dst[m][k] = *(const LAS bf16x8*)(lds + PG8_SA(b, h) + aoff + m * 2048 + k * 1024); } while (0)
; #define PG8_LDB(dst, b, h) do { _Pragma("unroll") for (int n = 0; n < 2; ++n) _Pragma("unroll") for (int k = 0; k < 2; ++k) dst[n][k] = *(const LAS bf16x8*)(lds + PG8_SB(b, h) + boff + n * 2048 + k * 1024); } while (0)
; #define PG8_MMA(ai, bj, At, Bt) do { __builtin_amdgcn_s_setprio(1); _Pragma("unroll") for (int m = 0; m < 4; ++m) _Pragma("unroll") for (int n = 0; n < 2; ++n) _Pragma("unroll") for (int k = 0; k < 2; ++k) \
;         acc[ai][bj][m][n] = __builtin_amdgcn_mfma_f32_16x16x32_bf16(Bt[n][k], At[m][k], acc[ai][bj][m][n], 0, 0, 0); __builtin_amdgcn_s_setprio(0); } while (0)
; #define PG8_WAIT_V(n) asm volatile("s_waitcnt vmcnt(" #n ")" ::: "memory")
; #define PG8_WAIT_L(n) asm volatile("s_waitcnt lgkmcnt(" #n ")" ::: "memory")
; #define PG8_BAR __builtin_amdgcn_s_barrier()
; #define PG8_SCHED __builtin_amdgcn_sched_barrier(0)
; template <class Epi>
; __device__ __forceinline__ void gemm_phase(LAS unsigned char* lds, const Gemm g, const StaticOrder& S, const Epi& E) {
;     ...
;             PG8_WAIT_V(8); PG8_WAIT_L(0); PG8_BAR; PG8_MMA(1, 0, At, B0); PG8_MMA(1, 1, At, B1); PG8_BAR; PG8_SCHED;
;             PG8_LDB(B0, 1, 0); PG8_LDB(B1, 1, 1); PG8_SCHED; PG8_LDA(At, 1, 0); PG8_STAGE(PG8_SA(0, 1), a2 + hstepA, voffA);
;             PG8_WAIT_V(8); PG8_WAIT_L(0); PG8_BAR; PG8_MMA(0, 0, At, B0); PG8_MMA(0, 1, At, B1); PG8_BAR; PG8_SCHED;
	s_setprio 1
	s_waitcnt lgkmcnt(0)
	v_mfma_f32_16x16x32_bf16 v[62:65], v[148:151], v[202:205], v[62:65]
	v_mfma_f32_16x16x32_bf16 v[58:61], v[156:159], v[202:205], v[58:61]
	v_mfma_f32_16x16x32_bf16 v[46:49], v[148:151], v[222:225], v[46:49]
	v_mfma_f32_16x16x32_bf16 v[42:45], v[156:159], v[222:225], v[42:45]
	v_mfma_f32_16x16x32_bf16 v[30:33], v[148:151], v[230:233], v[30:33]
	v_mfma_f32_16x16x32_bf16 v[26:29], v[156:159], v[230:233], v[26:29]
	v_mfma_f32_16x16x32_bf16 v[14:17], v[148:151], v[238:241], v[14:17]
	v_mfma_f32_16x16x32_bf16 v[10:13], v[156:159], v[238:241], v[10:13]
	v_mfma_f32_16x16x32_bf16 v[62:65], v[152:155], v[206:209], v[62:65]
	v_mfma_f32_16x16x32_bf16 v[58:61], v[160:163], v[206:209], v[58:61]
	v_mfma_f32_16x16x32_bf16 v[46:49], v[152:155], v[226:229], v[46:49]
	v_mfma_f32_16x16x32_bf16 v[42:45], v[160:163], v[226:229], v[42:45]
	v_mfma_f32_16x16x32_bf16 v[30:33], v[152:155], v[234:237], v[30:33]
	v_mfma_f32_16x16x32_bf16 v[26:29], v[160:163], v[234:237], v[26:29]
	v_mfma_f32_16x16x32_bf16 v[14:17], v[152:155], v[242:245], v[14:17]
	v_mfma_f32_16x16x32_bf16 v[10:13], v[160:163], v[242:245], v[10:13]
	v_mfma_f32_16x16x32_bf16 v[54:57], v[186:189], v[202:205], v[54:57]
	v_mfma_f32_16x16x32_bf16 v[50:53], v[194:197], v[202:205], v[50:53]
	v_mfma_f32_16x16x32_bf16 v[38:41], v[186:189], v[222:225], v[38:41]
	v_mfma_f32_16x16x32_bf16 v[34:37], v[194:197], v[222:225], v[34:37]
	v_mfma_f32_16x16x32_bf16 v[22:25], v[186:189], v[230:233], v[22:25]
	v_mfma_f32_16x16x32_bf16 v[18:21], v[194:197], v[230:233], v[18:21]
	v_mfma_f32_16x16x32_bf16 v[6:9], v[186:189], v[238:241], v[6:9]
	v_mfma_f32_16x16x32_bf16 v[2:5], v[194:197], v[238:241], v[2:5]
	v_mfma_f32_16x16x32_bf16 v[54:57], v[190:193], v[206:209], v[54:57]
	v_mfma_f32_16x16x32_bf16 v[50:53], v[198:201], v[206:209], v[50:53]
	v_mfma_f32_16x16x32_bf16 v[38:41], v[190:193], v[226:229], v[38:41]
	v_mfma_f32_16x16x32_bf16 v[34:37], v[198:201], v[226:229], v[34:37]
	v_mfma_f32_16x16x32_bf16 v[22:25], v[190:193], v[234:237], v[22:25]
	v_mfma_f32_16x16x32_bf16 v[18:21], v[198:201], v[234:237], v[18:21]
	v_mfma_f32_16x16x32_bf16 v[6:9], v[190:193], v[242:245], v[6:9]
	v_mfma_f32_16x16x32_bf16 v[2:5], v[198:201], v[242:245], v[2:5]
	s_setprio 0
	s_barrier
	s_add_i32 s12, 0, 0x18000
	v_add_u32_e32 v147, s12, v1
	s_add_i32 s13, 0, 0x1c000
	ds_read_b128 v[148:151], v147
	ds_read_b128 v[152:155], v147 offset:1024
	ds_read_b128 v[156:159], v147 offset:2048
	ds_read_b128 v[160:163], v147 offset:3072
	v_add_u32_e32 v147, s13, v1
	ds_read_b128 v[186:189], v147
	ds_read_b128 v[190:193], v147 offset:1024
	ds_read_b128 v[194:197], v147 offset:2048
	ds_read_b128 v[198:201], v147 offset:3072
	s_add_u32 s44, s86, 0x80000
	s_addc_u32 s45, s87, 0
	s_mov_b32 m0, s27
	v_lshl_add_u64 v[248:249], s[44:45], 0, v[136:137]
	ds_read_b128 v[202:205], v146 offset:32768
	ds_read_b128 v[206:209], v146 offset:33792
	ds_read_b128 v[222:225], v146 offset:34816
	ds_read_b128 v[226:229], v146 offset:35840
	ds_read_b128 v[230:233], v146 offset:36864
	ds_read_b128 v[234:237], v146 offset:37888
	ds_read_b128 v[238:241], v146 offset:38912
	ds_read_b128 v[242:245], v146 offset:39936
	global_load_lds_dwordx4 v[248:249], off
	v_lshl_add_u64 v[248:249], s[44:45], 0, v[132:133]
	s_mov_b32 m0, s28
	s_nop 0
	global_load_lds_dwordx4 v[248:249], off
	s_waitcnt vmcnt(8)
	s_waitcnt lgkmcnt(0)
	s_barrier
	s_setprio 1
	s_waitcnt lgkmcnt(0)
	v_mfma_f32_16x16x32_bf16 v[126:129], v[148:151], v[202:205], v[126:129]
	v_mfma_f32_16x16x32_bf16 v[122:125], v[156:159], v[202:205], v[122:125]
	v_mfma_f32_16x16x32_bf16 v[110:113], v[148:151], v[222:225], v[110:113]
	v_mfma_f32_16x16x32_bf16 v[106:109], v[156:159], v[222:225], v[106:109]
	v_mfma_f32_16x16x32_bf16 v[94:97], v[148:151], v[230:233], v[94:97]
	v_mfma_f32_16x16x32_bf16 v[90:93], v[156:159], v[230:233], v[90:93]
	v_mfma_f32_16x16x32_bf16 v[78:81], v[148:151], v[238:241], v[78:81]
	v_mfma_f32_16x16x32_bf16 v[74:77], v[156:159], v[238:241], v[74:77]
	v_mfma_f32_16x16x32_bf16 v[126:129], v[152:155], v[206:209], v[126:129]
	v_mfma_f32_16x16x32_bf16 v[122:125], v[160:163], v[206:209], v[122:125]
	v_mfma_f32_16x16x32_bf16 v[110:113], v[152:155], v[226:229], v[110:113]
	v_mfma_f32_16x16x32_bf16 v[106:109], v[160:163], v[226:229], v[106:109]
	v_mfma_f32_16x16x32_bf16 v[94:97], v[152:155], v[234:237], v[94:97]
	v_mfma_f32_16x16x32_bf16 v[90:93], v[160:163], v[234:237], v[90:93]
	v_mfma_f32_16x16x32_bf16 v[78:81], v[152:155], v[242:245], v[78:81]
	v_mfma_f32_16x16x32_bf16 v[74:77], v[160:163], v[242:245], v[74:77]
	v_mfma_f32_16x16x32_bf16 v[118:121], v[186:189], v[202:205], v[118:121]
	v_mfma_f32_16x16x32_bf16 v[114:117], v[194:197], v[202:205], v[114:117]
	v_mfma_f32_16x16x32_bf16 v[102:105], v[186:189], v[222:225], v[102:105]
	v_mfma_f32_16x16x32_bf16 v[98:101], v[194:197], v[222:225], v[98:101]
	v_mfma_f32_16x16x32_bf16 v[86:89], v[186:189], v[230:233], v[86:89]
	v_mfma_f32_16x16x32_bf16 v[82:85], v[194:197], v[230:233], v[82:85]
	v_mfma_f32_16x16x32_bf16 v[70:73], v[186:189], v[238:241], v[70:73]
	v_mfma_f32_16x16x32_bf16 v[66:69], v[194:197], v[238:241], v[66:69]
	v_mfma_f32_16x16x32_bf16 v[118:121], v[190:193], v[206:209], v[118:121]
	v_mfma_f32_16x16x32_bf16 v[114:117], v[198:201], v[206:209], v[114:117]
	v_mfma_f32_16x16x32_bf16 v[102:105], v[190:193], v[226:229], v[102:105]
	v_mfma_f32_16x16x32_bf16 v[98:101], v[198:201], v[226:229], v[98:101]
	v_mfma_f32_16x16x32_bf16 v[86:89], v[190:193], v[234:237], v[86:89]
	v_mfma_f32_16x16x32_bf16 v[82:85], v[198:201], v[234:237], v[82:85]
	v_mfma_f32_16x16x32_bf16 v[70:73], v[190:193], v[242:245], v[70:73]
	v_mfma_f32_16x16x32_bf16 v[66:69], v[198:201], v[242:245], v[66:69]
	s_setprio 0
	s_barrier
; #define PG8_STAGE(bufoff, gbase, voff) do { _Pragma("unroll") for (int _i = 0; _i < 2; ++_i) \
;         __builtin_amdgcn_global_load_lds((const unsigned*)((const char*)(gbase) + (voff)[_i]), (LAS unsigned*)(lds + (bufoff) + ldsw + _i * 8192), 16, 0, 0); } while (0)
; #define PG8_LDA(dst, b, h) do { _Pragma("unroll") for (int m = 0; m < 4; ++m) _Pragma("unroll") for (int k = 0; k < 2; ++k) dst[m][k] = *(const LAS bf16x8*)(lds + PG8_SA(b, h) + aoff + m * 2048 + k * 1024); } while (0)
; #define PG8_MMA(ai, bj, At, Bt) do { __builtin_amdgcn_s_setprio(1); _Pragma("unroll") for (int m = 0; m < 4; ++m) _Pragma("unroll") for (int n = 0; n < 2; ++n) _Pragma("unroll") for (int k = 0; k < 2; ++k) \
;         acc[ai][bj][m][n] = __builtin_amdgcn_mfma_f32_16x16x32_bf16(Bt[n][k], At[m][k], acc[ai][bj][m][n], 0, 0, 0); __builtin_amdgcn_s_setprio(0); } while (0)
; #define PG8_WAIT_V(n) asm volatile("s_waitcnt vmcnt(" #n ")" ::: "memory")
; #define PG8_WAIT_L(n) asm volatile("s_waitcnt lgkmcnt(" #n ")" ::: "memory")
; #define PG8_BAR __builtin_amdgcn_s_barrier()
; #define PG8_SCHED __builtin_amdgcn_sched_barrier(0)
; template <class Epi>
; __device__ __forceinline__ void gemm_phase(LAS unsigned char* lds, const Gemm g, const StaticOrder& S, const Epi& E) {
;     ...
;             PG8_LDA(At, 1, 1); PG8_STAGE(PG8_SB(1, 0), b3, voffB); PG8_STAGE(PG8_SB(1, 1), b3 + hstep, voffB); PG8_STAGE(PG8_SA(1, 0), a3, voffA);
;             PG8_WAIT_V(8); PG8_WAIT_L(0); PG8_BAR; PG8_MMA(1, 0, At, B0); PG8_MMA(1, 1, At, B1); PG8_BAR; PG8_SCHED;
;         }
;         if (wr == 0) PG8_BAR;
	s_add_i32 s12, s12, s24
	v_lshl_add_u64 v[212:213], v[212:213], 0, s[6:7]
	s_mov_b32 m0, s12
	ds_read_b128 v[202:205], v146 offset:49152
	ds_read_b128 v[206:209], v146 offset:50176
	ds_read_b128 v[222:225], v146 offset:51200
	ds_read_b128 v[226:229], v146 offset:52224
	ds_read_b128 v[230:233], v146 offset:53248
	ds_read_b128 v[234:237], v146 offset:54272
	ds_read_b128 v[238:241], v146 offset:55296
	ds_read_b128 v[242:245], v146 offset:56320
	global_load_lds_dwordx4 v[212:213], off
	s_add_i32 m0, s12, 0x2000
	s_add_u32 s44, s96, 0x80080
	v_lshl_add_u64 v[212:213], v[246:247], 0, s[6:7]
	s_addc_u32 s45, s97, 0
	s_add_i32 s12, s13, s24
	global_load_lds_dwordx4 v[212:213], off
	v_lshl_add_u64 v[212:213], s[44:45], 0, v[134:135]
	s_mov_b32 m0, s12
	s_nop 0
	global_load_lds_dwordx4 v[212:213], off
	v_lshl_add_u64 v[212:213], s[44:45], 0, v[130:131]
	s_add_i32 m0, s12, 0x2000
	s_nop 0
	global_load_lds_dwordx4 v[212:213], off
	v_lshl_add_u64 v[212:213], s[56:57], 0, v[136:137]
	s_mov_b32 m0, s29
	s_nop 0
	global_load_lds_dwordx4 v[212:213], off
	v_lshl_add_u64 v[212:213], s[56:57], 0, v[132:133]
	s_mov_b32 m0, s33
	s_nop 0
	global_load_lds_dwordx4 v[212:213], off
	s_waitcnt vmcnt(8)
	s_waitcnt lgkmcnt(0)
	s_barrier
	s_setprio 1
	s_waitcnt lgkmcnt(0)
	v_mfma_f32_16x16x32_bf16 v[62:65], v[148:151], v[202:205], v[62:65]
	v_mfma_f32_16x16x32_bf16 v[58:61], v[156:159], v[202:205], v[58:61]
	v_mfma_f32_16x16x32_bf16 v[46:49], v[148:151], v[222:225], v[46:49]
	v_mfma_f32_16x16x32_bf16 v[42:45], v[156:159], v[222:225], v[42:45]
	v_mfma_f32_16x16x32_bf16 v[30:33], v[148:151], v[230:233], v[30:33]
	v_mfma_f32_16x16x32_bf16 v[26:29], v[156:159], v[230:233], v[26:29]
	v_mfma_f32_16x16x32_bf16 v[14:17], v[148:151], v[238:241], v[14:17]
	v_mfma_f32_16x16x32_bf16 v[10:13], v[156:159], v[238:241], v[10:13]
	v_mfma_f32_16x16x32_bf16 v[62:65], v[152:155], v[206:209], v[62:65]
	v_mfma_f32_16x16x32_bf16 v[58:61], v[160:163], v[206:209], v[58:61]
	v_mfma_f32_16x16x32_bf16 v[46:49], v[152:155], v[226:229], v[46:49]
	v_mfma_f32_16x16x32_bf16 v[42:45], v[160:163], v[226:229], v[42:45]
	v_mfma_f32_16x16x32_bf16 v[30:33], v[152:155], v[234:237], v[30:33]
	v_mfma_f32_16x16x32_bf16 v[26:29], v[160:163], v[234:237], v[26:29]
	v_mfma_f32_16x16x32_bf16 v[14:17], v[152:155], v[242:245], v[14:17]
	v_mfma_f32_16x16x32_bf16 v[10:13], v[160:163], v[242:245], v[10:13]
	v_mfma_f32_16x16x32_bf16 v[54:57], v[186:189], v[202:205], v[54:57]
	v_mfma_f32_16x16x32_bf16 v[50:53], v[194:197], v[202:205], v[50:53]
	v_mfma_f32_16x16x32_bf16 v[38:41], v[186:189], v[222:225], v[38:41]
	v_mfma_f32_16x16x32_bf16 v[34:37], v[194:197], v[222:225], v[34:37]
	v_mfma_f32_16x16x32_bf16 v[22:25], v[186:189], v[230:233], v[22:25]
	v_mfma_f32_16x16x32_bf16 v[18:21], v[194:197], v[230:233], v[18:21]
	v_mfma_f32_16x16x32_bf16 v[6:9], v[186:189], v[238:241], v[6:9]
	v_mfma_f32_16x16x32_bf16 v[2:5], v[194:197], v[238:241], v[2:5]
	v_mfma_f32_16x16x32_bf16 v[54:57], v[190:193], v[206:209], v[54:57]
	v_mfma_f32_16x16x32_bf16 v[50:53], v[198:201], v[206:209], v[50:53]
	v_mfma_f32_16x16x32_bf16 v[38:41], v[190:193], v[226:229], v[38:41]
	v_mfma_f32_16x16x32_bf16 v[34:37], v[198:201], v[226:229], v[34:37]
	v_mfma_f32_16x16x32_bf16 v[22:25], v[190:193], v[234:237], v[22:25]
	v_mfma_f32_16x16x32_bf16 v[18:21], v[198:201], v[234:237], v[18:21]
	v_mfma_f32_16x16x32_bf16 v[6:9], v[190:193], v[242:245], v[6:9]
	v_mfma_f32_16x16x32_bf16 v[2:5], v[198:201], v[242:245], v[2:5]
	s_setprio 0
	s_barrier
	s_add_i32 vcc_lo, vcc_lo, 2
	s_add_u32 s54, s54, 0x100
	s_addc_u32 s55, s55, 0
	s_cmp_gt_u32 vcc_lo, 29
	s_cbranch_scc0 .LBB0_644
	s_and_b64 vcc, exec, s[36:37]
	s_cbranch_vccz .LBB0_647
	s_barrier

; #define PG8_STAGE(bufoff, gbase, voff) do { _Pragma("unroll") for (int _i = 0; _i < 2; ++_i) \
;         __builtin_amdgcn_global_load_lds((const unsigned*)((const char*)(gbase) + (voff)[_i]), (LAS unsigned*)(lds + (bufoff) + ldsw + _i * 8192), 16, 0, 0); } while (0)
; #define PG8_LDA(dst, b, h) do { _Pragma("unroll") for (int m = 0; m < 4; ++m) _Pragma("unroll") for (int k = 0; k < 2; ++k) dst[m][k] = *(const LAS bf16x8*)(lds + PG8_SA(b, h) + aoff + m * 2048 + k * 1024); } while (0)
; #define PG8_LDB(dst, b, h) do { _Pragma("unroll") for (int n = 0; n < 2; ++n) _Pragma("unroll") for (int k = 0; k < 2; ++k) dst[n][k] = *(const LAS bf16x8*)(lds + PG8_SB(b, h) + boff + n * 2048 + k * 1024); } while (0)
; #define PG8_MMA(ai, bj, At, Bt) do { __builtin_amdgcn_s_setprio(1); _Pragma("unroll") for (int m = 0; m < 4; ++m) _Pragma("unroll") for (int n = 0; n < 2; ++n) _Pragma("unroll") for (int k = 0; k < 2; ++k) \
;         acc[ai][bj][m][n] = __builtin_amdgcn_mfma_f32_16x16x32_bf16(Bt[n][k], At[m][k], acc[ai][bj][m][n], 0, 0, 0); __builtin_amdgcn_s_setprio(0); } while (0)
; #define PG8_WAIT_V(n) asm volatile("s_waitcnt vmcnt(" #n ")" ::: "memory")
; #define PG8_WAIT_L(n) asm volatile("s_waitcnt lgkmcnt(" #n ")" ::: "memory")
; #define PG8_BAR __builtin_amdgcn_s_barrier()
; #define PG8_SCHED __builtin_amdgcn_sched_barrier(0)
; template <class Epi>
; __device__ __forceinline__ void gemm_phase(LAS unsigned char* lds, const Gemm g, const StaticOrder& S, const Epi& E) {
;     ...
;             const char* a1 = PG8_AP(cA, t + 1);
;             const char* a2 = last ? nA : PG8_AP(cA, t + 2); const char* b2 = last ? nB : cB + (size_t)(t + 2) * kstep;
;             const char* a3 = last ? nA + kstep : PG8_AP(cA, t + 3); const char* b3 = b2 + kstep;
;             PG8_LDB(B0, 0, 0); PG8_LDB(B1, 0, 1); PG8_SCHED; PG8_LDA(At, 0, 0); PG8_STAGE(PG8_SA(1, 1), a1 + hstepA, voffA);
;             PG8_WAIT_V(8); PG8_WAIT_L(0); PG8_BAR; PG8_MMA(0, 0, At, B0); PG8_MMA(0, 1, At, B1); PG8_BAR; PG8_SCHED;
;             PG8_LDA(At, 0, 1); PG8_STAGE(PG8_SB(0, 0), b2, voffB); PG8_STAGE(PG8_SB(0, 1), b2 + hstep, voffB); PG8_STAGE(PG8_SA(0, 0), a2, voffA);
.LBB0_881:
	s_cmp_gt_u32 s33, 15
	s_cselect_b32 s12, 0xfdeff800, 0
	s_cselect_b32 s13, -1, 0
	s_cmp_gt_u32 s33, 13
	s_cselect_b32 s87, 0xfdeff800, 0
	s_cselect_b32 s86, -1, 0
	s_add_u32 s87, s87, s36
	s_addc_u32 s86, s86, s37
	s_add_u32 s87, s56, s87
	s_addc_u32 s86, s57, s86
	s_add_u32 s90, s87, 0x100
	s_addc_u32 s86, s86, 0
	s_add_u32 s87, s80, s36
	s_addc_u32 s91, s81, s37
	s_cmp_gt_u32 s33, 12
	s_cselect_b32 s96, 0xfdeff800, 0
	s_cselect_b32 s94, -1, 0
	s_add_u32 s96, s96, s36
	s_addc_u32 s94, s94, s37
	s_add_u32 s96, s56, s96
	s_addc_u32 s94, s57, s94
	s_add_u32 s96, s96, 0x180
	s_addc_u32 s94, s94, 0
	s_add_i32 s14, 0, 0x10000
	s_add_i32 s15, 0, 0x14000
	v_add_u32_e32 v1, s14, v162
	ds_read_b128 v[132:135], v1
	ds_read_b128 v[136:139], v1 offset:1024
	ds_read_b128 v[156:159], v1 offset:2048
	ds_read_b128 v[186:189], v1 offset:3072
	v_add_u32_e32 v1, s15, v162
	ds_read_b128 v[190:193], v1
	ds_read_b128 v[194:197], v1 offset:1024
	ds_read_b128 v[198:201], v1 offset:2048
	ds_read_b128 v[202:205], v1 offset:3072
	s_cmpk_eq_i32 s36, 0xf00
	s_cselect_b32 vcc_lo, s4, s87
	s_cselect_b32 s87, s55, s86
	s_cselect_b32 s86, s92, s90
	s_cselect_b32 s97, s52, s94
	s_cselect_b32 s96, s5, s96
	s_cselect_b32 vcc_hi, s67, s91
	s_add_u32 s90, s12, s36
	s_addc_u32 s91, s13, s37
	v_lshl_add_u64 v[2:3], v[152:153], 0, s[90:91]
	s_add_i32 m0, s93, 0xc000
	ds_read_b128 v[206:209], v163
	ds_read_b128 v[222:225], v163 offset:1024
	ds_read_b128 v[226:229], v163 offset:2048
	ds_read_b128 v[230:233], v163 offset:3072
	ds_read_b128 v[234:237], v163 offset:4096
	ds_read_b128 v[238:241], v163 offset:5120
	ds_read_b128 v[242:245], v163 offset:6144
	ds_read_b128 v[246:249], v163 offset:7168
	global_load_lds_dwordx4 v[2:3], off
	v_lshl_add_u64 v[2:3], v[154:155], 0, s[90:91]
	s_add_i32 m0, s93, 0xe000
	s_nop 0
	global_load_lds_dwordx4 v[2:3], off
	s_waitcnt vmcnt(8)
	s_waitcnt lgkmcnt(0)
	s_barrier
	s_setprio 1
	s_waitcnt lgkmcnt(0)
	v_mfma_f32_16x16x32_bf16 v[128:131], v[132:135], v[206:209], v[128:131]
	v_mfma_f32_16x16x32_bf16 v[124:127], v[156:159], v[206:209], v[124:127]
	v_mfma_f32_16x16x32_bf16 v[112:115], v[132:135], v[226:229], v[112:115]
	v_mfma_f32_16x16x32_bf16 v[108:111], v[156:159], v[226:229], v[108:111]
	v_mfma_f32_16x16x32_bf16 v[96:99], v[132:135], v[234:237], v[96:99]
	v_mfma_f32_16x16x32_bf16 v[92:95], v[156:159], v[234:237], v[92:95]
	v_mfma_f32_16x16x32_bf16 v[80:83], v[132:135], v[242:245], v[80:83]
	v_mfma_f32_16x16x32_bf16 v[76:79], v[156:159], v[242:245], v[76:79]
	v_mfma_f32_16x16x32_bf16 v[128:131], v[136:139], v[222:225], v[128:131]
	v_mfma_f32_16x16x32_bf16 v[124:127], v[186:189], v[222:225], v[124:127]
	v_mfma_f32_16x16x32_bf16 v[112:115], v[136:139], v[230:233], v[112:115]
	v_mfma_f32_16x16x32_bf16 v[108:111], v[186:189], v[230:233], v[108:111]
	v_mfma_f32_16x16x32_bf16 v[96:99], v[136:139], v[238:241], v[96:99]
	v_mfma_f32_16x16x32_bf16 v[92:95], v[186:189], v[238:241], v[92:95]
	v_mfma_f32_16x16x32_bf16 v[80:83], v[136:139], v[246:249], v[80:83]
	v_mfma_f32_16x16x32_bf16 v[76:79], v[186:189], v[246:249], v[76:79]
	v_mfma_f32_16x16x32_bf16 v[120:123], v[190:193], v[206:209], v[120:123]
	v_mfma_f32_16x16x32_bf16 v[116:119], v[198:201], v[206:209], v[116:119]
	v_mfma_f32_16x16x32_bf16 v[104:107], v[190:193], v[226:229], v[104:107]
	v_mfma_f32_16x16x32_bf16 v[100:103], v[198:201], v[226:229], v[100:103]
	v_mfma_f32_16x16x32_bf16 v[88:91], v[190:193], v[234:237], v[88:91]
	v_mfma_f32_16x16x32_bf16 v[84:87], v[198:201], v[234:237], v[84:87]
	v_mfma_f32_16x16x32_bf16 v[72:75], v[190:193], v[242:245], v[72:75]
	v_mfma_f32_16x16x32_bf16 v[68:71], v[198:201], v[242:245], v[68:71]
	v_mfma_f32_16x16x32_bf16 v[120:123], v[194:197], v[222:225], v[120:123]
	v_mfma_f32_16x16x32_bf16 v[116:119], v[202:205], v[222:225], v[116:119]
	v_mfma_f32_16x16x32_bf16 v[104:107], v[194:197], v[230:233], v[104:107]
	v_mfma_f32_16x16x32_bf16 v[100:103], v[202:205], v[230:233], v[100:103]
	v_mfma_f32_16x16x32_bf16 v[88:91], v[194:197], v[238:241], v[88:91]
	v_mfma_f32_16x16x32_bf16 v[84:87], v[202:205], v[238:241], v[84:87]
	v_mfma_f32_16x16x32_bf16 v[72:75], v[194:197], v[246:249], v[72:75]
	v_mfma_f32_16x16x32_bf16 v[68:71], v[202:205], v[246:249], v[68:71]
	s_setprio 0
	s_barrier
	s_add_i32 s12, s14, s85
	v_lshl_add_u64 v[160:161], vcc, 0, v[144:145]
	s_mov_b32 m0, s12
	ds_read_b128 v[206:209], v163 offset:16384
	ds_read_b128 v[222:225], v163 offset:17408
	ds_read_b128 v[226:229], v163 offset:18432
	ds_read_b128 v[230:233], v163 offset:19456
	ds_read_b128 v[234:237], v163 offset:20480
	ds_read_b128 v[238:241], v163 offset:21504
	ds_read_b128 v[242:245], v163 offset:22528
	ds_read_b128 v[246:249], v163 offset:23552
	global_load_lds_dwordx4 v[160:161], off
	s_add_i32 m0, s12, 0x2000
	s_add_u32 s90, vcc_lo, 0x80000
	v_lshl_add_u64 v[212:213], vcc, 0, v[140:141]
	s_addc_u32 s91, vcc_hi, 0
	s_add_i32 s12, s15, s85
	global_load_lds_dwordx4 v[212:213], off
	v_lshl_add_u64 v[2:3], s[90:91], 0, v[144:145]
	s_mov_b32 m0, s12
	s_nop 0
	global_load_lds_dwordx4 v[2:3], off
	v_lshl_add_u64 v[2:3], s[90:91], 0, v[140:141]
	s_add_i32 m0, s12, 0x2000
	s_nop 0
	global_load_lds_dwordx4 v[2:3], off
	v_lshl_add_u64 v[2:3], s[86:87], 0, v[146:147]
	s_mov_b32 m0, s93
	s_nop 0
	global_load_lds_dwordx4 v[2:3], off
	v_lshl_add_u64 v[2:3], s[86:87], 0, v[142:143]
	s_mov_b32 m0, s24
	s_nop 0
	global_load_lds_dwordx4 v[2:3], off
	s_waitcnt vmcnt(8)
	s_waitcnt lgkmcnt(0)
	s_barrier
; #define PG8_STAGE(bufoff, gbase, voff) do { _Pragma("unroll") for (int _i = 0; _i < 2; ++_i) \
;         __builtin_amdgcn_global_load_lds((const unsigned*)((const char*)(gbase) + (voff)[_i]), (LAS unsigned*)(lds + (bufoff) + ldsw + _i * 8192), 16, 0, 0); } while (0)
; #define PG8_LDA(dst, b, h) do { _Pragma("unroll") for (int m = 0; m < 4; ++m) _Pragma("unroll") for (int k = 0; k < 2; ++k) dst[m][k] = *(const LAS bf16x8*)(lds + PG8_SA(b, h) + aoff + m * 2048 + k * 1024); } while (0)
; #define PG8_LDB(dst, b, h) do { _Pragma("unroll") for (int n = 0; n < 2; ++n) _Pragma("unroll") for (int k = 0; k < 2; ++k) dst[n][k] = *(const LAS bf16x8*)(lds + PG8_SB(b, h) + boff + n * 2048 + k * 1024); } while (0)
; #define PG8_MMA(ai, bj, At, Bt) do { __builtin_amdgcn_s_setprio(1); _Pragma("unroll") for (int m = 0; m < 4; ++m) _Pragma("unroll") for (int n = 0; n < 2; ++n) _Pragma("unroll") for (int k = 0; k < 2; ++k) \
;         acc[ai][bj][m][n] = __builtin_amdgcn_mfma_f32_16x16x32_bf16(Bt[n][k], At[m][k], acc[ai][bj][m][n], 0, 0, 0); __builtin_amdgcn_s_setprio(0); } while (0)
; #define PG8_WAIT_V(n) asm volatile("s_waitcnt vmcnt(" #n ")" ::: "memory")
; #define PG8_WAIT_L(n) asm volatile("s_waitcnt lgkmcnt(" #n ")" ::: "memory")
; #define PG8_BAR __builtin_amdgcn_s_barrier()
; #define PG8_SCHED __builtin_amdgcn_sched_barrier(0)
; template <class Epi>
; __device__ __forceinline__ void gemm_phase(LAS unsigned char* lds, const Gemm g, const StaticOrder& S, const Epi& E) {
;     ...
;             PG8_WAIT_V(8); PG8_WAIT_L(0); PG8_BAR; PG8_MMA(1, 0, At, B0); PG8_MMA(1, 1, At, B1); PG8_BAR; PG8_SCHED;
;             PG8_LDB(B0, 1, 0); PG8_LDB(B1, 1, 1); PG8_SCHED; PG8_LDA(At, 1, 0); PG8_STAGE(PG8_SA(0, 1), a2 + hstepA, voffA);
;             PG8_WAIT_V(8); PG8_WAIT_L(0); PG8_BAR; PG8_MMA(0, 0, At, B0); PG8_MMA(0, 1, At, B1); PG8_BAR; PG8_SCHED;
	s_setprio 1
	s_waitcnt lgkmcnt(0)
	v_mfma_f32_16x16x32_bf16 v[64:67], v[132:135], v[206:209], v[64:67]
	v_mfma_f32_16x16x32_bf16 v[60:63], v[156:159], v[206:209], v[60:63]
	v_mfma_f32_16x16x32_bf16 v[48:51], v[132:135], v[226:229], v[48:51]
	v_mfma_f32_16x16x32_bf16 v[44:47], v[156:159], v[226:229], v[44:47]
	v_mfma_f32_16x16x32_bf16 v[32:35], v[132:135], v[234:237], v[32:35]
	v_mfma_f32_16x16x32_bf16 v[28:31], v[156:159], v[234:237], v[28:31]
	v_mfma_f32_16x16x32_bf16 v[16:19], v[132:135], v[242:245], v[16:19]
	v_mfma_f32_16x16x32_bf16 v[12:15], v[156:159], v[242:245], v[12:15]
	v_mfma_f32_16x16x32_bf16 v[64:67], v[136:139], v[222:225], v[64:67]
	v_mfma_f32_16x16x32_bf16 v[60:63], v[186:189], v[222:225], v[60:63]
	v_mfma_f32_16x16x32_bf16 v[48:51], v[136:139], v[230:233], v[48:51]
	v_mfma_f32_16x16x32_bf16 v[44:47], v[186:189], v[230:233], v[44:47]
	v_mfma_f32_16x16x32_bf16 v[32:35], v[136:139], v[238:241], v[32:35]
	v_mfma_f32_16x16x32_bf16 v[28:31], v[186:189], v[238:241], v[28:31]
	v_mfma_f32_16x16x32_bf16 v[16:19], v[136:139], v[246:249], v[16:19]
	v_mfma_f32_16x16x32_bf16 v[12:15], v[186:189], v[246:249], v[12:15]
	v_mfma_f32_16x16x32_bf16 v[56:59], v[190:193], v[206:209], v[56:59]
	v_mfma_f32_16x16x32_bf16 v[52:55], v[198:201], v[206:209], v[52:55]
	v_mfma_f32_16x16x32_bf16 v[40:43], v[190:193], v[226:229], v[40:43]
	v_mfma_f32_16x16x32_bf16 v[36:39], v[198:201], v[226:229], v[36:39]
	v_mfma_f32_16x16x32_bf16 v[24:27], v[190:193], v[234:237], v[24:27]
	v_mfma_f32_16x16x32_bf16 v[20:23], v[198:201], v[234:237], v[20:23]
	v_mfma_f32_16x16x32_bf16 v[8:11], v[190:193], v[242:245], v[8:11]
	v_mfma_f32_16x16x32_bf16 v[2:5], v[198:201], v[242:245], v[4:7]
	v_mfma_f32_16x16x32_bf16 v[56:59], v[194:197], v[222:225], v[56:59]
	v_mfma_f32_16x16x32_bf16 v[52:55], v[202:205], v[222:225], v[52:55]
	v_mfma_f32_16x16x32_bf16 v[40:43], v[194:197], v[230:233], v[40:43]
	v_mfma_f32_16x16x32_bf16 v[36:39], v[202:205], v[230:233], v[36:39]
	v_mfma_f32_16x16x32_bf16 v[24:27], v[194:197], v[238:241], v[24:27]
	v_mfma_f32_16x16x32_bf16 v[20:23], v[202:205], v[238:241], v[20:23]
	v_mfma_f32_16x16x32_bf16 v[8:11], v[194:197], v[246:249], v[8:11]
	v_mfma_f32_16x16x32_bf16 v[2:5], v[202:205], v[246:249], v[2:5]
	s_setprio 0
	s_barrier
	s_add_i32 s12, 0, 0x18000
	v_add_u32_e32 v1, s12, v162
	s_add_i32 s13, 0, 0x1c000
	ds_read_b128 v[132:135], v1
	ds_read_b128 v[136:139], v1 offset:1024
	ds_read_b128 v[156:159], v1 offset:2048
	ds_read_b128 v[186:189], v1 offset:3072
	v_add_u32_e32 v1, s13, v162
	ds_read_b128 v[190:193], v1
	ds_read_b128 v[194:197], v1 offset:1024
	ds_read_b128 v[198:201], v1 offset:2048
	ds_read_b128 v[202:205], v1 offset:3072
	s_add_u32 s86, s86, 0x40000
	s_addc_u32 s87, s87, 0
	s_mov_b32 m0, s25
	v_lshl_add_u64 v[6:7], s[86:87], 0, v[146:147]
	ds_read_b128 v[206:209], v163 offset:32768
	ds_read_b128 v[222:225], v163 offset:33792
	ds_read_b128 v[226:229], v163 offset:34816
	ds_read_b128 v[230:233], v163 offset:35840
	ds_read_b128 v[234:237], v163 offset:36864
	ds_read_b128 v[238:241], v163 offset:37888
	ds_read_b128 v[242:245], v163 offset:38912
	ds_read_b128 v[246:249], v163 offset:39936
	global_load_lds_dwordx4 v[6:7], off
	v_lshl_add_u64 v[6:7], s[86:87], 0, v[142:143]
	s_mov_b32 m0, s26
	s_nop 0
	global_load_lds_dwordx4 v[6:7], off
	s_waitcnt vmcnt(8)
	s_waitcnt lgkmcnt(0)
	s_barrier
	s_setprio 1
	s_waitcnt lgkmcnt(0)
	v_mfma_f32_16x16x32_bf16 v[128:131], v[132:135], v[206:209], v[128:131]
	v_mfma_f32_16x16x32_bf16 v[124:127], v[156:159], v[206:209], v[124:127]
	v_mfma_f32_16x16x32_bf16 v[112:115], v[132:135], v[226:229], v[112:115]
	v_mfma_f32_16x16x32_bf16 v[108:111], v[156:159], v[226:229], v[108:111]
	v_mfma_f32_16x16x32_bf16 v[96:99], v[132:135], v[234:237], v[96:99]
	v_mfma_f32_16x16x32_bf16 v[92:95], v[156:159], v[234:237], v[92:95]
	v_mfma_f32_16x16x32_bf16 v[80:83], v[132:135], v[242:245], v[80:83]
	v_mfma_f32_16x16x32_bf16 v[76:79], v[156:159], v[242:245], v[76:79]
	v_mfma_f32_16x16x32_bf16 v[128:131], v[136:139], v[222:225], v[128:131]
	v_mfma_f32_16x16x32_bf16 v[124:127], v[186:189], v[222:225], v[124:127]
	v_mfma_f32_16x16x32_bf16 v[112:115], v[136:139], v[230:233], v[112:115]
	v_mfma_f32_16x16x32_bf16 v[108:111], v[186:189], v[230:233], v[108:111]
	v_mfma_f32_16x16x32_bf16 v[96:99], v[136:139], v[238:241], v[96:99]
	v_mfma_f32_16x16x32_bf16 v[92:95], v[186:189], v[238:241], v[92:95]
	v_mfma_f32_16x16x32_bf16 v[80:83], v[136:139], v[246:249], v[80:83]
	v_mfma_f32_16x16x32_bf16 v[76:79], v[186:189], v[246:249], v[76:79]
	v_mfma_f32_16x16x32_bf16 v[120:123], v[190:193], v[206:209], v[120:123]
	v_mfma_f32_16x16x32_bf16 v[116:119], v[198:201], v[206:209], v[116:119]
	v_mfma_f32_16x16x32_bf16 v[104:107], v[190:193], v[226:229], v[104:107]
	v_mfma_f32_16x16x32_bf16 v[100:103], v[198:201], v[226:229], v[100:103]
	v_mfma_f32_16x16x32_bf16 v[88:91], v[190:193], v[234:237], v[88:91]
	v_mfma_f32_16x16x32_bf16 v[84:87], v[198:201], v[234:237], v[84:87]
	v_mfma_f32_16x16x32_bf16 v[72:75], v[190:193], v[242:245], v[72:75]
	v_mfma_f32_16x16x32_bf16 v[68:71], v[198:201], v[242:245], v[68:71]
	v_mfma_f32_16x16x32_bf16 v[120:123], v[194:197], v[222:225], v[120:123]
	v_mfma_f32_16x16x32_bf16 v[116:119], v[202:205], v[222:225], v[116:119]
	v_mfma_f32_16x16x32_bf16 v[104:107], v[194:197], v[230:233], v[104:107]
	v_mfma_f32_16x16x32_bf16 v[100:103], v[202:205], v[230:233], v[100:103]
	v_mfma_f32_16x16x32_bf16 v[88:91], v[194:197], v[238:241], v[88:91]
	v_mfma_f32_16x16x32_bf16 v[84:87], v[202:205], v[238:241], v[84:87]
	v_mfma_f32_16x16x32_bf16 v[72:75], v[194:197], v[246:249], v[72:75]
	v_mfma_f32_16x16x32_bf16 v[68:71], v[202:205], v[246:249], v[68:71]
	s_setprio 0
	s_barrier
; #define PG8_STAGE(bufoff, gbase, voff) do { _Pragma("unroll") for (int _i = 0; _i < 2; ++_i) \
;         __builtin_amdgcn_global_load_lds((const unsigned*)((const char*)(gbase) + (voff)[_i]), (LAS unsigned*)(lds + (bufoff) + ldsw + _i * 8192), 16, 0, 0); } while (0)
; #define PG8_LDA(dst, b, h) do { _Pragma("unroll") for (int m = 0; m < 4; ++m) _Pragma("unroll") for (int k = 0; k < 2; ++k) dst[m][k] = *(const LAS bf16x8*)(lds + PG8_SA(b, h) + aoff + m * 2048 + k * 1024); } while (0)
; #define PG8_MMA(ai, bj, At, Bt) do { __builtin_amdgcn_s_setprio(1); _Pragma("unroll") for (int m = 0; m < 4; ++m) _Pragma("unroll") for (int n = 0; n < 2; ++n) _Pragma("unroll") for (int k = 0; k < 2; ++k) \
;         acc[ai][bj][m][n] = __builtin_amdgcn_mfma_f32_16x16x32_bf16(Bt[n][k], At[m][k], acc[ai][bj][m][n], 0, 0, 0); __builtin_amdgcn_s_setprio(0); } while (0)
; #define PG8_WAIT_V(n) asm volatile("s_waitcnt vmcnt(" #n ")" ::: "memory")
; #define PG8_WAIT_L(n) asm volatile("s_waitcnt lgkmcnt(" #n ")" ::: "memory")
; #define PG8_BAR __builtin_amdgcn_s_barrier()
; #define PG8_SCHED __builtin_amdgcn_sched_barrier(0)
; template <class Epi>
; __device__ __forceinline__ void gemm_phase(LAS unsigned char* lds, const Gemm g, const StaticOrder& S, const Epi& E) {
;     ...
;             if constexpr (Epi::GATED) { if (t == 8 || t == 16) E.rescale(acc, cur, t == 8 ? 0 : 1, wr, wc, fr, fq); }
;     ...
;             PG8_LDA(At, 1, 1); PG8_STAGE(PG8_SB(1, 0), b3, voffB); PG8_STAGE(PG8_SB(1, 1), b3 + hstep, voffB); PG8_STAGE(PG8_SA(1, 0), a3, voffA);
;             PG8_WAIT_V(8); PG8_WAIT_L(0); PG8_BAR; PG8_MMA(1, 0, At, B0); PG8_MMA(1, 1, At, B1); PG8_BAR; PG8_SCHED;
;         }
	s_add_i32 s12, s12, s85
	v_lshl_add_u64 v[6:7], v[160:161], 0, s[6:7]
	s_mov_b32 m0, s12
	ds_read_b128 v[206:209], v163 offset:49152
	ds_read_b128 v[222:225], v163 offset:50176
	ds_read_b128 v[226:229], v163 offset:51200
	ds_read_b128 v[230:233], v163 offset:52224
	ds_read_b128 v[234:237], v163 offset:53248
	ds_read_b128 v[238:241], v163 offset:54272
	ds_read_b128 v[242:245], v163 offset:55296
	ds_read_b128 v[246:249], v163 offset:56320
	global_load_lds_dwordx4 v[6:7], off
	s_add_i32 m0, s12, 0x2000
	s_add_u32 s86, vcc_lo, 0x80080
	v_lshl_add_u64 v[6:7], v[212:213], 0, s[6:7]
	s_addc_u32 s87, vcc_hi, 0
	s_add_i32 s12, s13, s85
	global_load_lds_dwordx4 v[6:7], off
	v_lshl_add_u64 v[6:7], s[86:87], 0, v[144:145]
	s_mov_b32 m0, s12
	s_nop 0
	global_load_lds_dwordx4 v[6:7], off
	v_lshl_add_u64 v[6:7], s[86:87], 0, v[140:141]
	s_add_i32 m0, s12, 0x2000
	s_nop 0
	global_load_lds_dwordx4 v[6:7], off
	v_lshl_add_u64 v[6:7], s[96:97], 0, v[146:147]
	s_mov_b32 m0, s27
	s_nop 0
	global_load_lds_dwordx4 v[6:7], off
	v_lshl_add_u64 v[6:7], s[96:97], 0, v[142:143]
	s_mov_b32 m0, s38
	s_nop 0
	global_load_lds_dwordx4 v[6:7], off
	s_waitcnt vmcnt(8)
	s_waitcnt lgkmcnt(0)
	s_barrier
	s_setprio 1
	s_waitcnt lgkmcnt(0)
	v_mfma_f32_16x16x32_bf16 v[64:67], v[132:135], v[206:209], v[64:67]
	v_mfma_f32_16x16x32_bf16 v[60:63], v[156:159], v[206:209], v[60:63]
	v_mfma_f32_16x16x32_bf16 v[48:51], v[132:135], v[226:229], v[48:51]
	v_mfma_f32_16x16x32_bf16 v[44:47], v[156:159], v[226:229], v[44:47]
	v_mfma_f32_16x16x32_bf16 v[32:35], v[132:135], v[234:237], v[32:35]
	v_mfma_f32_16x16x32_bf16 v[28:31], v[156:159], v[234:237], v[28:31]
	v_mfma_f32_16x16x32_bf16 v[16:19], v[132:135], v[242:245], v[16:19]
	v_mfma_f32_16x16x32_bf16 v[12:15], v[156:159], v[242:245], v[12:15]
	v_mfma_f32_16x16x32_bf16 v[64:67], v[136:139], v[222:225], v[64:67]
	v_mfma_f32_16x16x32_bf16 v[60:63], v[186:189], v[222:225], v[60:63]
	v_mfma_f32_16x16x32_bf16 v[48:51], v[136:139], v[230:233], v[48:51]
	v_mfma_f32_16x16x32_bf16 v[44:47], v[186:189], v[230:233], v[44:47]
	v_mfma_f32_16x16x32_bf16 v[32:35], v[136:139], v[238:241], v[32:35]
	v_mfma_f32_16x16x32_bf16 v[28:31], v[186:189], v[238:241], v[28:31]
	v_mfma_f32_16x16x32_bf16 v[16:19], v[136:139], v[246:249], v[16:19]
	v_mfma_f32_16x16x32_bf16 v[12:15], v[186:189], v[246:249], v[12:15]
	v_mfma_f32_16x16x32_bf16 v[56:59], v[190:193], v[206:209], v[56:59]
	v_mfma_f32_16x16x32_bf16 v[52:55], v[198:201], v[206:209], v[52:55]
	v_mfma_f32_16x16x32_bf16 v[40:43], v[190:193], v[226:229], v[40:43]
	v_mfma_f32_16x16x32_bf16 v[36:39], v[198:201], v[226:229], v[36:39]
	v_mfma_f32_16x16x32_bf16 v[24:27], v[190:193], v[234:237], v[24:27]
	v_mfma_f32_16x16x32_bf16 v[20:23], v[198:201], v[234:237], v[20:23]
	v_mfma_f32_16x16x32_bf16 v[6:9], v[190:193], v[242:245], v[8:11]
	v_mfma_f32_16x16x32_bf16 v[2:5], v[198:201], v[242:245], v[2:5]
	v_mfma_f32_16x16x32_bf16 v[56:59], v[194:197], v[222:225], v[56:59]
	v_mfma_f32_16x16x32_bf16 v[52:55], v[202:205], v[222:225], v[52:55]
	v_mfma_f32_16x16x32_bf16 v[40:43], v[194:197], v[230:233], v[40:43]
	v_mfma_f32_16x16x32_bf16 v[36:39], v[202:205], v[230:233], v[36:39]
	v_mfma_f32_16x16x32_bf16 v[24:27], v[194:197], v[238:241], v[24:27]
	v_mfma_f32_16x16x32_bf16 v[20:23], v[202:205], v[238:241], v[20:23]
	v_mfma_f32_16x16x32_bf16 v[8:11], v[194:197], v[246:249], v[6:9]
	v_mfma_f32_16x16x32_bf16 v[4:7], v[202:205], v[246:249], v[2:5]
	s_setprio 0
	s_barrier
	s_add_i32 s86, s33, 2
	s_add_u32 s36, s36, 0x100
	s_addc_u32 s37, s37, 0
	s_cmp_gt_u32 s33, 29
	s_cbranch_scc1 .LBB0_884
	s_mov_b32 s33, s86
	s_cmp_lt_i32 s33, 16
	s_cbranch_scc1 .LBB0_876
	s_branch .LBB0_875

; #define PG8_STAGE(bufoff, gbase, voff) do { _Pragma("unroll") for (int _i = 0; _i < 2; ++_i) \
;         __builtin_amdgcn_global_load_lds((const unsigned*)((const char*)(gbase) + (voff)[_i]), (LAS unsigned*)(lds + (bufoff) + ldsw + _i * 8192), 16, 0, 0); } while (0)
; #define PG8_LDA(dst, b, h) do { _Pragma("unroll") for (int m = 0; m < 4; ++m) _Pragma("unroll") for (int k = 0; k < 2; ++k) dst[m][k] = *(const LAS bf16x8*)(lds + PG8_SA(b, h) + aoff + m * 2048 + k * 1024); } while (0)
; #define PG8_LDB(dst, b, h) do { _Pragma("unroll") for (int n = 0; n < 2; ++n) _Pragma("unroll") for (int k = 0; k < 2; ++k) dst[n][k] = *(const LAS bf16x8*)(lds + PG8_SB(b, h) + boff + n * 2048 + k * 1024); } while (0)
; #define PG8_MMA(ai, bj, At, Bt) do { __builtin_amdgcn_s_setprio(1); _Pragma("unroll") for (int m = 0; m < 4; ++m) _Pragma("unroll") for (int n = 0; n < 2; ++n) _Pragma("unroll") for (int k = 0; k < 2; ++k) \
;         acc[ai][bj][m][n] = __builtin_amdgcn_mfma_f32_16x16x32_bf16(Bt[n][k], At[m][k], acc[ai][bj][m][n], 0, 0, 0); __builtin_amdgcn_s_setprio(0); } while (0)
; #define PG8_WAIT_V(n) asm volatile("s_waitcnt vmcnt(" #n ")" ::: "memory")
; #define PG8_WAIT_L(n) asm volatile("s_waitcnt lgkmcnt(" #n ")" ::: "memory")
; #define PG8_BAR __builtin_amdgcn_s_barrier()
; #define PG8_SCHED __builtin_amdgcn_sched_barrier(0)
; template <class Epi>
; __device__ __forceinline__ void gemm_phase(LAS unsigned char* lds, const Gemm g, const StaticOrder& S, const Epi& E) {
;     ...
;             const char* a1 = PG8_AP(cA, t + 1);
;             const char* a2 = last ? nA : PG8_AP(cA, t + 2); const char* b2 = last ? nB : cB + (size_t)(t + 2) * kstep;
;             const char* a3 = last ? nA + kstep : PG8_AP(cA, t + 3); const char* b3 = b2 + kstep;
;             PG8_LDB(B0, 0, 0); PG8_LDB(B1, 0, 1); PG8_SCHED; PG8_LDA(At, 0, 0); PG8_STAGE(PG8_SA(1, 1), a1 + hstepA, voffA);
;             PG8_WAIT_V(8); PG8_WAIT_L(0); PG8_BAR; PG8_MMA(0, 0, At, B0); PG8_MMA(0, 1, At, B1); PG8_BAR; PG8_SCHED;
;             PG8_LDA(At, 0, 1); PG8_STAGE(PG8_SB(0, 0), b2, voffB); PG8_STAGE(PG8_SB(0, 1), b2 + hstep, voffB); PG8_STAGE(PG8_SA(0, 0), a2, voffA);
.LBB0_955:
	s_add_u32 s12, s50, s54
	s_addc_u32 s13, s51, s55
	s_add_u32 s14, s12, 0x100
	s_addc_u32 s15, s13, 0
	s_add_u32 s86, s85, s54
	s_addc_u32 s87, s92, s55
	s_add_u32 s12, s12, 0x180
	s_addc_u32 s13, s13, 0
	s_add_i32 s90, 0, 0x10000
	s_add_i32 s94, 0, 0x14000
	v_add_u32_e32 v147, s90, v1
	ds_read_b128 v[148:151], v147
	ds_read_b128 v[152:155], v147 offset:1024
	ds_read_b128 v[156:159], v147 offset:2048
	ds_read_b128 v[160:163], v147 offset:3072
	v_add_u32_e32 v147, s94, v1
	ds_read_b128 v[186:189], v147
	ds_read_b128 v[190:193], v147 offset:1024
	ds_read_b128 v[194:197], v147 offset:2048
	ds_read_b128 v[198:201], v147 offset:3072
	s_cmpk_eq_i32 s54, 0xf00
	s_cselect_b32 s57, s81, s13
	s_cselect_b32 s56, s80, s12
	s_cselect_b32 s97, s43, s87
	s_cselect_b32 s96, s67, s86
	s_cselect_b32 s87, s45, s15
	s_cselect_b32 s86, s63, s14
	v_lshl_add_u64 v[212:213], v[142:143], 0, s[54:55]
	s_add_i32 m0, s25, 0xc000
	ds_read_b128 v[202:205], v146
	ds_read_b128 v[206:209], v146 offset:1024
	ds_read_b128 v[222:225], v146 offset:2048
	ds_read_b128 v[226:229], v146 offset:3072
	ds_read_b128 v[230:233], v146 offset:4096
	ds_read_b128 v[234:237], v146 offset:5120
	ds_read_b128 v[238:241], v146 offset:6144
	ds_read_b128 v[242:245], v146 offset:7168
	global_load_lds_dwordx4 v[212:213], off
	v_lshl_add_u64 v[212:213], v[144:145], 0, s[54:55]
	s_add_i32 m0, s25, 0xe000
	s_nop 0
	global_load_lds_dwordx4 v[212:213], off
	s_waitcnt vmcnt(8)
	s_waitcnt lgkmcnt(0)
	s_barrier
	s_setprio 1
	s_waitcnt lgkmcnt(0)
	v_mfma_f32_16x16x32_bf16 v[126:129], v[148:151], v[202:205], v[126:129]
	v_mfma_f32_16x16x32_bf16 v[122:125], v[156:159], v[202:205], v[122:125]
	v_mfma_f32_16x16x32_bf16 v[118:121], v[148:151], v[222:225], v[118:121]
	v_mfma_f32_16x16x32_bf16 v[110:113], v[156:159], v[222:225], v[110:113]
	v_mfma_f32_16x16x32_bf16 v[102:105], v[148:151], v[230:233], v[102:105]
	v_mfma_f32_16x16x32_bf16 v[94:97], v[156:159], v[230:233], v[94:97]
	v_mfma_f32_16x16x32_bf16 v[86:89], v[148:151], v[238:241], v[86:89]
	v_mfma_f32_16x16x32_bf16 v[78:81], v[156:159], v[238:241], v[78:81]
	v_mfma_f32_16x16x32_bf16 v[126:129], v[152:155], v[206:209], v[126:129]
	v_mfma_f32_16x16x32_bf16 v[122:125], v[160:163], v[206:209], v[122:125]
	v_mfma_f32_16x16x32_bf16 v[118:121], v[152:155], v[226:229], v[118:121]
	v_mfma_f32_16x16x32_bf16 v[110:113], v[160:163], v[226:229], v[110:113]
	v_mfma_f32_16x16x32_bf16 v[102:105], v[152:155], v[234:237], v[102:105]
	v_mfma_f32_16x16x32_bf16 v[94:97], v[160:163], v[234:237], v[94:97]
	v_mfma_f32_16x16x32_bf16 v[86:89], v[152:155], v[242:245], v[86:89]
	v_mfma_f32_16x16x32_bf16 v[78:81], v[160:163], v[242:245], v[78:81]
	v_mfma_f32_16x16x32_bf16 v[114:117], v[186:189], v[202:205], v[114:117]
	v_mfma_f32_16x16x32_bf16 v[106:109], v[194:197], v[202:205], v[106:109]
	v_mfma_f32_16x16x32_bf16 v[98:101], v[186:189], v[222:225], v[98:101]
	v_mfma_f32_16x16x32_bf16 v[90:93], v[194:197], v[222:225], v[90:93]
	v_mfma_f32_16x16x32_bf16 v[82:85], v[186:189], v[230:233], v[82:85]
	v_mfma_f32_16x16x32_bf16 v[74:77], v[194:197], v[230:233], v[74:77]
	v_mfma_f32_16x16x32_bf16 v[70:73], v[186:189], v[238:241], v[70:73]
	v_mfma_f32_16x16x32_bf16 v[66:69], v[194:197], v[238:241], v[66:69]
	v_mfma_f32_16x16x32_bf16 v[114:117], v[190:193], v[206:209], v[114:117]
	v_mfma_f32_16x16x32_bf16 v[106:109], v[198:201], v[206:209], v[106:109]
	v_mfma_f32_16x16x32_bf16 v[98:101], v[190:193], v[226:229], v[98:101]
	v_mfma_f32_16x16x32_bf16 v[90:93], v[198:201], v[226:229], v[90:93]
	v_mfma_f32_16x16x32_bf16 v[82:85], v[190:193], v[234:237], v[82:85]
	v_mfma_f32_16x16x32_bf16 v[74:77], v[198:201], v[234:237], v[74:77]
	v_mfma_f32_16x16x32_bf16 v[70:73], v[190:193], v[242:245], v[70:73]
	v_mfma_f32_16x16x32_bf16 v[66:69], v[198:201], v[242:245], v[66:69]
	s_setprio 0
	s_barrier
	s_add_i32 s12, s90, s24
	v_lshl_add_u64 v[212:213], s[96:97], 0, v[134:135]
	s_mov_b32 m0, s12
	ds_read_b128 v[202:205], v146 offset:16384
	ds_read_b128 v[206:209], v146 offset:17408
	ds_read_b128 v[222:225], v146 offset:18432
	ds_read_b128 v[226:229], v146 offset:19456
	ds_read_b128 v[230:233], v146 offset:20480
	ds_read_b128 v[234:237], v146 offset:21504
	ds_read_b128 v[238:241], v146 offset:22528
	ds_read_b128 v[242:245], v146 offset:23552
	global_load_lds_dwordx4 v[212:213], off
	s_add_i32 m0, s12, 0x2000
	s_add_u32 s90, s96, 0x80000
	v_lshl_add_u64 v[246:247], s[96:97], 0, v[130:131]
	s_addc_u32 s91, s97, 0
	s_add_i32 s12, s94, s24
	global_load_lds_dwordx4 v[246:247], off
	v_lshl_add_u64 v[248:249], s[90:91], 0, v[134:135]
	s_mov_b32 m0, s12
	s_nop 0
	global_load_lds_dwordx4 v[248:249], off
	v_lshl_add_u64 v[248:249], s[90:91], 0, v[130:131]
	s_add_i32 m0, s12, 0x2000
	s_nop 0
	global_load_lds_dwordx4 v[248:249], off
	v_lshl_add_u64 v[248:249], s[86:87], 0, v[136:137]
	s_mov_b32 m0, s25
	s_nop 0
	global_load_lds_dwordx4 v[248:249], off
	v_lshl_add_u64 v[248:249], s[86:87], 0, v[132:133]
	s_mov_b32 m0, s26
	s_nop 0
	global_load_lds_dwordx4 v[248:249], off
	s_waitcnt vmcnt(8)
	s_waitcnt lgkmcnt(0)
	s_barrier
; #define PG8_STAGE(bufoff, gbase, voff) do { _Pragma("unroll") for (int _i = 0; _i < 2; ++_i) \
;         __builtin_amdgcn_global_load_lds((const unsigned*)((const char*)(gbase) + (voff)[_i]), (LAS unsigned*)(lds + (bufoff) + ldsw + _i * 8192), 16, 0, 0); } while (0)
; #define PG8_LDA(dst, b, h) do { _Pragma("unroll") for (int m = 0; m < 4; ++m) _Pragma("unroll") for (int k = 0; k < 2; ++k) dst[m][k] = *(const LAS bf16x8*)(lds + PG8_SA(b, h) + aoff + m * 2048 + k * 1024); } while (0)
; #define PG8_LDB(dst, b, h) do { _Pragma("unroll") for (int n = 0; n < 2; ++n) _Pragma("unroll") for (int k = 0; k < 2; ++k) dst[n][k] = *(const LAS bf16x8*)(lds + PG8_SB(b, h) + boff + n * 2048 + k * 1024); } while (0)
; #define PG8_MMA(ai, bj, At, Bt) do { __builtin_amdgcn_s_setprio(1); _Pragma("unroll") for (int m = 0; m < 4; ++m) _Pragma("unroll") for (int n = 0; n < 2; ++n) _Pragma("unroll") for (int k = 0; k < 2; ++k) \
;         acc[ai][bj][m][n] = __builtin_amdgcn_mfma_f32_16x16x32_bf16(Bt[n][k], At[m][k], acc[ai][bj][m][n], 0, 0, 0); __builtin_amdgcn_s_setprio(0); } while (0)
; #define PG8_WAIT_V(n) asm volatile("s_waitcnt vmcnt(" #n ")" ::: "memory")
; #define PG8_WAIT_L(n) asm volatile("s_waitcnt lgkmcnt(" #n ")" ::: "memory")
; #define PG8_BAR __builtin_amdgcn_s_barrier()
; #define PG8_SCHED __builtin_amdgcn_sched_barrier(0)
; template <class Epi>
; __device__ __forceinline__ void gemm_phase(LAS unsigned char* lds, const Gemm g, const StaticOrder& S, const Epi& E) {
;     ...
;             PG8_WAIT_V(8); PG8_WAIT_L(0); PG8_BAR; PG8_MMA(1, 0, At, B0); PG8_MMA(1, 1, At, B1); PG8_BAR; PG8_SCHED;
;             PG8_LDB(B0, 1, 0); PG8_LDB(B1, 1, 1); PG8_SCHED; PG8_LDA(At, 1, 0); PG8_STAGE(PG8_SA(0, 1), a2 + hstepA, voffA);
;             PG8_WAIT_V(8); PG8_WAIT_L(0); PG8_BAR; PG8_MMA(0, 0, At, B0); PG8_MMA(0, 1, At, B1); PG8_BAR; PG8_SCHED;
	s_setprio 1
	s_waitcnt lgkmcnt(0)
	v_mfma_f32_16x16x32_bf16 v[62:65], v[148:151], v[202:205], v[62:65]
	v_mfma_f32_16x16x32_bf16 v[58:61], v[156:159], v[202:205], v[58:61]
	v_mfma_f32_16x16x32_bf16 v[54:57], v[148:151], v[222:225], v[54:57]
	v_mfma_f32_16x16x32_bf16 v[46:49], v[156:159], v[222:225], v[46:49]
	v_mfma_f32_16x16x32_bf16 v[38:41], v[148:151], v[230:233], v[38:41]
	v_mfma_f32_16x16x32_bf16 v[30:33], v[156:159], v[230:233], v[30:33]
	v_mfma_f32_16x16x32_bf16 v[22:25], v[148:151], v[238:241], v[22:25]
	v_mfma_f32_16x16x32_bf16 v[14:17], v[156:159], v[238:241], v[14:17]
	v_mfma_f32_16x16x32_bf16 v[62:65], v[152:155], v[206:209], v[62:65]
	v_mfma_f32_16x16x32_bf16 v[58:61], v[160:163], v[206:209], v[58:61]
	v_mfma_f32_16x16x32_bf16 v[54:57], v[152:155], v[226:229], v[54:57]
	v_mfma_f32_16x16x32_bf16 v[46:49], v[160:163], v[226:229], v[46:49]
	v_mfma_f32_16x16x32_bf16 v[38:41], v[152:155], v[234:237], v[38:41]
	v_mfma_f32_16x16x32_bf16 v[30:33], v[160:163], v[234:237], v[30:33]
	v_mfma_f32_16x16x32_bf16 v[22:25], v[152:155], v[242:245], v[22:25]
	v_mfma_f32_16x16x32_bf16 v[14:17], v[160:163], v[242:245], v[14:17]
	v_mfma_f32_16x16x32_bf16 v[50:53], v[186:189], v[202:205], v[50:53]
	v_mfma_f32_16x16x32_bf16 v[42:45], v[194:197], v[202:205], v[42:45]
	v_mfma_f32_16x16x32_bf16 v[34:37], v[186:189], v[222:225], v[34:37]
	v_mfma_f32_16x16x32_bf16 v[26:29], v[194:197], v[222:225], v[26:29]
	v_mfma_f32_16x16x32_bf16 v[18:21], v[186:189], v[230:233], v[18:21]
	v_mfma_f32_16x16x32_bf16 v[10:13], v[194:197], v[230:233], v[10:13]
	v_mfma_f32_16x16x32_bf16 v[6:9], v[186:189], v[238:241], v[6:9]
	v_mfma_f32_16x16x32_bf16 v[2:5], v[194:197], v[238:241], v[2:5]
	v_mfma_f32_16x16x32_bf16 v[50:53], v[190:193], v[206:209], v[50:53]
	v_mfma_f32_16x16x32_bf16 v[42:45], v[198:201], v[206:209], v[42:45]
	v_mfma_f32_16x16x32_bf16 v[34:37], v[190:193], v[226:229], v[34:37]
	v_mfma_f32_16x16x32_bf16 v[26:29], v[198:201], v[226:229], v[26:29]
	v_mfma_f32_16x16x32_bf16 v[18:21], v[190:193], v[234:237], v[18:21]
	v_mfma_f32_16x16x32_bf16 v[10:13], v[198:201], v[234:237], v[10:13]
	v_mfma_f32_16x16x32_bf16 v[6:9], v[190:193], v[242:245], v[6:9]
	v_mfma_f32_16x16x32_bf16 v[2:5], v[198:201], v[242:245], v[2:5]
	s_setprio 0
	s_barrier
	s_add_i32 s12, 0, 0x18000
	v_add_u32_e32 v147, s12, v1
	s_add_i32 s13, 0, 0x1c000
	ds_read_b128 v[148:151], v147
	ds_read_b128 v[152:155], v147 offset:1024
	ds_read_b128 v[156:159], v147 offset:2048
	ds_read_b128 v[160:163], v147 offset:3072
	v_add_u32_e32 v147, s13, v1
	ds_read_b128 v[186:189], v147
	ds_read_b128 v[190:193], v147 offset:1024
	ds_read_b128 v[194:197], v147 offset:2048
	ds_read_b128 v[198:201], v147 offset:3072
	s_add_u32 s86, s86, 0x80000
	s_addc_u32 s87, s87, 0
	s_mov_b32 m0, s27
	v_lshl_add_u64 v[248:249], s[86:87], 0, v[136:137]
	ds_read_b128 v[202:205], v146 offset:32768
	ds_read_b128 v[206:209], v146 offset:33792
	ds_read_b128 v[222:225], v146 offset:34816
	ds_read_b128 v[226:229], v146 offset:35840
	ds_read_b128 v[230:233], v146 offset:36864
	ds_read_b128 v[234:237], v146 offset:37888
	ds_read_b128 v[238:241], v146 offset:38912
	ds_read_b128 v[242:245], v146 offset:39936
	global_load_lds_dwordx4 v[248:249], off
	v_lshl_add_u64 v[248:249], s[86:87], 0, v[132:133]
	s_mov_b32 m0, s28
	s_nop 0
	global_load_lds_dwordx4 v[248:249], off
	s_waitcnt vmcnt(8)
	s_waitcnt lgkmcnt(0)
	s_barrier
	s_setprio 1
	s_waitcnt lgkmcnt(0)
	v_mfma_f32_16x16x32_bf16 v[126:129], v[148:151], v[202:205], v[126:129]
	v_mfma_f32_16x16x32_bf16 v[122:125], v[156:159], v[202:205], v[122:125]
	v_mfma_f32_16x16x32_bf16 v[118:121], v[148:151], v[222:225], v[118:121]
	v_mfma_f32_16x16x32_bf16 v[110:113], v[156:159], v[222:225], v[110:113]
	v_mfma_f32_16x16x32_bf16 v[102:105], v[148:151], v[230:233], v[102:105]
	v_mfma_f32_16x16x32_bf16 v[94:97], v[156:159], v[230:233], v[94:97]
	v_mfma_f32_16x16x32_bf16 v[86:89], v[148:151], v[238:241], v[86:89]
	v_mfma_f32_16x16x32_bf16 v[78:81], v[156:159], v[238:241], v[78:81]
	v_mfma_f32_16x16x32_bf16 v[126:129], v[152:155], v[206:209], v[126:129]
	v_mfma_f32_16x16x32_bf16 v[122:125], v[160:163], v[206:209], v[122:125]
	v_mfma_f32_16x16x32_bf16 v[118:121], v[152:155], v[226:229], v[118:121]
	v_mfma_f32_16x16x32_bf16 v[110:113], v[160:163], v[226:229], v[110:113]
	v_mfma_f32_16x16x32_bf16 v[102:105], v[152:155], v[234:237], v[102:105]
	v_mfma_f32_16x16x32_bf16 v[94:97], v[160:163], v[234:237], v[94:97]
	v_mfma_f32_16x16x32_bf16 v[86:89], v[152:155], v[242:245], v[86:89]
	v_mfma_f32_16x16x32_bf16 v[78:81], v[160:163], v[242:245], v[78:81]
	v_mfma_f32_16x16x32_bf16 v[114:117], v[186:189], v[202:205], v[114:117]
	v_mfma_f32_16x16x32_bf16 v[106:109], v[194:197], v[202:205], v[106:109]
	v_mfma_f32_16x16x32_bf16 v[98:101], v[186:189], v[222:225], v[98:101]
	v_mfma_f32_16x16x32_bf16 v[90:93], v[194:197], v[222:225], v[90:93]
	v_mfma_f32_16x16x32_bf16 v[82:85], v[186:189], v[230:233], v[82:85]
	v_mfma_f32_16x16x32_bf16 v[74:77], v[194:197], v[230:233], v[74:77]
	v_mfma_f32_16x16x32_bf16 v[70:73], v[186:189], v[238:241], v[70:73]
	v_mfma_f32_16x16x32_bf16 v[66:69], v[194:197], v[238:241], v[66:69]
	v_mfma_f32_16x16x32_bf16 v[114:117], v[190:193], v[206:209], v[114:117]
	v_mfma_f32_16x16x32_bf16 v[106:109], v[198:201], v[206:209], v[106:109]
	v_mfma_f32_16x16x32_bf16 v[98:101], v[190:193], v[226:229], v[98:101]
	v_mfma_f32_16x16x32_bf16 v[90:93], v[198:201], v[226:229], v[90:93]
	v_mfma_f32_16x16x32_bf16 v[82:85], v[190:193], v[234:237], v[82:85]
	v_mfma_f32_16x16x32_bf16 v[74:77], v[198:201], v[234:237], v[74:77]
	v_mfma_f32_16x16x32_bf16 v[70:73], v[190:193], v[242:245], v[70:73]
	v_mfma_f32_16x16x32_bf16 v[66:69], v[198:201], v[242:245], v[66:69]
	s_setprio 0
	s_barrier
; #define PG8_STAGE(bufoff, gbase, voff) do { _Pragma("unroll") for (int _i = 0; _i < 2; ++_i) \
;         __builtin_amdgcn_global_load_lds((const unsigned*)((const char*)(gbase) + (voff)[_i]), (LAS unsigned*)(lds + (bufoff) + ldsw + _i * 8192), 16, 0, 0); } while (0)
; #define PG8_LDA(dst, b, h) do { _Pragma("unroll") for (int m = 0; m < 4; ++m) _Pragma("unroll") for (int k = 0; k < 2; ++k) dst[m][k] = *(const LAS bf16x8*)(lds + PG8_SA(b, h) + aoff + m * 2048 + k * 1024); } while (0)
; #define PG8_MMA(ai, bj, At, Bt) do { __builtin_amdgcn_s_setprio(1); _Pragma("unroll") for (int m = 0; m < 4; ++m) _Pragma("unroll") for (int n = 0; n < 2; ++n) _Pragma("unroll") for (int k = 0; k < 2; ++k) \
;         acc[ai][bj][m][n] = __builtin_amdgcn_mfma_f32_16x16x32_bf16(Bt[n][k], At[m][k], acc[ai][bj][m][n], 0, 0, 0); __builtin_amdgcn_s_setprio(0); } while (0)
; #define PG8_WAIT_V(n) asm volatile("s_waitcnt vmcnt(" #n ")" ::: "memory")
; #define PG8_WAIT_L(n) asm volatile("s_waitcnt lgkmcnt(" #n ")" ::: "memory")
; #define PG8_BAR __builtin_amdgcn_s_barrier()
; #define PG8_SCHED __builtin_amdgcn_sched_barrier(0)
; template <class Epi>
; __device__ __forceinline__ void gemm_phase(LAS unsigned char* lds, const Gemm g, const StaticOrder& S, const Epi& E) {
;     ...
;             PG8_LDA(At, 1, 1); PG8_STAGE(PG8_SB(1, 0), b3, voffB); PG8_STAGE(PG8_SB(1, 1), b3 + hstep, voffB); PG8_STAGE(PG8_SA(1, 0), a3, voffA);
;             PG8_WAIT_V(8); PG8_WAIT_L(0); PG8_BAR; PG8_MMA(1, 0, At, B0); PG8_MMA(1, 1, At, B1); PG8_BAR; PG8_SCHED;
;         }
;         if (wr == 0) PG8_BAR;
	s_add_i32 s12, s12, s24
	v_lshl_add_u64 v[212:213], v[212:213], 0, s[6:7]
	s_mov_b32 m0, s12
	ds_read_b128 v[202:205], v146 offset:49152
	ds_read_b128 v[206:209], v146 offset:50176
	ds_read_b128 v[222:225], v146 offset:51200
	ds_read_b128 v[226:229], v146 offset:52224
	ds_read_b128 v[230:233], v146 offset:53248
	ds_read_b128 v[234:237], v146 offset:54272
	ds_read_b128 v[238:241], v146 offset:55296
	ds_read_b128 v[242:245], v146 offset:56320
	global_load_lds_dwordx4 v[212:213], off
	s_add_i32 m0, s12, 0x2000
	s_add_u32 s86, s96, 0x80080
	v_lshl_add_u64 v[212:213], v[246:247], 0, s[6:7]
	s_addc_u32 s87, s97, 0
	s_add_i32 s12, s13, s24
	global_load_lds_dwordx4 v[212:213], off
	v_lshl_add_u64 v[212:213], s[86:87], 0, v[134:135]
	s_mov_b32 m0, s12
	s_nop 0
	global_load_lds_dwordx4 v[212:213], off
	v_lshl_add_u64 v[212:213], s[86:87], 0, v[130:131]
	s_add_i32 m0, s12, 0x2000
	s_nop 0
	global_load_lds_dwordx4 v[212:213], off
	v_lshl_add_u64 v[212:213], s[56:57], 0, v[136:137]
	s_mov_b32 m0, s29
	s_nop 0
	global_load_lds_dwordx4 v[212:213], off
	v_lshl_add_u64 v[212:213], s[56:57], 0, v[132:133]
	s_mov_b32 m0, s33
	s_nop 0
	global_load_lds_dwordx4 v[212:213], off
	s_waitcnt vmcnt(8)
	s_waitcnt lgkmcnt(0)
	s_barrier
	s_setprio 1
	s_waitcnt lgkmcnt(0)
	v_mfma_f32_16x16x32_bf16 v[62:65], v[148:151], v[202:205], v[62:65]
	v_mfma_f32_16x16x32_bf16 v[58:61], v[156:159], v[202:205], v[58:61]
	v_mfma_f32_16x16x32_bf16 v[54:57], v[148:151], v[222:225], v[54:57]
	v_mfma_f32_16x16x32_bf16 v[46:49], v[156:159], v[222:225], v[46:49]
	v_mfma_f32_16x16x32_bf16 v[38:41], v[148:151], v[230:233], v[38:41]
	v_mfma_f32_16x16x32_bf16 v[30:33], v[156:159], v[230:233], v[30:33]
	v_mfma_f32_16x16x32_bf16 v[22:25], v[148:151], v[238:241], v[22:25]
	v_mfma_f32_16x16x32_bf16 v[14:17], v[156:159], v[238:241], v[14:17]
	v_mfma_f32_16x16x32_bf16 v[62:65], v[152:155], v[206:209], v[62:65]
	v_mfma_f32_16x16x32_bf16 v[58:61], v[160:163], v[206:209], v[58:61]
	v_mfma_f32_16x16x32_bf16 v[54:57], v[152:155], v[226:229], v[54:57]
	v_mfma_f32_16x16x32_bf16 v[46:49], v[160:163], v[226:229], v[46:49]
	v_mfma_f32_16x16x32_bf16 v[38:41], v[152:155], v[234:237], v[38:41]
	v_mfma_f32_16x16x32_bf16 v[30:33], v[160:163], v[234:237], v[30:33]
	v_mfma_f32_16x16x32_bf16 v[22:25], v[152:155], v[242:245], v[22:25]
	v_mfma_f32_16x16x32_bf16 v[14:17], v[160:163], v[242:245], v[14:17]
	v_mfma_f32_16x16x32_bf16 v[50:53], v[186:189], v[202:205], v[50:53]
	v_mfma_f32_16x16x32_bf16 v[42:45], v[194:197], v[202:205], v[42:45]
	v_mfma_f32_16x16x32_bf16 v[34:37], v[186:189], v[222:225], v[34:37]
	v_mfma_f32_16x16x32_bf16 v[26:29], v[194:197], v[222:225], v[26:29]
	v_mfma_f32_16x16x32_bf16 v[18:21], v[186:189], v[230:233], v[18:21]
	v_mfma_f32_16x16x32_bf16 v[10:13], v[194:197], v[230:233], v[10:13]
	v_mfma_f32_16x16x32_bf16 v[6:9], v[186:189], v[238:241], v[6:9]
	v_mfma_f32_16x16x32_bf16 v[2:5], v[194:197], v[238:241], v[2:5]
	v_mfma_f32_16x16x32_bf16 v[50:53], v[190:193], v[206:209], v[50:53]
	v_mfma_f32_16x16x32_bf16 v[42:45], v[198:201], v[206:209], v[42:45]
	v_mfma_f32_16x16x32_bf16 v[34:37], v[190:193], v[226:229], v[34:37]
	v_mfma_f32_16x16x32_bf16 v[26:29], v[198:201], v[226:229], v[26:29]
	v_mfma_f32_16x16x32_bf16 v[18:21], v[190:193], v[234:237], v[18:21]
	v_mfma_f32_16x16x32_bf16 v[10:13], v[198:201], v[234:237], v[10:13]
	v_mfma_f32_16x16x32_bf16 v[6:9], v[190:193], v[242:245], v[6:9]
	v_mfma_f32_16x16x32_bf16 v[2:5], v[198:201], v[242:245], v[2:5]
	s_setprio 0
	s_barrier
	s_add_i32 s93, s93, 2
	s_add_u32 s54, s54, 0x100
	s_addc_u32 s55, s55, 0
	s_cmp_gt_u32 s93, 29
	s_cbranch_scc0 .LBB0_955
	s_and_b64 vcc, exec, s[36:37]
	s_cbranch_vccz .LBB0_958
	s_barrier

; #define PG8_STAGE(bufoff, gbase, voff) do { _Pragma("unroll") for (int _i = 0; _i < 2; ++_i) \
;         __builtin_amdgcn_global_load_lds((const unsigned*)((const char*)(gbase) + (voff)[_i]), (LAS unsigned*)(lds + (bufoff) + ldsw + _i * 8192), 16, 0, 0); } while (0)
; #define PG8_LDA(dst, b, h) do { _Pragma("unroll") for (int m = 0; m < 4; ++m) _Pragma("unroll") for (int k = 0; k < 2; ++k) dst[m][k] = *(const LAS bf16x8*)(lds + PG8_SA(b, h) + aoff + m * 2048 + k * 1024); } while (0)
; #define PG8_LDB(dst, b, h) do { _Pragma("unroll") for (int n = 0; n < 2; ++n) _Pragma("unroll") for (int k = 0; k < 2; ++k) dst[n][k] = *(const LAS bf16x8*)(lds + PG8_SB(b, h) + boff + n * 2048 + k * 1024); } while (0)
; #define PG8_MMA(ai, bj, At, Bt) do { __builtin_amdgcn_s_setprio(1); _Pragma("unroll") for (int m = 0; m < 4; ++m) _Pragma("unroll") for (int n = 0; n < 2; ++n) _Pragma("unroll") for (int k = 0; k < 2; ++k) \
;         acc[ai][bj][m][n] = __builtin_amdgcn_mfma_f32_16x16x32_bf16(Bt[n][k], At[m][k], acc[ai][bj][m][n], 0, 0, 0); __builtin_amdgcn_s_setprio(0); } while (0)
; #define PG8_WAIT_V(n) asm volatile("s_waitcnt vmcnt(" #n ")" ::: "memory")
; #define PG8_WAIT_L(n) asm volatile("s_waitcnt lgkmcnt(" #n ")" ::: "memory")
; #define PG8_BAR __builtin_amdgcn_s_barrier()
; #define PG8_SCHED __builtin_amdgcn_sched_barrier(0)
; template <class Epi>
; __device__ __forceinline__ void gemm_phase(LAS unsigned char* lds, const Gemm g, const StaticOrder& S, const Epi& E) {
;     ...
;             const char* a1 = PG8_AP(cA, t + 1);
;             const char* a2 = last ? nA : PG8_AP(cA, t + 2); const char* b2 = last ? nB : cB + (size_t)(t + 2) * kstep;
;             const char* a3 = last ? nA + kstep : PG8_AP(cA, t + 3); const char* b3 = b2 + kstep;
;             PG8_LDB(B0, 0, 0); PG8_LDB(B1, 0, 1); PG8_SCHED; PG8_LDA(At, 0, 0); PG8_STAGE(PG8_SA(1, 1), a1 + hstepA, voffA);
;             PG8_WAIT_V(8); PG8_WAIT_L(0); PG8_BAR; PG8_MMA(0, 0, At, B0); PG8_MMA(0, 1, At, B1); PG8_BAR; PG8_SCHED;
;             PG8_LDA(At, 0, 1); PG8_STAGE(PG8_SB(0, 0), b2, voffB); PG8_STAGE(PG8_SB(0, 1), b2 + hstep, voffB); PG8_STAGE(PG8_SA(0, 0), a2, voffA);
.LBB0_1090:
	s_add_u32 s12, s48, s50
	s_addc_u32 s13, s49, s51
	s_add_u32 s14, s12, 0x100
	s_addc_u32 s15, s13, 0
	s_add_u32 s56, s96, s50
	s_addc_u32 s57, s97, s51
	s_add_u32 s12, s12, 0x180
	s_addc_u32 s13, s13, 0
	s_add_i32 s90, 0, 0x10000
	s_add_i32 vcc_hi, 0, 0x14000
	v_add_u32_e32 v147, s90, v1
	ds_read_b128 v[148:151], v147
	ds_read_b128 v[152:155], v147 offset:1024
	ds_read_b128 v[156:159], v147 offset:2048
	ds_read_b128 v[160:163], v147 offset:3072
	v_add_u32_e32 v147, vcc_hi, v1
	ds_read_b128 v[186:189], v147
	ds_read_b128 v[190:193], v147 offset:1024
	ds_read_b128 v[194:197], v147 offset:2048
	ds_read_b128 v[198:201], v147 offset:3072
	s_cmpk_eq_i32 s50, 0xf00
	s_cselect_b32 s55, s94, s13
	s_cselect_b32 s54, s93, s12
	s_cselect_b32 s57, s37, s57
	s_cselect_b32 s56, s92, s56
	s_cselect_b32 s87, s43, s15
	s_cselect_b32 s86, s85, s14
	v_lshl_add_u64 v[212:213], v[142:143], 0, s[50:51]
	s_add_i32 m0, s25, 0xc000
	ds_read_b128 v[202:205], v146
	ds_read_b128 v[206:209], v146 offset:1024
	ds_read_b128 v[222:225], v146 offset:2048
	ds_read_b128 v[226:229], v146 offset:3072
	ds_read_b128 v[230:233], v146 offset:4096
	ds_read_b128 v[234:237], v146 offset:5120
	ds_read_b128 v[238:241], v146 offset:6144
	ds_read_b128 v[242:245], v146 offset:7168
	global_load_lds_dwordx4 v[212:213], off
	v_lshl_add_u64 v[212:213], v[144:145], 0, s[50:51]
	s_add_i32 m0, s25, 0xe000
	s_nop 0
	global_load_lds_dwordx4 v[212:213], off
	s_waitcnt vmcnt(8)
	s_waitcnt lgkmcnt(0)
	s_barrier
	s_setprio 1
	s_waitcnt lgkmcnt(0)
	v_mfma_f32_16x16x32_bf16 v[126:129], v[148:151], v[202:205], v[126:129]
	v_mfma_f32_16x16x32_bf16 v[122:125], v[156:159], v[202:205], v[122:125]
	v_mfma_f32_16x16x32_bf16 v[110:113], v[148:151], v[222:225], v[110:113]
	v_mfma_f32_16x16x32_bf16 v[106:109], v[156:159], v[222:225], v[106:109]
	v_mfma_f32_16x16x32_bf16 v[94:97], v[148:151], v[230:233], v[94:97]
	v_mfma_f32_16x16x32_bf16 v[90:93], v[156:159], v[230:233], v[90:93]
	v_mfma_f32_16x16x32_bf16 v[78:81], v[148:151], v[238:241], v[78:81]
	v_mfma_f32_16x16x32_bf16 v[74:77], v[156:159], v[238:241], v[74:77]
	v_mfma_f32_16x16x32_bf16 v[126:129], v[152:155], v[206:209], v[126:129]
	v_mfma_f32_16x16x32_bf16 v[122:125], v[160:163], v[206:209], v[122:125]
	v_mfma_f32_16x16x32_bf16 v[110:113], v[152:155], v[226:229], v[110:113]
	v_mfma_f32_16x16x32_bf16 v[106:109], v[160:163], v[226:229], v[106:109]
	v_mfma_f32_16x16x32_bf16 v[94:97], v[152:155], v[234:237], v[94:97]
	v_mfma_f32_16x16x32_bf16 v[90:93], v[160:163], v[234:237], v[90:93]
	v_mfma_f32_16x16x32_bf16 v[78:81], v[152:155], v[242:245], v[78:81]
	v_mfma_f32_16x16x32_bf16 v[74:77], v[160:163], v[242:245], v[74:77]
	v_mfma_f32_16x16x32_bf16 v[118:121], v[186:189], v[202:205], v[118:121]
	v_mfma_f32_16x16x32_bf16 v[114:117], v[194:197], v[202:205], v[114:117]
	v_mfma_f32_16x16x32_bf16 v[102:105], v[186:189], v[222:225], v[102:105]
	v_mfma_f32_16x16x32_bf16 v[98:101], v[194:197], v[222:225], v[98:101]
	v_mfma_f32_16x16x32_bf16 v[86:89], v[186:189], v[230:233], v[86:89]
	v_mfma_f32_16x16x32_bf16 v[82:85], v[194:197], v[230:233], v[82:85]
	v_mfma_f32_16x16x32_bf16 v[70:73], v[186:189], v[238:241], v[70:73]
	v_mfma_f32_16x16x32_bf16 v[66:69], v[194:197], v[238:241], v[66:69]
	v_mfma_f32_16x16x32_bf16 v[118:121], v[190:193], v[206:209], v[118:121]
	v_mfma_f32_16x16x32_bf16 v[114:117], v[198:201], v[206:209], v[114:117]
	v_mfma_f32_16x16x32_bf16 v[102:105], v[190:193], v[226:229], v[102:105]
	v_mfma_f32_16x16x32_bf16 v[98:101], v[198:201], v[226:229], v[98:101]
	v_mfma_f32_16x16x32_bf16 v[86:89], v[190:193], v[234:237], v[86:89]
	v_mfma_f32_16x16x32_bf16 v[82:85], v[198:201], v[234:237], v[82:85]
	v_mfma_f32_16x16x32_bf16 v[70:73], v[190:193], v[242:245], v[70:73]
	v_mfma_f32_16x16x32_bf16 v[66:69], v[198:201], v[242:245], v[66:69]
	s_setprio 0
	s_barrier
	s_add_i32 s12, s90, s24
	v_lshl_add_u64 v[212:213], s[56:57], 0, v[134:135]
	s_mov_b32 m0, s12
	ds_read_b128 v[202:205], v146 offset:16384
	ds_read_b128 v[206:209], v146 offset:17408
	ds_read_b128 v[222:225], v146 offset:18432
	ds_read_b128 v[226:229], v146 offset:19456
	ds_read_b128 v[230:233], v146 offset:20480
	ds_read_b128 v[234:237], v146 offset:21504
	ds_read_b128 v[238:241], v146 offset:22528
	ds_read_b128 v[242:245], v146 offset:23552
	global_load_lds_dwordx4 v[212:213], off
	s_add_i32 m0, s12, 0x2000
	s_add_u32 s90, s56, 0x80000
	v_lshl_add_u64 v[246:247], s[56:57], 0, v[130:131]
	s_addc_u32 s91, s57, 0
	s_add_i32 s12, vcc_hi, s24
	global_load_lds_dwordx4 v[246:247], off
	v_lshl_add_u64 v[248:249], s[90:91], 0, v[134:135]
	s_mov_b32 m0, s12
	s_nop 0
	global_load_lds_dwordx4 v[248:249], off
	v_lshl_add_u64 v[248:249], s[90:91], 0, v[130:131]
	s_add_i32 m0, s12, 0x2000
	s_nop 0
	global_load_lds_dwordx4 v[248:249], off
	v_lshl_add_u64 v[248:249], s[86:87], 0, v[136:137]
	s_mov_b32 m0, s25
	s_nop 0
	global_load_lds_dwordx4 v[248:249], off
	v_lshl_add_u64 v[248:249], s[86:87], 0, v[132:133]
	s_mov_b32 m0, s33
	s_nop 0
	global_load_lds_dwordx4 v[248:249], off
	s_waitcnt vmcnt(8)
	s_waitcnt lgkmcnt(0)
	s_barrier
; #define PG8_STAGE(bufoff, gbase, voff) do { _Pragma("unroll") for (int _i = 0; _i < 2; ++_i) \
;         __builtin_amdgcn_global_load_lds((const unsigned*)((const char*)(gbase) + (voff)[_i]), (LAS unsigned*)(lds + (bufoff) + ldsw + _i * 8192), 16, 0, 0); } while (0)
; #define PG8_LDA(dst, b, h) do { _Pragma("unroll") for (int m = 0; m < 4; ++m) _Pragma("unroll") for (int k = 0; k < 2; ++k) dst[m][k] = *(const LAS bf16x8*)(lds + PG8_SA(b, h) + aoff + m * 2048 + k * 1024); } while (0)
; #define PG8_LDB(dst, b, h) do { _Pragma("unroll") for (int n = 0; n < 2; ++n) _Pragma("unroll") for (int k = 0; k < 2; ++k) dst[n][k] = *(const LAS bf16x8*)(lds + PG8_SB(b, h) + boff + n * 2048 + k * 1024); } while (0)
; #define PG8_MMA(ai, bj, At, Bt) do { __builtin_amdgcn_s_setprio(1); _Pragma("unroll") for (int m = 0; m < 4; ++m) _Pragma("unroll") for (int n = 0; n < 2; ++n) _Pragma("unroll") for (int k = 0; k < 2; ++k) \
;         acc[ai][bj][m][n] = __builtin_amdgcn_mfma_f32_16x16x32_bf16(Bt[n][k], At[m][k], acc[ai][bj][m][n], 0, 0, 0); __builtin_amdgcn_s_setprio(0); } while (0)
; #define PG8_WAIT_V(n) asm volatile("s_waitcnt vmcnt(" #n ")" ::: "memory")
; #define PG8_WAIT_L(n) asm volatile("s_waitcnt lgkmcnt(" #n ")" ::: "memory")
; #define PG8_BAR __builtin_amdgcn_s_barrier()
; #define PG8_SCHED __builtin_amdgcn_sched_barrier(0)
; template <class Epi>
; __device__ __forceinline__ void gemm_phase(LAS unsigned char* lds, const Gemm g, const StaticOrder& S, const Epi& E) {
;     ...
;             PG8_WAIT_V(8); PG8_WAIT_L(0); PG8_BAR; PG8_MMA(1, 0, At, B0); PG8_MMA(1, 1, At, B1); PG8_BAR; PG8_SCHED;
;             PG8_LDB(B0, 1, 0); PG8_LDB(B1, 1, 1); PG8_SCHED; PG8_LDA(At, 1, 0); PG8_STAGE(PG8_SA(0, 1), a2 + hstepA, voffA);
;             PG8_WAIT_V(8); PG8_WAIT_L(0); PG8_BAR; PG8_MMA(0, 0, At, B0); PG8_MMA(0, 1, At, B1); PG8_BAR; PG8_SCHED;
	s_setprio 1
	s_waitcnt lgkmcnt(0)
	v_mfma_f32_16x16x32_bf16 v[62:65], v[148:151], v[202:205], v[62:65]
	v_mfma_f32_16x16x32_bf16 v[58:61], v[156:159], v[202:205], v[58:61]
	v_mfma_f32_16x16x32_bf16 v[46:49], v[148:151], v[222:225], v[46:49]
	v_mfma_f32_16x16x32_bf16 v[42:45], v[156:159], v[222:225], v[42:45]
	v_mfma_f32_16x16x32_bf16 v[30:33], v[148:151], v[230:233], v[30:33]
	v_mfma_f32_16x16x32_bf16 v[26:29], v[156:159], v[230:233], v[26:29]
	v_mfma_f32_16x16x32_bf16 v[14:17], v[148:151], v[238:241], v[14:17]
	v_mfma_f32_16x16x32_bf16 v[10:13], v[156:159], v[238:241], v[10:13]
	v_mfma_f32_16x16x32_bf16 v[62:65], v[152:155], v[206:209], v[62:65]
	v_mfma_f32_16x16x32_bf16 v[58:61], v[160:163], v[206:209], v[58:61]
	v_mfma_f32_16x16x32_bf16 v[46:49], v[152:155], v[226:229], v[46:49]
	v_mfma_f32_16x16x32_bf16 v[42:45], v[160:163], v[226:229], v[42:45]
	v_mfma_f32_16x16x32_bf16 v[30:33], v[152:155], v[234:237], v[30:33]
	v_mfma_f32_16x16x32_bf16 v[26:29], v[160:163], v[234:237], v[26:29]
	v_mfma_f32_16x16x32_bf16 v[14:17], v[152:155], v[242:245], v[14:17]
	v_mfma_f32_16x16x32_bf16 v[10:13], v[160:163], v[242:245], v[10:13]
	v_mfma_f32_16x16x32_bf16 v[54:57], v[186:189], v[202:205], v[54:57]
	v_mfma_f32_16x16x32_bf16 v[50:53], v[194:197], v[202:205], v[50:53]
	v_mfma_f32_16x16x32_bf16 v[38:41], v[186:189], v[222:225], v[38:41]
	v_mfma_f32_16x16x32_bf16 v[34:37], v[194:197], v[222:225], v[34:37]
	v_mfma_f32_16x16x32_bf16 v[22:25], v[186:189], v[230:233], v[22:25]
	v_mfma_f32_16x16x32_bf16 v[18:21], v[194:197], v[230:233], v[18:21]
	v_mfma_f32_16x16x32_bf16 v[6:9], v[186:189], v[238:241], v[6:9]
	v_mfma_f32_16x16x32_bf16 v[2:5], v[194:197], v[238:241], v[2:5]
	v_mfma_f32_16x16x32_bf16 v[54:57], v[190:193], v[206:209], v[54:57]
	v_mfma_f32_16x16x32_bf16 v[50:53], v[198:201], v[206:209], v[50:53]
	v_mfma_f32_16x16x32_bf16 v[38:41], v[190:193], v[226:229], v[38:41]
	v_mfma_f32_16x16x32_bf16 v[34:37], v[198:201], v[226:229], v[34:37]
	v_mfma_f32_16x16x32_bf16 v[22:25], v[190:193], v[234:237], v[22:25]
	v_mfma_f32_16x16x32_bf16 v[18:21], v[198:201], v[234:237], v[18:21]
	v_mfma_f32_16x16x32_bf16 v[6:9], v[190:193], v[242:245], v[6:9]
	v_mfma_f32_16x16x32_bf16 v[2:5], v[198:201], v[242:245], v[2:5]
	s_setprio 0
	s_barrier
	s_add_i32 s12, 0, 0x18000
	v_add_u32_e32 v147, s12, v1
	s_add_i32 s13, 0, 0x1c000
	ds_read_b128 v[148:151], v147
	ds_read_b128 v[152:155], v147 offset:1024
	ds_read_b128 v[156:159], v147 offset:2048
	ds_read_b128 v[160:163], v147 offset:3072
	v_add_u32_e32 v147, s13, v1
	ds_read_b128 v[186:189], v147
	ds_read_b128 v[190:193], v147 offset:1024
	ds_read_b128 v[194:197], v147 offset:2048
	ds_read_b128 v[198:201], v147 offset:3072
	s_add_u32 s86, s86, 0x80000
	s_addc_u32 s87, s87, 0
	s_mov_b32 m0, s38
	v_lshl_add_u64 v[248:249], s[86:87], 0, v[136:137]
	ds_read_b128 v[202:205], v146 offset:32768
	ds_read_b128 v[206:209], v146 offset:33792
	ds_read_b128 v[222:225], v146 offset:34816
	ds_read_b128 v[226:229], v146 offset:35840
	ds_read_b128 v[230:233], v146 offset:36864
	ds_read_b128 v[234:237], v146 offset:37888
	ds_read_b128 v[238:241], v146 offset:38912
	ds_read_b128 v[242:245], v146 offset:39936
	global_load_lds_dwordx4 v[248:249], off
	v_lshl_add_u64 v[248:249], s[86:87], 0, v[132:133]
	s_mov_b32 m0, s39
	s_nop 0
	global_load_lds_dwordx4 v[248:249], off
	s_waitcnt vmcnt(8)
	s_waitcnt lgkmcnt(0)
	s_barrier
	s_setprio 1
	s_waitcnt lgkmcnt(0)
	v_mfma_f32_16x16x32_bf16 v[126:129], v[148:151], v[202:205], v[126:129]
	v_mfma_f32_16x16x32_bf16 v[122:125], v[156:159], v[202:205], v[122:125]
	v_mfma_f32_16x16x32_bf16 v[110:113], v[148:151], v[222:225], v[110:113]
	v_mfma_f32_16x16x32_bf16 v[106:109], v[156:159], v[222:225], v[106:109]
	v_mfma_f32_16x16x32_bf16 v[94:97], v[148:151], v[230:233], v[94:97]
	v_mfma_f32_16x16x32_bf16 v[90:93], v[156:159], v[230:233], v[90:93]
	v_mfma_f32_16x16x32_bf16 v[78:81], v[148:151], v[238:241], v[78:81]
	v_mfma_f32_16x16x32_bf16 v[74:77], v[156:159], v[238:241], v[74:77]
	v_mfma_f32_16x16x32_bf16 v[126:129], v[152:155], v[206:209], v[126:129]
	v_mfma_f32_16x16x32_bf16 v[122:125], v[160:163], v[206:209], v[122:125]
	v_mfma_f32_16x16x32_bf16 v[110:113], v[152:155], v[226:229], v[110:113]
	v_mfma_f32_16x16x32_bf16 v[106:109], v[160:163], v[226:229], v[106:109]
	v_mfma_f32_16x16x32_bf16 v[94:97], v[152:155], v[234:237], v[94:97]
	v_mfma_f32_16x16x32_bf16 v[90:93], v[160:163], v[234:237], v[90:93]
	v_mfma_f32_16x16x32_bf16 v[78:81], v[152:155], v[242:245], v[78:81]
	v_mfma_f32_16x16x32_bf16 v[74:77], v[160:163], v[242:245], v[74:77]
	v_mfma_f32_16x16x32_bf16 v[118:121], v[186:189], v[202:205], v[118:121]
	v_mfma_f32_16x16x32_bf16 v[114:117], v[194:197], v[202:205], v[114:117]
	v_mfma_f32_16x16x32_bf16 v[102:105], v[186:189], v[222:225], v[102:105]
	v_mfma_f32_16x16x32_bf16 v[98:101], v[194:197], v[222:225], v[98:101]
	v_mfma_f32_16x16x32_bf16 v[86:89], v[186:189], v[230:233], v[86:89]
	v_mfma_f32_16x16x32_bf16 v[82:85], v[194:197], v[230:233], v[82:85]
	v_mfma_f32_16x16x32_bf16 v[70:73], v[186:189], v[238:241], v[70:73]
	v_mfma_f32_16x16x32_bf16 v[66:69], v[194:197], v[238:241], v[66:69]
	v_mfma_f32_16x16x32_bf16 v[118:121], v[190:193], v[206:209], v[118:121]
	v_mfma_f32_16x16x32_bf16 v[114:117], v[198:201], v[206:209], v[114:117]
	v_mfma_f32_16x16x32_bf16 v[102:105], v[190:193], v[226:229], v[102:105]
	v_mfma_f32_16x16x32_bf16 v[98:101], v[198:201], v[226:229], v[98:101]
	v_mfma_f32_16x16x32_bf16 v[86:89], v[190:193], v[234:237], v[86:89]
	v_mfma_f32_16x16x32_bf16 v[82:85], v[198:201], v[234:237], v[82:85]
	v_mfma_f32_16x16x32_bf16 v[70:73], v[190:193], v[242:245], v[70:73]
	v_mfma_f32_16x16x32_bf16 v[66:69], v[198:201], v[242:245], v[66:69]
	s_setprio 0
	s_barrier
; #define PG8_STAGE(bufoff, gbase, voff) do { _Pragma("unroll") for (int _i = 0; _i < 2; ++_i) \
;         __builtin_amdgcn_global_load_lds((const unsigned*)((const char*)(gbase) + (voff)[_i]), (LAS unsigned*)(lds + (bufoff) + ldsw + _i * 8192), 16, 0, 0); } while (0)
; #define PG8_LDA(dst, b, h) do { _Pragma("unroll") for (int m = 0; m < 4; ++m) _Pragma("unroll") for (int k = 0; k < 2; ++k) dst[m][k] = *(const LAS bf16x8*)(lds + PG8_SA(b, h) + aoff + m * 2048 + k * 1024); } while (0)
; #define PG8_MMA(ai, bj, At, Bt) do { __builtin_amdgcn_s_setprio(1); _Pragma("unroll") for (int m = 0; m < 4; ++m) _Pragma("unroll") for (int n = 0; n < 2; ++n) _Pragma("unroll") for (int k = 0; k < 2; ++k) \
;         acc[ai][bj][m][n] = __builtin_amdgcn_mfma_f32_16x16x32_bf16(Bt[n][k], At[m][k], acc[ai][bj][m][n], 0, 0, 0); __builtin_amdgcn_s_setprio(0); } while (0)
; #define PG8_WAIT_V(n) asm volatile("s_waitcnt vmcnt(" #n ")" ::: "memory")
; #define PG8_WAIT_L(n) asm volatile("s_waitcnt lgkmcnt(" #n ")" ::: "memory")
; #define PG8_BAR __builtin_amdgcn_s_barrier()
; #define PG8_SCHED __builtin_amdgcn_sched_barrier(0)
; template <class Epi>
; __device__ __forceinline__ void gemm_phase(LAS unsigned char* lds, const Gemm g, const StaticOrder& S, const Epi& E) {
;     ...
;             PG8_LDA(At, 1, 1); PG8_STAGE(PG8_SB(1, 0), b3, voffB); PG8_STAGE(PG8_SB(1, 1), b3 + hstep, voffB); PG8_STAGE(PG8_SA(1, 0), a3, voffA);
;             PG8_WAIT_V(8); PG8_WAIT_L(0); PG8_BAR; PG8_MMA(1, 0, At, B0); PG8_MMA(1, 1, At, B1); PG8_BAR; PG8_SCHED;
;         }
;         if (wr == 0) PG8_BAR;
	s_add_i32 s12, s12, s24
	v_lshl_add_u64 v[212:213], v[212:213], 0, s[6:7]
	s_mov_b32 m0, s12
	ds_read_b128 v[202:205], v146 offset:49152
	ds_read_b128 v[206:209], v146 offset:50176
	ds_read_b128 v[222:225], v146 offset:51200
	ds_read_b128 v[226:229], v146 offset:52224
	ds_read_b128 v[230:233], v146 offset:53248
	ds_read_b128 v[234:237], v146 offset:54272
	ds_read_b128 v[238:241], v146 offset:55296
	ds_read_b128 v[242:245], v146 offset:56320
	global_load_lds_dwordx4 v[212:213], off
	s_add_i32 m0, s12, 0x2000
	s_add_u32 s56, s56, 0x80080
	v_lshl_add_u64 v[212:213], v[246:247], 0, s[6:7]
	s_addc_u32 s57, s57, 0
	s_add_i32 s12, s13, s24
	global_load_lds_dwordx4 v[212:213], off
	v_lshl_add_u64 v[212:213], s[56:57], 0, v[134:135]
	s_mov_b32 m0, s12
	s_nop 0
	global_load_lds_dwordx4 v[212:213], off
	v_lshl_add_u64 v[212:213], s[56:57], 0, v[130:131]
	s_add_i32 m0, s12, 0x2000
	s_nop 0
	global_load_lds_dwordx4 v[212:213], off
	v_lshl_add_u64 v[212:213], s[54:55], 0, v[136:137]
	s_mov_b32 m0, s52
	s_nop 0
	global_load_lds_dwordx4 v[212:213], off
	v_lshl_add_u64 v[212:213], s[54:55], 0, v[132:133]
	s_mov_b32 m0, s63
	s_nop 0
	global_load_lds_dwordx4 v[212:213], off
	s_waitcnt vmcnt(8)
	s_waitcnt lgkmcnt(0)
	s_barrier
	s_setprio 1
	s_waitcnt lgkmcnt(0)
	v_mfma_f32_16x16x32_bf16 v[62:65], v[148:151], v[202:205], v[62:65]
	v_mfma_f32_16x16x32_bf16 v[58:61], v[156:159], v[202:205], v[58:61]
	v_mfma_f32_16x16x32_bf16 v[46:49], v[148:151], v[222:225], v[46:49]
	v_mfma_f32_16x16x32_bf16 v[42:45], v[156:159], v[222:225], v[42:45]
	v_mfma_f32_16x16x32_bf16 v[30:33], v[148:151], v[230:233], v[30:33]
	v_mfma_f32_16x16x32_bf16 v[26:29], v[156:159], v[230:233], v[26:29]
	v_mfma_f32_16x16x32_bf16 v[14:17], v[148:151], v[238:241], v[14:17]
	v_mfma_f32_16x16x32_bf16 v[10:13], v[156:159], v[238:241], v[10:13]
	v_mfma_f32_16x16x32_bf16 v[62:65], v[152:155], v[206:209], v[62:65]
	v_mfma_f32_16x16x32_bf16 v[58:61], v[160:163], v[206:209], v[58:61]
	v_mfma_f32_16x16x32_bf16 v[46:49], v[152:155], v[226:229], v[46:49]
	v_mfma_f32_16x16x32_bf16 v[42:45], v[160:163], v[226:229], v[42:45]
	v_mfma_f32_16x16x32_bf16 v[30:33], v[152:155], v[234:237], v[30:33]
	v_mfma_f32_16x16x32_bf16 v[26:29], v[160:163], v[234:237], v[26:29]
	v_mfma_f32_16x16x32_bf16 v[14:17], v[152:155], v[242:245], v[14:17]
	v_mfma_f32_16x16x32_bf16 v[10:13], v[160:163], v[242:245], v[10:13]
	v_mfma_f32_16x16x32_bf16 v[54:57], v[186:189], v[202:205], v[54:57]
	v_mfma_f32_16x16x32_bf16 v[50:53], v[194:197], v[202:205], v[50:53]
	v_mfma_f32_16x16x32_bf16 v[38:41], v[186:189], v[222:225], v[38:41]
	v_mfma_f32_16x16x32_bf16 v[34:37], v[194:197], v[222:225], v[34:37]
	v_mfma_f32_16x16x32_bf16 v[22:25], v[186:189], v[230:233], v[22:25]
	v_mfma_f32_16x16x32_bf16 v[18:21], v[194:197], v[230:233], v[18:21]
	v_mfma_f32_16x16x32_bf16 v[6:9], v[186:189], v[238:241], v[6:9]
	v_mfma_f32_16x16x32_bf16 v[2:5], v[194:197], v[238:241], v[2:5]
	v_mfma_f32_16x16x32_bf16 v[54:57], v[190:193], v[206:209], v[54:57]
	v_mfma_f32_16x16x32_bf16 v[50:53], v[198:201], v[206:209], v[50:53]
	v_mfma_f32_16x16x32_bf16 v[38:41], v[190:193], v[226:229], v[38:41]
	v_mfma_f32_16x16x32_bf16 v[34:37], v[198:201], v[226:229], v[34:37]
	v_mfma_f32_16x16x32_bf16 v[22:25], v[190:193], v[234:237], v[22:25]
	v_mfma_f32_16x16x32_bf16 v[18:21], v[198:201], v[234:237], v[18:21]
	v_mfma_f32_16x16x32_bf16 v[6:9], v[190:193], v[242:245], v[6:9]
	v_mfma_f32_16x16x32_bf16 v[2:5], v[198:201], v[242:245], v[2:5]
	s_setprio 0
	s_barrier
	s_add_i32 vcc_lo, vcc_lo, 2
	s_add_u32 s50, s50, 0x100
	s_addc_u32 s51, s51, 0
	s_cmp_gt_u32 vcc_lo, 29
	s_cbranch_scc0 .LBB0_1090
	s_and_b64 vcc, exec, s[34:35]
	s_cbranch_vccz .LBB0_1093
	s_barrier

; #define PG8_STAGE(bufoff, gbase, voff) do { _Pragma("unroll") for (int _i = 0; _i < 2; ++_i) \
;         __builtin_amdgcn_global_load_lds((const unsigned*)((const char*)(gbase) + (voff)[_i]), (LAS unsigned*)(lds + (bufoff) + ldsw + _i * 8192), 16, 0, 0); } while (0)
; #define PG8_LDA(dst, b, h) do { _Pragma("unroll") for (int m = 0; m < 4; ++m) _Pragma("unroll") for (int k = 0; k < 2; ++k) dst[m][k] = *(const LAS bf16x8*)(lds + PG8_SA(b, h) + aoff + m * 2048 + k * 1024); } while (0)
; #define PG8_LDB(dst, b, h) do { _Pragma("unroll") for (int n = 0; n < 2; ++n) _Pragma("unroll") for (int k = 0; k < 2; ++k) dst[n][k] = *(const LAS bf16x8*)(lds + PG8_SB(b, h) + boff + n * 2048 + k * 1024); } while (0)
; #define PG8_MMA(ai, bj, At, Bt) do { __builtin_amdgcn_s_setprio(1); _Pragma("unroll") for (int m = 0; m < 4; ++m) _Pragma("unroll") for (int n = 0; n < 2; ++n) _Pragma("unroll") for (int k = 0; k < 2; ++k) \
;         acc[ai][bj][m][n] = __builtin_amdgcn_mfma_f32_16x16x32_bf16(Bt[n][k], At[m][k], acc[ai][bj][m][n], 0, 0, 0); __builtin_amdgcn_s_setprio(0); } while (0)
; #define PG8_WAIT_V(n) asm volatile("s_waitcnt vmcnt(" #n ")" ::: "memory")
; #define PG8_WAIT_L(n) asm volatile("s_waitcnt lgkmcnt(" #n ")" ::: "memory")
; #define PG8_BAR __builtin_amdgcn_s_barrier()
; #define PG8_SCHED __builtin_amdgcn_sched_barrier(0)
; template <class Epi>
; __device__ __forceinline__ void gemm_phase(LAS unsigned char* lds, const Gemm g, const StaticOrder& S, const Epi& E) {
;     ...
;             const char* a1 = PG8_AP(cA, t + 1);
;             const char* a2 = last ? nA : PG8_AP(cA, t + 2); const char* b2 = last ? nB : cB + (size_t)(t + 2) * kstep;
;             const char* a3 = last ? nA + kstep : PG8_AP(cA, t + 3); const char* b3 = b2 + kstep;
;             PG8_LDB(B0, 0, 0); PG8_LDB(B1, 0, 1); PG8_SCHED; PG8_LDA(At, 0, 0); PG8_STAGE(PG8_SA(1, 1), a1 + hstepA, voffA);
;             PG8_WAIT_V(8); PG8_WAIT_L(0); PG8_BAR; PG8_MMA(0, 0, At, B0); PG8_MMA(0, 1, At, B1); PG8_BAR; PG8_SCHED;
;             PG8_LDA(At, 0, 1); PG8_STAGE(PG8_SB(0, 0), b2, voffB); PG8_STAGE(PG8_SB(0, 1), b2 + hstep, voffB); PG8_STAGE(PG8_SA(0, 0), a2, voffA);
.LBB0_1162:
	s_add_u32 s12, s46, s48
	s_addc_u32 s13, s47, s49
	s_add_u32 s14, s12, 0x100
	s_addc_u32 s15, s13, 0
	s_add_u32 s54, s96, s48
	s_addc_u32 s55, s97, s49
	s_add_u32 s12, s12, 0x180
	s_addc_u32 s13, s13, 0
	s_add_i32 s90, 0, 0x10000
	s_add_i32 vcc_hi, 0, 0x14000
	v_add_u32_e32 v147, s90, v1
	ds_read_b128 v[148:151], v147
	ds_read_b128 v[152:155], v147 offset:1024
	ds_read_b128 v[156:159], v147 offset:2048
	ds_read_b128 v[160:163], v147 offset:3072
	v_add_u32_e32 v147, vcc_hi, v1
	ds_read_b128 v[186:189], v147
	ds_read_b128 v[190:193], v147 offset:1024
	ds_read_b128 v[194:197], v147 offset:2048
	ds_read_b128 v[198:201], v147 offset:3072
	s_cmpk_eq_i32 s48, 0x3f00
	s_cselect_b32 s51, s94, s13
	s_cselect_b32 s50, s93, s12
	s_cselect_b32 s55, s37, s55
	s_cselect_b32 s54, s92, s54
	s_cselect_b32 s57, s41, s15
	s_cselect_b32 s56, s87, s14
	v_lshl_add_u64 v[212:213], v[142:143], 0, s[48:49]
	s_add_i32 m0, s25, 0xc000
	ds_read_b128 v[202:205], v146
	ds_read_b128 v[206:209], v146 offset:1024
	ds_read_b128 v[222:225], v146 offset:2048
	ds_read_b128 v[226:229], v146 offset:3072
	ds_read_b128 v[230:233], v146 offset:4096
	ds_read_b128 v[234:237], v146 offset:5120
	ds_read_b128 v[238:241], v146 offset:6144
	ds_read_b128 v[242:245], v146 offset:7168
	global_load_lds_dwordx4 v[212:213], off
	v_lshl_add_u64 v[212:213], v[144:145], 0, s[48:49]
	s_add_i32 m0, s25, 0xe000
	s_nop 0
	global_load_lds_dwordx4 v[212:213], off
	s_waitcnt vmcnt(8)
	s_waitcnt lgkmcnt(0)
	s_barrier
	s_setprio 1
	s_waitcnt lgkmcnt(0)
	v_mfma_f32_16x16x32_bf16 v[126:129], v[148:151], v[202:205], v[126:129]
	v_mfma_f32_16x16x32_bf16 v[122:125], v[156:159], v[202:205], v[122:125]
	v_mfma_f32_16x16x32_bf16 v[118:121], v[148:151], v[222:225], v[118:121]
	v_mfma_f32_16x16x32_bf16 v[110:113], v[156:159], v[222:225], v[110:113]
	v_mfma_f32_16x16x32_bf16 v[102:105], v[148:151], v[230:233], v[102:105]
	v_mfma_f32_16x16x32_bf16 v[94:97], v[156:159], v[230:233], v[94:97]
	v_mfma_f32_16x16x32_bf16 v[86:89], v[148:151], v[238:241], v[86:89]
	v_mfma_f32_16x16x32_bf16 v[78:81], v[156:159], v[238:241], v[78:81]
	v_mfma_f32_16x16x32_bf16 v[126:129], v[152:155], v[206:209], v[126:129]
	v_mfma_f32_16x16x32_bf16 v[122:125], v[160:163], v[206:209], v[122:125]
	v_mfma_f32_16x16x32_bf16 v[118:121], v[152:155], v[226:229], v[118:121]
	v_mfma_f32_16x16x32_bf16 v[110:113], v[160:163], v[226:229], v[110:113]
	v_mfma_f32_16x16x32_bf16 v[102:105], v[152:155], v[234:237], v[102:105]
	v_mfma_f32_16x16x32_bf16 v[94:97], v[160:163], v[234:237], v[94:97]
	v_mfma_f32_16x16x32_bf16 v[86:89], v[152:155], v[242:245], v[86:89]
	v_mfma_f32_16x16x32_bf16 v[78:81], v[160:163], v[242:245], v[78:81]
	v_mfma_f32_16x16x32_bf16 v[114:117], v[186:189], v[202:205], v[114:117]
	v_mfma_f32_16x16x32_bf16 v[106:109], v[194:197], v[202:205], v[106:109]
	v_mfma_f32_16x16x32_bf16 v[98:101], v[186:189], v[222:225], v[98:101]
	v_mfma_f32_16x16x32_bf16 v[90:93], v[194:197], v[222:225], v[90:93]
	v_mfma_f32_16x16x32_bf16 v[82:85], v[186:189], v[230:233], v[82:85]
	v_mfma_f32_16x16x32_bf16 v[74:77], v[194:197], v[230:233], v[74:77]
	v_mfma_f32_16x16x32_bf16 v[70:73], v[186:189], v[238:241], v[70:73]
	v_mfma_f32_16x16x32_bf16 v[66:69], v[194:197], v[238:241], v[66:69]
	v_mfma_f32_16x16x32_bf16 v[114:117], v[190:193], v[206:209], v[114:117]
	v_mfma_f32_16x16x32_bf16 v[106:109], v[198:201], v[206:209], v[106:109]
	v_mfma_f32_16x16x32_bf16 v[98:101], v[190:193], v[226:229], v[98:101]
	v_mfma_f32_16x16x32_bf16 v[90:93], v[198:201], v[226:229], v[90:93]
	v_mfma_f32_16x16x32_bf16 v[82:85], v[190:193], v[234:237], v[82:85]
	v_mfma_f32_16x16x32_bf16 v[74:77], v[198:201], v[234:237], v[74:77]
	v_mfma_f32_16x16x32_bf16 v[70:73], v[190:193], v[242:245], v[70:73]
	v_mfma_f32_16x16x32_bf16 v[66:69], v[198:201], v[242:245], v[66:69]
	s_setprio 0
	s_barrier
	s_add_i32 s12, s90, s24
	v_lshl_add_u64 v[212:213], s[54:55], 0, v[134:135]
	s_mov_b32 m0, s12
	ds_read_b128 v[202:205], v146 offset:16384
	ds_read_b128 v[206:209], v146 offset:17408
	ds_read_b128 v[222:225], v146 offset:18432
	ds_read_b128 v[226:229], v146 offset:19456
	ds_read_b128 v[230:233], v146 offset:20480
	ds_read_b128 v[234:237], v146 offset:21504
	ds_read_b128 v[238:241], v146 offset:22528
	ds_read_b128 v[242:245], v146 offset:23552
	global_load_lds_dwordx4 v[212:213], off
	s_add_i32 m0, s12, 0x2000
	s_add_u32 s90, s54, 0x200000
	v_lshl_add_u64 v[246:247], s[54:55], 0, v[130:131]
	s_addc_u32 s91, s55, 0
	s_add_i32 s12, vcc_hi, s24
	global_load_lds_dwordx4 v[246:247], off
	v_lshl_add_u64 v[248:249], s[90:91], 0, v[134:135]
	s_mov_b32 m0, s12
	s_nop 0
	global_load_lds_dwordx4 v[248:249], off
	v_lshl_add_u64 v[248:249], s[90:91], 0, v[130:131]
	s_add_i32 m0, s12, 0x2000
	s_nop 0
	global_load_lds_dwordx4 v[248:249], off
	v_lshl_add_u64 v[248:249], s[56:57], 0, v[136:137]
	s_mov_b32 m0, s25
	s_nop 0
	global_load_lds_dwordx4 v[248:249], off
	v_lshl_add_u64 v[248:249], s[56:57], 0, v[132:133]
	s_mov_b32 m0, s33
	s_nop 0
	global_load_lds_dwordx4 v[248:249], off
	s_waitcnt vmcnt(8)
	s_waitcnt lgkmcnt(0)
	s_barrier
; #define PG8_STAGE(bufoff, gbase, voff) do { _Pragma("unroll") for (int _i = 0; _i < 2; ++_i) \
;         __builtin_amdgcn_global_load_lds((const unsigned*)((const char*)(gbase) + (voff)[_i]), (LAS unsigned*)(lds + (bufoff) + ldsw + _i * 8192), 16, 0, 0); } while (0)
; #define PG8_LDA(dst, b, h) do { _Pragma("unroll") for (int m = 0; m < 4; ++m) _Pragma("unroll") for (int k = 0; k < 2; ++k) dst[m][k] = *(const LAS bf16x8*)(lds + PG8_SA(b, h) + aoff + m * 2048 + k * 1024); } while (0)
; #define PG8_LDB(dst, b, h) do { _Pragma("unroll") for (int n = 0; n < 2; ++n) _Pragma("unroll") for (int k = 0; k < 2; ++k) dst[n][k] = *(const LAS bf16x8*)(lds + PG8_SB(b, h) + boff + n * 2048 + k * 1024); } while (0)
; #define PG8_MMA(ai, bj, At, Bt) do { __builtin_amdgcn_s_setprio(1); _Pragma("unroll") for (int m = 0; m < 4; ++m) _Pragma("unroll") for (int n = 0; n < 2; ++n) _Pragma("unroll") for (int k = 0; k < 2; ++k) \
;         acc[ai][bj][m][n] = __builtin_amdgcn_mfma_f32_16x16x32_bf16(Bt[n][k], At[m][k], acc[ai][bj][m][n], 0, 0, 0); __builtin_amdgcn_s_setprio(0); } while (0)
; #define PG8_WAIT_V(n) asm volatile("s_waitcnt vmcnt(" #n ")" ::: "memory")
; #define PG8_WAIT_L(n) asm volatile("s_waitcnt lgkmcnt(" #n ")" ::: "memory")
; #define PG8_BAR __builtin_amdgcn_s_barrier()
; #define PG8_SCHED __builtin_amdgcn_sched_barrier(0)
; template <class Epi>
; __device__ __forceinline__ void gemm_phase(LAS unsigned char* lds, const Gemm g, const StaticOrder& S, const Epi& E) {
;     ...
;             PG8_WAIT_V(8); PG8_WAIT_L(0); PG8_BAR; PG8_MMA(1, 0, At, B0); PG8_MMA(1, 1, At, B1); PG8_BAR; PG8_SCHED;
;             PG8_LDB(B0, 1, 0); PG8_LDB(B1, 1, 1); PG8_SCHED; PG8_LDA(At, 1, 0); PG8_STAGE(PG8_SA(0, 1), a2 + hstepA, voffA);
;             PG8_WAIT_V(8); PG8_WAIT_L(0); PG8_BAR; PG8_MMA(0, 0, At, B0); PG8_MMA(0, 1, At, B1); PG8_BAR; PG8_SCHED;
	s_setprio 1
	s_waitcnt lgkmcnt(0)
	v_mfma_f32_16x16x32_bf16 v[62:65], v[148:151], v[202:205], v[62:65]
	v_mfma_f32_16x16x32_bf16 v[58:61], v[156:159], v[202:205], v[58:61]
	v_mfma_f32_16x16x32_bf16 v[54:57], v[148:151], v[222:225], v[54:57]
	v_mfma_f32_16x16x32_bf16 v[46:49], v[156:159], v[222:225], v[46:49]
	v_mfma_f32_16x16x32_bf16 v[38:41], v[148:151], v[230:233], v[38:41]
	v_mfma_f32_16x16x32_bf16 v[30:33], v[156:159], v[230:233], v[30:33]
	v_mfma_f32_16x16x32_bf16 v[22:25], v[148:151], v[238:241], v[22:25]
	v_mfma_f32_16x16x32_bf16 v[14:17], v[156:159], v[238:241], v[14:17]
	v_mfma_f32_16x16x32_bf16 v[62:65], v[152:155], v[206:209], v[62:65]
	v_mfma_f32_16x16x32_bf16 v[58:61], v[160:163], v[206:209], v[58:61]
	v_mfma_f32_16x16x32_bf16 v[54:57], v[152:155], v[226:229], v[54:57]
	v_mfma_f32_16x16x32_bf16 v[46:49], v[160:163], v[226:229], v[46:49]
	v_mfma_f32_16x16x32_bf16 v[38:41], v[152:155], v[234:237], v[38:41]
	v_mfma_f32_16x16x32_bf16 v[30:33], v[160:163], v[234:237], v[30:33]
	v_mfma_f32_16x16x32_bf16 v[22:25], v[152:155], v[242:245], v[22:25]
	v_mfma_f32_16x16x32_bf16 v[14:17], v[160:163], v[242:245], v[14:17]
	v_mfma_f32_16x16x32_bf16 v[50:53], v[186:189], v[202:205], v[50:53]
	v_mfma_f32_16x16x32_bf16 v[42:45], v[194:197], v[202:205], v[42:45]
	v_mfma_f32_16x16x32_bf16 v[34:37], v[186:189], v[222:225], v[34:37]
	v_mfma_f32_16x16x32_bf16 v[26:29], v[194:197], v[222:225], v[26:29]
	v_mfma_f32_16x16x32_bf16 v[18:21], v[186:189], v[230:233], v[18:21]
	v_mfma_f32_16x16x32_bf16 v[10:13], v[194:197], v[230:233], v[10:13]
	v_mfma_f32_16x16x32_bf16 v[6:9], v[186:189], v[238:241], v[6:9]
	v_mfma_f32_16x16x32_bf16 v[2:5], v[194:197], v[238:241], v[2:5]
	v_mfma_f32_16x16x32_bf16 v[50:53], v[190:193], v[206:209], v[50:53]
	v_mfma_f32_16x16x32_bf16 v[42:45], v[198:201], v[206:209], v[42:45]
	v_mfma_f32_16x16x32_bf16 v[34:37], v[190:193], v[226:229], v[34:37]
	v_mfma_f32_16x16x32_bf16 v[26:29], v[198:201], v[226:229], v[26:29]
	v_mfma_f32_16x16x32_bf16 v[18:21], v[190:193], v[234:237], v[18:21]
	v_mfma_f32_16x16x32_bf16 v[10:13], v[198:201], v[234:237], v[10:13]
	v_mfma_f32_16x16x32_bf16 v[6:9], v[190:193], v[242:245], v[6:9]
	v_mfma_f32_16x16x32_bf16 v[2:5], v[198:201], v[242:245], v[2:5]
	s_setprio 0
	s_barrier
	s_add_i32 s12, 0, 0x18000
	v_add_u32_e32 v147, s12, v1
	s_add_i32 s13, 0, 0x1c000
	ds_read_b128 v[148:151], v147
	ds_read_b128 v[152:155], v147 offset:1024
	ds_read_b128 v[156:159], v147 offset:2048
	ds_read_b128 v[160:163], v147 offset:3072
	v_add_u32_e32 v147, s13, v1
	ds_read_b128 v[186:189], v147
	ds_read_b128 v[190:193], v147 offset:1024
	ds_read_b128 v[194:197], v147 offset:2048
	ds_read_b128 v[198:201], v147 offset:3072
	s_add_u32 s56, s56, 0x200000
	s_addc_u32 s57, s57, 0
	s_mov_b32 m0, s52
	v_lshl_add_u64 v[248:249], s[56:57], 0, v[136:137]
	ds_read_b128 v[202:205], v146 offset:32768
	ds_read_b128 v[206:209], v146 offset:33792
	ds_read_b128 v[222:225], v146 offset:34816
	ds_read_b128 v[226:229], v146 offset:35840
	ds_read_b128 v[230:233], v146 offset:36864
	ds_read_b128 v[234:237], v146 offset:37888
	ds_read_b128 v[238:241], v146 offset:38912
	ds_read_b128 v[242:245], v146 offset:39936
	global_load_lds_dwordx4 v[248:249], off
	v_lshl_add_u64 v[248:249], s[56:57], 0, v[132:133]
	s_mov_b32 m0, s63
	s_nop 0
	global_load_lds_dwordx4 v[248:249], off
	s_waitcnt vmcnt(8)
	s_waitcnt lgkmcnt(0)
	s_barrier
	s_setprio 1
	s_waitcnt lgkmcnt(0)
	v_mfma_f32_16x16x32_bf16 v[126:129], v[148:151], v[202:205], v[126:129]
	v_mfma_f32_16x16x32_bf16 v[122:125], v[156:159], v[202:205], v[122:125]
	v_mfma_f32_16x16x32_bf16 v[118:121], v[148:151], v[222:225], v[118:121]
	v_mfma_f32_16x16x32_bf16 v[110:113], v[156:159], v[222:225], v[110:113]
	v_mfma_f32_16x16x32_bf16 v[102:105], v[148:151], v[230:233], v[102:105]
	v_mfma_f32_16x16x32_bf16 v[94:97], v[156:159], v[230:233], v[94:97]
	v_mfma_f32_16x16x32_bf16 v[86:89], v[148:151], v[238:241], v[86:89]
	v_mfma_f32_16x16x32_bf16 v[78:81], v[156:159], v[238:241], v[78:81]
	v_mfma_f32_16x16x32_bf16 v[126:129], v[152:155], v[206:209], v[126:129]
	v_mfma_f32_16x16x32_bf16 v[122:125], v[160:163], v[206:209], v[122:125]
	v_mfma_f32_16x16x32_bf16 v[118:121], v[152:155], v[226:229], v[118:121]
	v_mfma_f32_16x16x32_bf16 v[110:113], v[160:163], v[226:229], v[110:113]
	v_mfma_f32_16x16x32_bf16 v[102:105], v[152:155], v[234:237], v[102:105]
	v_mfma_f32_16x16x32_bf16 v[94:97], v[160:163], v[234:237], v[94:97]
	v_mfma_f32_16x16x32_bf16 v[86:89], v[152:155], v[242:245], v[86:89]
	v_mfma_f32_16x16x32_bf16 v[78:81], v[160:163], v[242:245], v[78:81]
	v_mfma_f32_16x16x32_bf16 v[114:117], v[186:189], v[202:205], v[114:117]
	v_mfma_f32_16x16x32_bf16 v[106:109], v[194:197], v[202:205], v[106:109]
	v_mfma_f32_16x16x32_bf16 v[98:101], v[186:189], v[222:225], v[98:101]
	v_mfma_f32_16x16x32_bf16 v[90:93], v[194:197], v[222:225], v[90:93]
	v_mfma_f32_16x16x32_bf16 v[82:85], v[186:189], v[230:233], v[82:85]
	v_mfma_f32_16x16x32_bf16 v[74:77], v[194:197], v[230:233], v[74:77]
	v_mfma_f32_16x16x32_bf16 v[70:73], v[186:189], v[238:241], v[70:73]
	v_mfma_f32_16x16x32_bf16 v[66:69], v[194:197], v[238:241], v[66:69]
	v_mfma_f32_16x16x32_bf16 v[114:117], v[190:193], v[206:209], v[114:117]
	v_mfma_f32_16x16x32_bf16 v[106:109], v[198:201], v[206:209], v[106:109]
	v_mfma_f32_16x16x32_bf16 v[98:101], v[190:193], v[226:229], v[98:101]
	v_mfma_f32_16x16x32_bf16 v[90:93], v[198:201], v[226:229], v[90:93]
	v_mfma_f32_16x16x32_bf16 v[82:85], v[190:193], v[234:237], v[82:85]
	v_mfma_f32_16x16x32_bf16 v[74:77], v[198:201], v[234:237], v[74:77]
	v_mfma_f32_16x16x32_bf16 v[70:73], v[190:193], v[242:245], v[70:73]
	v_mfma_f32_16x16x32_bf16 v[66:69], v[198:201], v[242:245], v[66:69]
	s_setprio 0
	s_barrier
; #define PG8_STAGE(bufoff, gbase, voff) do { _Pragma("unroll") for (int _i = 0; _i < 2; ++_i) \
;         __builtin_amdgcn_global_load_lds((const unsigned*)((const char*)(gbase) + (voff)[_i]), (LAS unsigned*)(lds + (bufoff) + ldsw + _i * 8192), 16, 0, 0); } while (0)
; #define PG8_LDA(dst, b, h) do { _Pragma("unroll") for (int m = 0; m < 4; ++m) _Pragma("unroll") for (int k = 0; k < 2; ++k) dst[m][k] = *(const LAS bf16x8*)(lds + PG8_SA(b, h) + aoff + m * 2048 + k * 1024); } while (0)
; #define PG8_MMA(ai, bj, At, Bt) do { __builtin_amdgcn_s_setprio(1); _Pragma("unroll") for (int m = 0; m < 4; ++m) _Pragma("unroll") for (int n = 0; n < 2; ++n) _Pragma("unroll") for (int k = 0; k < 2; ++k) \
;         acc[ai][bj][m][n] = __builtin_amdgcn_mfma_f32_16x16x32_bf16(Bt[n][k], At[m][k], acc[ai][bj][m][n], 0, 0, 0); __builtin_amdgcn_s_setprio(0); } while (0)
; #define PG8_WAIT_V(n) asm volatile("s_waitcnt vmcnt(" #n ")" ::: "memory")
; #define PG8_WAIT_L(n) asm volatile("s_waitcnt lgkmcnt(" #n ")" ::: "memory")
; #define PG8_BAR __builtin_amdgcn_s_barrier()
; #define PG8_SCHED __builtin_amdgcn_sched_barrier(0)
; template <class Epi>
; __device__ __forceinline__ void gemm_phase(LAS unsigned char* lds, const Gemm g, const StaticOrder& S, const Epi& E) {
;     ...
;             PG8_LDA(At, 1, 1); PG8_STAGE(PG8_SB(1, 0), b3, voffB); PG8_STAGE(PG8_SB(1, 1), b3 + hstep, voffB); PG8_STAGE(PG8_SA(1, 0), a3, voffA);
;             PG8_WAIT_V(8); PG8_WAIT_L(0); PG8_BAR; PG8_MMA(1, 0, At, B0); PG8_MMA(1, 1, At, B1); PG8_BAR; PG8_SCHED;
;         }
;         if (wr == 0) PG8_BAR;
	s_add_i32 s12, s12, s24
	v_lshl_add_u64 v[212:213], v[212:213], 0, s[6:7]
	s_mov_b32 m0, s12
	ds_read_b128 v[202:205], v146 offset:49152
	ds_read_b128 v[206:209], v146 offset:50176
	ds_read_b128 v[222:225], v146 offset:51200
	ds_read_b128 v[226:229], v146 offset:52224
	ds_read_b128 v[230:233], v146 offset:53248
	ds_read_b128 v[234:237], v146 offset:54272
	ds_read_b128 v[238:241], v146 offset:55296
	ds_read_b128 v[242:245], v146 offset:56320
	global_load_lds_dwordx4 v[212:213], off
	s_add_i32 m0, s12, 0x2000
	s_add_u32 s54, s54, 0x200080
	v_lshl_add_u64 v[212:213], v[246:247], 0, s[6:7]
	s_addc_u32 s55, s55, 0
	s_add_i32 s12, s13, s24
	global_load_lds_dwordx4 v[212:213], off
	v_lshl_add_u64 v[212:213], s[54:55], 0, v[134:135]
	s_mov_b32 m0, s12
	s_nop 0
	global_load_lds_dwordx4 v[212:213], off
	v_lshl_add_u64 v[212:213], s[54:55], 0, v[130:131]
	s_add_i32 m0, s12, 0x2000
	s_nop 0
	global_load_lds_dwordx4 v[212:213], off
	v_lshl_add_u64 v[212:213], s[50:51], 0, v[136:137]
	s_mov_b32 m0, s67
	s_nop 0
	global_load_lds_dwordx4 v[212:213], off
	v_lshl_add_u64 v[212:213], s[50:51], 0, v[132:133]
	s_mov_b32 m0, s80
	s_nop 0
	global_load_lds_dwordx4 v[212:213], off
	s_waitcnt vmcnt(8)
	s_waitcnt lgkmcnt(0)
	s_barrier
	s_setprio 1
	s_waitcnt lgkmcnt(0)
	v_mfma_f32_16x16x32_bf16 v[62:65], v[148:151], v[202:205], v[62:65]
	v_mfma_f32_16x16x32_bf16 v[58:61], v[156:159], v[202:205], v[58:61]
	v_mfma_f32_16x16x32_bf16 v[54:57], v[148:151], v[222:225], v[54:57]
	v_mfma_f32_16x16x32_bf16 v[46:49], v[156:159], v[222:225], v[46:49]
	v_mfma_f32_16x16x32_bf16 v[38:41], v[148:151], v[230:233], v[38:41]
	v_mfma_f32_16x16x32_bf16 v[30:33], v[156:159], v[230:233], v[30:33]
	v_mfma_f32_16x16x32_bf16 v[22:25], v[148:151], v[238:241], v[22:25]
	v_mfma_f32_16x16x32_bf16 v[14:17], v[156:159], v[238:241], v[14:17]
	v_mfma_f32_16x16x32_bf16 v[62:65], v[152:155], v[206:209], v[62:65]
	v_mfma_f32_16x16x32_bf16 v[58:61], v[160:163], v[206:209], v[58:61]
	v_mfma_f32_16x16x32_bf16 v[54:57], v[152:155], v[226:229], v[54:57]
	v_mfma_f32_16x16x32_bf16 v[46:49], v[160:163], v[226:229], v[46:49]
	v_mfma_f32_16x16x32_bf16 v[38:41], v[152:155], v[234:237], v[38:41]
	v_mfma_f32_16x16x32_bf16 v[30:33], v[160:163], v[234:237], v[30:33]
	v_mfma_f32_16x16x32_bf16 v[22:25], v[152:155], v[242:245], v[22:25]
	v_mfma_f32_16x16x32_bf16 v[14:17], v[160:163], v[242:245], v[14:17]
	v_mfma_f32_16x16x32_bf16 v[50:53], v[186:189], v[202:205], v[50:53]
	v_mfma_f32_16x16x32_bf16 v[42:45], v[194:197], v[202:205], v[42:45]
	v_mfma_f32_16x16x32_bf16 v[34:37], v[186:189], v[222:225], v[34:37]
	v_mfma_f32_16x16x32_bf16 v[26:29], v[194:197], v[222:225], v[26:29]
	v_mfma_f32_16x16x32_bf16 v[18:21], v[186:189], v[230:233], v[18:21]
	v_mfma_f32_16x16x32_bf16 v[10:13], v[194:197], v[230:233], v[10:13]
	v_mfma_f32_16x16x32_bf16 v[6:9], v[186:189], v[238:241], v[6:9]
	v_mfma_f32_16x16x32_bf16 v[2:5], v[194:197], v[238:241], v[2:5]
	v_mfma_f32_16x16x32_bf16 v[50:53], v[190:193], v[206:209], v[50:53]
	v_mfma_f32_16x16x32_bf16 v[42:45], v[198:201], v[206:209], v[42:45]
	v_mfma_f32_16x16x32_bf16 v[34:37], v[190:193], v[226:229], v[34:37]
	v_mfma_f32_16x16x32_bf16 v[26:29], v[198:201], v[226:229], v[26:29]
	v_mfma_f32_16x16x32_bf16 v[18:21], v[190:193], v[234:237], v[18:21]
	v_mfma_f32_16x16x32_bf16 v[10:13], v[198:201], v[234:237], v[10:13]
	v_mfma_f32_16x16x32_bf16 v[6:9], v[190:193], v[242:245], v[6:9]
	v_mfma_f32_16x16x32_bf16 v[2:5], v[198:201], v[242:245], v[2:5]
	s_setprio 0
	s_barrier
	s_add_i32 vcc_lo, vcc_lo, 2
	s_add_u32 s48, s48, 0x100
	s_addc_u32 s49, s49, 0
	s_cmpk_gt_u32 vcc_lo, 0x7d
	s_cbranch_scc0 .LBB0_1162
	s_and_b64 vcc, exec, s[34:35]
	s_cbranch_vccz .LBB0_1165
	s_barrier
